# v33 + residual epilogue: x loads for row groups 5,6,7 issued two groups ahead into idle registers (copied into place at use), waits recounted
# speedup vs baseline: 1.0019x; 1.0019x over previous
; #define LAS __attribute__((address_space(3)))
; #define ERN_EOFF(q, m) (eb + (unsigned)((((q) & 1) * HALF + (m) * 16) * DM + ERN_COL((q) >> 1)))
;     __device__ __forceinline__ void operator()(const f32x4 (&acc)[2][2][4][2], const Unit& u, int wr, int wc, int fr, int fq) const {
;     ...
;         ERN_LOADX(0);
; #pragma unroll
;         for (int g = 0; g < 8; ++g) { const int ai = g >> 2, m = g & 3;
;             if (g + 1 < 8) ERN_LOADX(g + 1);
;             float sq0 = 0.f, sq1 = 0.f; u32x2 hw[2][2];
; #pragma unroll
;             for (int bj = 0; bj < 2; ++bj) {
;                 *(LAS f32x4*)(st + wr_off) = acc[ai][bj][m][0]; *(LAS f32x4*)(st + wr_off + 64) = acc[ai][bj][m][1];
;                 const f32x4 a0 = *(const LAS f32x4*)(st + rd_off), a1 = *(const LAS f32x4*)(st + rd_off + 8 * 144);
;                 { const f32x4 xv = xb[g & 1][bj][0] + gv[bj] * a0; __builtin_nontemporal_store(xv, (f32x4*)((char*)xo + 4u * ERN_EOFF(g, bj, 0)));
;                   sq0 += (xv.x * xv.x + xv.y * xv.y) + (xv.z * xv.z + xv.w * xv.w);
;                   const f32x4 hv = xv * gsn[bj]; hw[bj][0].x = cvt_pk_bf16(hv.x, hv.y); hw[bj][0].y = cvt_pk_bf16(hv.z, hv.w); }
;                 { const f32x4 xv = xb[g & 1][bj][1] + gv[bj] * a1; __builtin_nontemporal_store(xv, (f32x4*)((char*)xo + 4u * ERN_EOFF(g, bj, 1)));
;                   sq1 += (xv.x * xv.x + xv.y * xv.y) + (xv.z * xv.z + xv.w * xv.w);
;                   const f32x4 hv = xv * gsn[bj]; hw[bj][1].x = cvt_pk_bf16(hv.x, hv.y); hw[bj][1].y = cvt_pk_bf16(hv.z, hv.w); }
;             }
;             if (!NOH && !PLAIN) {
; #pragma unroll
;                 for (int rh = 0; rh < 2; ++rh) { u32x2 rv; rv.x = __shfl_xor(hw[1][rh].x, 8); rv.y = __shfl_xor(hw[1][rh].y, 8);
;                     const unsigned e0 = ERN_EOFF(g, 0, rh);
;                     const unsigned ee = odd ? (e0 - DM + 32) : e0, eo2 = odd ? e0 : (e0 + DM + 32);
;                     *(u32x2*)((char*)ho + 2u * ee) = odd ? rv : hw[0][rh];
;                     *(u32x2*)((char*)ho + 2u * eo2) = odd ? hw[0][rh] : rv; }
;             }
;             if (!PLAIN) { sq0 += __shfl_xor(sq0, 1); sq0 += __shfl_xor(sq0, 2); sq0 += __shfl_xor(sq0, 4);
;             sq1 += __shfl_xor(sq1, 1); sq1 += __shfl_xor(sq1, 2); sq1 += __shfl_xor(sq1, 4); }
;             if (!PLAIN && pc == 0) { sst[g * 16 + rr] = sq0; sst[g * 16 + 8 + rr] = sq1; }
.LBB0_350:
	s_or_b64 exec, exec, s[16:17]
	v_add_u32_e32 v82, 0x100000, v207
	s_waitcnt lgkmcnt(1)
	v_add_u32_e32 v83, 0x110000, v207
	v_add_u32_e32 v116, 0x100080, v207
	global_load_dwordx4 v[94:97], v82, s[58:59]
	global_load_dwordx4 v[90:93], v83, s[58:59]
	v_add_u32_e32 v114, 0x110080, v207
	global_load_dwordx4 v[86:89], v116, s[58:59]
	s_waitcnt lgkmcnt(0)
	global_load_dwordx4 v[82:85], v114, s[58:59]
	v_add_u32_e32 v128, 0x120000, v207
	global_load_dwordx4 v[120:123], v128, s[58:59]
	v_add_u32_e32 v129, 0x130000, v207
	global_load_dwordx4 v[124:127], v129, s[58:59]
	v_add_u32_e32 v134, 0x120080, v207
	global_load_dwordx4 v[136:139], v134, s[58:59]
	v_add_u32_e32 v135, 0x130080, v207
	global_load_dwordx4 v[140:143], v135, s[58:59]
	ds_write_b128 v200, v[78:81]
	ds_write_b128 v200, v[74:77] offset:64
	ds_read_b128 v[74:77], v201
	ds_read_b128 v[78:81], v201 offset:1152
	v_mov_b32_e32 v133, v155
	v_mov_b32_e32 v131, v155
	s_waitcnt vmcnt(15) lgkmcnt(1)
	v_pk_fma_f32 v[76:77], v[178:179], v[76:77], v[112:113]
	v_add_u32_e32 v112, 0x18000, v202
	v_pk_fma_f32 v[74:75], v[180:181], v[74:75], v[110:111]
	v_lshlrev_b32_e32 v110, 2, v112
	global_store_dwordx4 v110, v[74:77], s[56:57] nt
	v_pk_mul_f32 v[110:111], v[176:177], v[74:75]
	s_waitcnt lgkmcnt(0)
	v_pk_fma_f32 v[80:81], v[178:179], v[80:81], v[108:109]
	v_pk_fma_f32 v[78:79], v[180:181], v[78:79], v[106:107]
	v_lshl_add_u64 v[106:107], s[56:57], 0, v[154:155]
	v_pk_mul_f32 v[118:119], v[174:175], v[76:77]
	v_cvt_pk_bf16_f32 v110, v110, v111
	v_pk_mul_f32 v[108:109], v[174:175], v[80:81]
	v_cvt_pk_bf16_f32 v111, v118, v119
	global_store_dwordx4 v[106:107], v[78:81], off nt
	v_pk_mul_f32 v[106:107], v[176:177], v[78:79]
	s_nop 0
	v_cvt_pk_bf16_f32 v106, v106, v107
	v_cvt_pk_bf16_f32 v107, v108, v109
	ds_write_b128 v200, v[70:73]
	ds_write_b128 v200, v[66:69] offset:64
	ds_read_b128 v[66:69], v201
	ds_read_b128 v[70:73], v201 offset:1152
	s_waitcnt lgkmcnt(1)
	v_pk_fma_f32 v[66:67], v[168:169], v[66:67], v[102:103]
	v_pk_fma_f32 v[68:69], v[166:167], v[68:69], v[104:105]
	v_lshl_add_u64 v[102:103], s[56:57], 0, v[132:133]
	v_pk_mul_f32 v[104:105], v[172:173], v[66:67]
	s_waitcnt vmcnt(16) lgkmcnt(0)
	v_pk_fma_f32 v[72:73], v[166:167], v[72:73], v[100:101]
	v_pk_fma_f32 v[70:71], v[168:169], v[70:71], v[98:99]
	v_lshl_add_u64 v[98:99], s[56:57], 0, v[130:131]
	global_store_dwordx4 v[102:103], v[66:69], off nt
	v_pk_mul_f32 v[102:103], v[170:171], v[68:69]
	v_cvt_pk_bf16_f32 v104, v104, v105
	v_pk_mul_f32 v[100:101], v[172:173], v[70:71]
	v_cvt_pk_bf16_f32 v105, v102, v103
	global_store_dwordx4 v[98:99], v[70:73], off nt
	ds_bpermute_b32 v98, v203, v104
	ds_bpermute_b32 v99, v203, v105
	v_pk_mul_f32 v[102:103], v[170:171], v[72:73]
	v_cvt_pk_bf16_f32 v100, v100, v101
	s_nop 0
	v_cvt_pk_bf16_f32 v101, v102, v103
	v_lshlrev_b32_e32 v102, 1, v112
	s_waitcnt lgkmcnt(0)
	v_add_u32_e32 v250, 0xfffff040, v102
	v_cndmask_b32_e64 v250, v102, v250, s[40:41]
	v_cndmask_b32_e64 v248, v110, v98, s[40:41]
	v_cndmask_b32_e64 v249, v111, v99, s[40:41]
	global_store_dwordx2 v250, v[248:249], s[54:55]
	v_cndmask_b32_e64 v246, v98, v110, s[40:41]
	v_cndmask_b32_e64 v247, v99, v111, s[40:41]
	s_waitcnt lgkmcnt(1)
	v_add_u32_e32 v98, 0x1040, v102
	v_cndmask_b32_e64 v98, v102, v98, s[38:39]
	global_store_dwordx2 v98, v[246:247], s[54:55]
	ds_bpermute_b32 v98, v203, v100
	s_waitcnt lgkmcnt(1)
	ds_bpermute_b32 v99, v203, v101
	v_add_u32_e32 v101, 0x1c000, v202
	v_lshlrev_b32_e32 v100, 1, v101
	s_waitcnt lgkmcnt(0)
	v_add_u32_e32 v250, 0xfffff040, v100
	v_cndmask_b32_e64 v250, v100, v250, s[40:41]
	v_cndmask_b32_e64 v248, v106, v98, s[40:41]
	v_cndmask_b32_e64 v249, v107, v99, s[40:41]
	global_store_dwordx2 v250, v[248:249], s[54:55]
	v_cndmask_b32_e64 v246, v98, v106, s[40:41]
	v_cndmask_b32_e64 v247, v99, v107, s[40:41]
	v_mul_f32_e32 v67, v67, v67
	v_fmac_f32_e32 v67, v66, v66
	v_mul_f32_e32 v66, v69, v69
	v_mul_f32_e32 v77, v77, v77
	v_fmac_f32_e32 v66, v68, v68
	v_mul_f32_e32 v75, v75, v75
	v_fmac_f32_e32 v77, v76, v76
	v_mul_f32_e32 v76, v79, v79
	v_mul_f32_e32 v79, v81, v81
	v_add_f32_e32 v66, v67, v66
	v_mul_f32_e32 v67, v71, v71
	v_mul_f32_e32 v68, v73, v73
	v_fmac_f32_e32 v79, v80, v80
	v_fmac_f32_e32 v67, v70, v70
	v_fmac_f32_e32 v68, v72, v72
	v_fmac_f32_e32 v75, v74, v74
	v_fmac_f32_e32 v76, v78, v78
	v_add_f32_e32 v67, v67, v68
	v_add_f32_e32 v68, v75, v77
	v_add_f32_e32 v69, v76, v79
	v_add_f32_e32 v66, v68, v66
	v_add_f32_e32 v67, v69, v67
	ds_bpermute_b32 v68, v204, v66
	ds_bpermute_b32 v69, v204, v67
	s_waitcnt lgkmcnt(1)
	v_add_f32_e32 v66, v66, v68
	s_waitcnt lgkmcnt(0)
	v_add_f32_e32 v69, v67, v69
	ds_bpermute_b32 v68, v205, v66
	ds_bpermute_b32 v70, v205, v69
	s_waitcnt lgkmcnt(1)
	v_add_f32_e32 v66, v66, v68
	s_waitcnt lgkmcnt(0)
	v_add_f32_e32 v68, v69, v70
	ds_bpermute_b32 v67, v206, v66
	ds_bpermute_b32 v69, v206, v68
	v_add_u32_e32 v70, 0x1040, v100
	v_cndmask_b32_e64 v70, v100, v70, s[38:39]
	global_store_dwordx2 v70, v[246:247], s[54:55]
	s_and_saveexec_b64 s[16:17], s[42:43]
	s_cbranch_execz .LBB0_360
	s_waitcnt lgkmcnt(1)
	v_add_f32_e32 v66, v66, v67
	s_waitcnt lgkmcnt(0)
	v_add_f32_e32 v67, v68, v69
	ds_write2_b32 v194, v66, v67 offset0:48 offset1:56
; #define LAS __attribute__((address_space(3)))
; #define ERN_EOFF(q, m) (eb + (unsigned)((((q) & 1) * HALF + (m) * 16) * DM + ERN_COL((q) >> 1)))
;     __device__ __forceinline__ void operator()(const f32x4 (&acc)[2][2][4][2], const Unit& u, int wr, int wc, int fr, int fq) const {
;     ...
;         ERN_LOADX(0);
; #pragma unroll
;         for (int g = 0; g < 8; ++g) { const int ai = g >> 2, m = g & 3;
;             if (g + 1 < 8) ERN_LOADX(g + 1);
;             float sq0 = 0.f, sq1 = 0.f; u32x2 hw[2][2];
; #pragma unroll
;             for (int bj = 0; bj < 2; ++bj) {
;                 *(LAS f32x4*)(st + wr_off) = acc[ai][bj][m][0]; *(LAS f32x4*)(st + wr_off + 64) = acc[ai][bj][m][1];
;                 const f32x4 a0 = *(const LAS f32x4*)(st + rd_off), a1 = *(const LAS f32x4*)(st + rd_off + 8 * 144);
;                 { const f32x4 xv = xb[g & 1][bj][0] + gv[bj] * a0; __builtin_nontemporal_store(xv, (f32x4*)((char*)xo + 4u * ERN_EOFF(g, bj, 0)));
;                   sq0 += (xv.x * xv.x + xv.y * xv.y) + (xv.z * xv.z + xv.w * xv.w);
;                   const f32x4 hv = xv * gsn[bj]; hw[bj][0].x = cvt_pk_bf16(hv.x, hv.y); hw[bj][0].y = cvt_pk_bf16(hv.z, hv.w); }
;                 { const f32x4 xv = xb[g & 1][bj][1] + gv[bj] * a1; __builtin_nontemporal_store(xv, (f32x4*)((char*)xo + 4u * ERN_EOFF(g, bj, 1)));
;                   sq1 += (xv.x * xv.x + xv.y * xv.y) + (xv.z * xv.z + xv.w * xv.w);
;                   const f32x4 hv = xv * gsn[bj]; hw[bj][1].x = cvt_pk_bf16(hv.x, hv.y); hw[bj][1].y = cvt_pk_bf16(hv.z, hv.w); }
;             }
;             if (!NOH && !PLAIN) {
; #pragma unroll
;                 for (int rh = 0; rh < 2; ++rh) { u32x2 rv; rv.x = __shfl_xor(hw[1][rh].x, 8); rv.y = __shfl_xor(hw[1][rh].y, 8);
;                     const unsigned e0 = ERN_EOFF(g, 0, rh);
;                     const unsigned ee = odd ? (e0 - DM + 32) : e0, eo2 = odd ? e0 : (e0 + DM + 32);
;                     *(u32x2*)((char*)ho + 2u * ee) = odd ? rv : hw[0][rh];
;                     *(u32x2*)((char*)ho + 2u * eo2) = odd ? hw[0][rh] : rv; }
;             }
;             if (!PLAIN) { sq0 += __shfl_xor(sq0, 1); sq0 += __shfl_xor(sq0, 2); sq0 += __shfl_xor(sq0, 4);
;             sq1 += __shfl_xor(sq1, 1); sq1 += __shfl_xor(sq1, 2); sq1 += __shfl_xor(sq1, 4); }
;             if (!PLAIN && pc == 0) { sst[g * 16 + rr] = sq0; sst[g * 16 + 8 + rr] = sq1; }
.LBB0_360:
	s_or_b64 exec, exec, s[16:17]
	v_add_u32_e32 v154, 0x120000, v207
	v_add_u32_e32 v100, 0x120080, v207
	v_add_u32_e32 v102, 0x130000, v207
	v_add_u32_e32 v98, 0x130080, v207
	s_waitcnt lgkmcnt(0)
	v_add_u32_e32 v128, 0x140000, v207
	global_load_dwordx4 v[184:187], v128, s[58:59]
	v_add_u32_e32 v129, 0x150000, v207
	global_load_dwordx4 v[188:191], v129, s[58:59]
	v_add_u32_e32 v134, 0x140080, v207
	global_load_dwordx4 v[208:211], v134, s[58:59]
	v_add_u32_e32 v135, 0x150080, v207
	global_load_dwordx4 v[212:215], v135, s[58:59]
	ds_write_b128 v200, v[62:65]
	ds_write_b128 v200, v[58:61] offset:64
	ds_read_b128 v[58:61], v201
	ds_read_b128 v[62:65], v201 offset:1152
	v_mov_b32_e32 v117, v155
	v_mov_b32_e32 v115, v155
	s_waitcnt vmcnt(17) lgkmcnt(1)
	v_pk_fma_f32 v[60:61], v[178:179], v[60:61], v[96:97]
	v_add_u32_e32 v96, 0x40000, v202
	v_pk_fma_f32 v[58:59], v[180:181], v[58:59], v[94:95]
	v_lshlrev_b32_e32 v94, 2, v96
	s_waitcnt vmcnt(16) lgkmcnt(0)
	v_pk_fma_f32 v[64:65], v[178:179], v[64:65], v[92:93]
	v_add_u32_e32 v92, 0x44000, v202
	global_store_dwordx4 v94, v[58:61], s[56:57] nt
	v_pk_mul_f32 v[94:95], v[176:177], v[58:59]
	v_pk_fma_f32 v[62:63], v[180:181], v[62:63], v[90:91]
	v_lshlrev_b32_e32 v90, 2, v92
	v_pk_mul_f32 v[104:105], v[174:175], v[60:61]
	v_cvt_pk_bf16_f32 v94, v94, v95
	s_nop 0
	v_cvt_pk_bf16_f32 v95, v104, v105
	global_store_dwordx4 v90, v[62:65], s[56:57] nt
	v_pk_mul_f32 v[90:91], v[176:177], v[62:63]
	v_pk_mul_f32 v[104:105], v[174:175], v[64:65]
	v_cvt_pk_bf16_f32 v90, v90, v91
	s_nop 0
	v_cvt_pk_bf16_f32 v91, v104, v105
	ds_write_b128 v200, v[54:57]
	ds_write_b128 v200, v[50:53] offset:64
	ds_read_b128 v[50:53], v201
	ds_read_b128 v[54:57], v201 offset:1152
	s_waitcnt vmcnt(17) lgkmcnt(1)
	v_pk_fma_f32 v[50:51], v[168:169], v[50:51], v[86:87]
	v_pk_fma_f32 v[52:53], v[166:167], v[52:53], v[88:89]
	v_lshl_add_u64 v[86:87], s[56:57], 0, v[116:117]
	v_pk_mul_f32 v[88:89], v[172:173], v[50:51]
	s_waitcnt vmcnt(16) lgkmcnt(0)
	v_pk_fma_f32 v[56:57], v[166:167], v[56:57], v[84:85]
	v_pk_fma_f32 v[54:55], v[168:169], v[54:55], v[82:83]
	v_lshl_add_u64 v[82:83], s[56:57], 0, v[114:115]
	global_store_dwordx4 v[86:87], v[50:53], off nt
	v_pk_mul_f32 v[86:87], v[170:171], v[52:53]
	v_cvt_pk_bf16_f32 v88, v88, v89
	v_pk_mul_f32 v[84:85], v[172:173], v[54:55]
	v_cvt_pk_bf16_f32 v89, v86, v87
	global_store_dwordx4 v[82:83], v[54:57], off nt
	ds_bpermute_b32 v82, v203, v88
	ds_bpermute_b32 v83, v203, v89
	v_pk_mul_f32 v[86:87], v[170:171], v[56:57]
	v_cvt_pk_bf16_f32 v84, v84, v85
	s_nop 0
	v_cvt_pk_bf16_f32 v85, v86, v87
	v_lshlrev_b32_e32 v86, 1, v96
	s_waitcnt lgkmcnt(0)
	v_add_u32_e32 v250, 0xfffff040, v86
	v_cndmask_b32_e64 v250, v86, v250, s[40:41]
	v_cndmask_b32_e64 v248, v94, v82, s[40:41]
	v_cndmask_b32_e64 v249, v95, v83, s[40:41]
	global_store_dwordx2 v250, v[248:249], s[54:55]
	v_cndmask_b32_e64 v246, v82, v94, s[40:41]
	v_cndmask_b32_e64 v247, v83, v95, s[40:41]
	s_waitcnt lgkmcnt(1)
	v_add_u32_e32 v82, 0x1040, v86
	v_cndmask_b32_e64 v82, v86, v82, s[38:39]
	global_store_dwordx2 v82, v[246:247], s[54:55]
	ds_bpermute_b32 v82, v203, v84
	s_waitcnt lgkmcnt(1)
	ds_bpermute_b32 v83, v203, v85
	v_lshlrev_b32_e32 v84, 1, v92
	s_waitcnt lgkmcnt(0)
	v_add_u32_e32 v250, 0xfffff040, v84
	v_cndmask_b32_e64 v250, v84, v250, s[40:41]
	v_cndmask_b32_e64 v248, v90, v82, s[40:41]
	v_cndmask_b32_e64 v249, v91, v83, s[40:41]
	global_store_dwordx2 v250, v[248:249], s[54:55]
	v_cndmask_b32_e64 v246, v82, v90, s[40:41]
	v_cndmask_b32_e64 v247, v83, v91, s[40:41]
	v_mul_f32_e32 v51, v51, v51
	v_fmac_f32_e32 v51, v50, v50
	v_mul_f32_e32 v50, v53, v53
	v_mul_f32_e32 v61, v61, v61
	v_fmac_f32_e32 v50, v52, v52
	v_mul_f32_e32 v59, v59, v59
	v_fmac_f32_e32 v61, v60, v60
	v_mul_f32_e32 v60, v63, v63
	v_mul_f32_e32 v63, v65, v65
	v_add_f32_e32 v50, v51, v50
	v_mul_f32_e32 v51, v55, v55
	v_mul_f32_e32 v52, v57, v57
	v_fmac_f32_e32 v63, v64, v64
	v_fmac_f32_e32 v51, v54, v54
	v_fmac_f32_e32 v52, v56, v56
	v_fmac_f32_e32 v59, v58, v58
	v_fmac_f32_e32 v60, v62, v62
	v_add_f32_e32 v51, v51, v52
	v_add_f32_e32 v52, v59, v61
	v_add_f32_e32 v53, v60, v63
	v_add_f32_e32 v50, v52, v50
	v_add_f32_e32 v51, v53, v51
	ds_bpermute_b32 v52, v204, v50
	ds_bpermute_b32 v53, v204, v51
	s_waitcnt lgkmcnt(1)
	v_add_f32_e32 v50, v50, v52
	s_waitcnt lgkmcnt(0)
	v_add_f32_e32 v53, v51, v53
	ds_bpermute_b32 v52, v205, v50
	ds_bpermute_b32 v54, v205, v53
	s_waitcnt lgkmcnt(1)
	v_add_f32_e32 v50, v50, v52
	s_waitcnt lgkmcnt(0)
	v_add_f32_e32 v52, v53, v54
	ds_bpermute_b32 v51, v206, v50
	ds_bpermute_b32 v53, v206, v52
	v_add_u32_e32 v54, 0x1040, v84
	v_cndmask_b32_e64 v54, v84, v54, s[38:39]
	global_store_dwordx2 v54, v[246:247], s[54:55]
	s_and_saveexec_b64 s[16:17], s[42:43]
	s_cbranch_execz .LBB0_370
	s_waitcnt lgkmcnt(1)
	v_add_f32_e32 v50, v50, v51
	s_waitcnt lgkmcnt(0)
	v_add_f32_e32 v51, v52, v53
	ds_write2_b32 v194, v50, v51 offset0:64 offset1:72
; #define LAS __attribute__((address_space(3)))
; #define ERN_EOFF(q, m) (eb + (unsigned)((((q) & 1) * HALF + (m) * 16) * DM + ERN_COL((q) >> 1)))
;     __device__ __forceinline__ void operator()(const f32x4 (&acc)[2][2][4][2], const Unit& u, int wr, int wc, int fr, int fq) const {
;     ...
;         ERN_LOADX(0);
; #pragma unroll
;         for (int g = 0; g < 8; ++g) { const int ai = g >> 2, m = g & 3;
;             if (g + 1 < 8) ERN_LOADX(g + 1);
;             float sq0 = 0.f, sq1 = 0.f; u32x2 hw[2][2];
; #pragma unroll
;             for (int bj = 0; bj < 2; ++bj) {
;                 *(LAS f32x4*)(st + wr_off) = acc[ai][bj][m][0]; *(LAS f32x4*)(st + wr_off + 64) = acc[ai][bj][m][1];
;                 const f32x4 a0 = *(const LAS f32x4*)(st + rd_off), a1 = *(const LAS f32x4*)(st + rd_off + 8 * 144);
;                 { const f32x4 xv = xb[g & 1][bj][0] + gv[bj] * a0; __builtin_nontemporal_store(xv, (f32x4*)((char*)xo + 4u * ERN_EOFF(g, bj, 0)));
;                   sq0 += (xv.x * xv.x + xv.y * xv.y) + (xv.z * xv.z + xv.w * xv.w);
;                   const f32x4 hv = xv * gsn[bj]; hw[bj][0].x = cvt_pk_bf16(hv.x, hv.y); hw[bj][0].y = cvt_pk_bf16(hv.z, hv.w); }
;                 { const f32x4 xv = xb[g & 1][bj][1] + gv[bj] * a1; __builtin_nontemporal_store(xv, (f32x4*)((char*)xo + 4u * ERN_EOFF(g, bj, 1)));
;                   sq1 += (xv.x * xv.x + xv.y * xv.y) + (xv.z * xv.z + xv.w * xv.w);
;                   const f32x4 hv = xv * gsn[bj]; hw[bj][1].x = cvt_pk_bf16(hv.x, hv.y); hw[bj][1].y = cvt_pk_bf16(hv.z, hv.w); }
;             }
;             if (!NOH && !PLAIN) {
; #pragma unroll
;                 for (int rh = 0; rh < 2; ++rh) { u32x2 rv; rv.x = __shfl_xor(hw[1][rh].x, 8); rv.y = __shfl_xor(hw[1][rh].y, 8);
;                     const unsigned e0 = ERN_EOFF(g, 0, rh);
;                     const unsigned ee = odd ? (e0 - DM + 32) : e0, eo2 = odd ? e0 : (e0 + DM + 32);
;                     *(u32x2*)((char*)ho + 2u * ee) = odd ? rv : hw[0][rh];
;                     *(u32x2*)((char*)ho + 2u * eo2) = odd ? hw[0][rh] : rv; }
;             }
;             if (!PLAIN) { sq0 += __shfl_xor(sq0, 1); sq0 += __shfl_xor(sq0, 2); sq0 += __shfl_xor(sq0, 4);
;             sq1 += __shfl_xor(sq1, 1); sq1 += __shfl_xor(sq1, 2); sq1 += __shfl_xor(sq1, 4); }
;             if (!PLAIN && pc == 0) { sst[g * 16 + rr] = sq0; sst[g * 16 + 8 + rr] = sq1; }
.LBB0_370:
	s_or_b64 exec, exec, s[16:17]
	v_add_u32_e32 v88, 0x140000, v207
	v_add_u32_e32 v84, 0x140080, v207
	v_add_u32_e32 v86, 0x150000, v207
	v_add_u32_e32 v82, 0x150080, v207
	s_waitcnt lgkmcnt(0)
	ds_write_b128 v200, v[46:49]
	ds_write_b128 v200, v[42:45] offset:64
	ds_read_b128 v[42:45], v201
	ds_read_b128 v[46:49], v201 offset:1152
	v_mov_b32_e32 v103, v155
	v_mov_b32_e32 v101, v155
	v_mov_b32_e32 v99, v155
	s_waitcnt vmcnt(18) lgkmcnt(1)
	v_mov_b64_e32 v[78:79], v[120:121]
	v_mov_b64_e32 v[80:81], v[122:123]
	v_mov_b64_e32 v[74:75], v[124:125]
	v_mov_b64_e32 v[76:77], v[126:127]
	v_mov_b64_e32 v[70:71], v[136:137]
	v_mov_b64_e32 v[72:73], v[138:139]
	v_mov_b64_e32 v[66:67], v[140:141]
	v_mov_b64_e32 v[68:69], v[142:143]
	v_add_u32_e32 v128, 0x160000, v207
	global_load_dwordx4 v[120:123], v128, s[58:59]
	v_add_u32_e32 v129, 0x170000, v207
	global_load_dwordx4 v[124:127], v129, s[58:59]
	v_add_u32_e32 v134, 0x160080, v207
	global_load_dwordx4 v[136:139], v134, s[58:59]
	v_add_u32_e32 v135, 0x170080, v207
	global_load_dwordx4 v[140:143], v135, s[58:59]
	v_pk_fma_f32 v[44:45], v[178:179], v[44:45], v[80:81]
	v_pk_fma_f32 v[42:43], v[180:181], v[42:43], v[78:79]
	v_lshl_add_u64 v[78:79], s[56:57], 0, v[154:155]
	global_store_dwordx4 v[78:79], v[42:45], off nt
	v_pk_mul_f32 v[78:79], v[176:177], v[42:43]
	s_waitcnt lgkmcnt(0)
	v_pk_fma_f32 v[48:49], v[178:179], v[48:49], v[76:77]
	v_pk_fma_f32 v[46:47], v[180:181], v[46:47], v[74:75]
	v_lshl_add_u64 v[74:75], s[56:57], 0, v[102:103]
	v_pk_mul_f32 v[80:81], v[174:175], v[44:45]
	v_cvt_pk_bf16_f32 v78, v78, v79
	v_pk_mul_f32 v[76:77], v[174:175], v[48:49]
	v_cvt_pk_bf16_f32 v79, v80, v81
	global_store_dwordx4 v[74:75], v[46:49], off nt
	v_pk_mul_f32 v[74:75], v[176:177], v[46:47]
	s_nop 0
	v_cvt_pk_bf16_f32 v74, v74, v75
	v_cvt_pk_bf16_f32 v75, v76, v77
	ds_write_b128 v200, v[38:41]
	ds_write_b128 v200, v[34:37] offset:64
	ds_read_b128 v[34:37], v201
	ds_read_b128 v[38:41], v201 offset:1152
	s_waitcnt lgkmcnt(1)
	v_pk_fma_f32 v[34:35], v[168:169], v[34:35], v[70:71]
	v_pk_fma_f32 v[36:37], v[166:167], v[36:37], v[72:73]
	v_lshl_add_u64 v[70:71], s[56:57], 0, v[100:101]
	v_pk_mul_f32 v[72:73], v[172:173], v[34:35]
	s_waitcnt lgkmcnt(0)
	v_pk_fma_f32 v[40:41], v[166:167], v[40:41], v[68:69]
	v_pk_fma_f32 v[38:39], v[168:169], v[38:39], v[66:67]
	v_lshl_add_u64 v[66:67], s[56:57], 0, v[98:99]
	global_store_dwordx4 v[70:71], v[34:37], off nt
	v_pk_mul_f32 v[70:71], v[170:171], v[36:37]
	v_cvt_pk_bf16_f32 v72, v72, v73
	v_pk_mul_f32 v[68:69], v[172:173], v[38:39]
	v_cvt_pk_bf16_f32 v73, v70, v71
	global_store_dwordx4 v[66:67], v[38:41], off nt
	ds_bpermute_b32 v66, v203, v72
	ds_bpermute_b32 v67, v203, v73
	v_pk_mul_f32 v[70:71], v[170:171], v[40:41]
	v_cvt_pk_bf16_f32 v68, v68, v69
	s_nop 0
	v_cvt_pk_bf16_f32 v69, v70, v71
	v_add_u32_e32 v71, 0x48000, v202
	v_lshlrev_b32_e32 v70, 1, v71
	s_waitcnt lgkmcnt(0)
	v_add_u32_e32 v250, 0xfffff040, v70
	v_cndmask_b32_e64 v250, v70, v250, s[40:41]
	v_cndmask_b32_e64 v248, v78, v66, s[40:41]
	v_cndmask_b32_e64 v249, v79, v67, s[40:41]
	global_store_dwordx2 v250, v[248:249], s[54:55]
	v_cndmask_b32_e64 v246, v66, v78, s[40:41]
	v_cndmask_b32_e64 v247, v67, v79, s[40:41]
	s_waitcnt lgkmcnt(1)
	v_add_u32_e32 v66, 0x1040, v70
	v_cndmask_b32_e64 v66, v70, v66, s[38:39]
	global_store_dwordx2 v66, v[246:247], s[54:55]
	ds_bpermute_b32 v66, v203, v68
	s_waitcnt lgkmcnt(1)
	ds_bpermute_b32 v67, v203, v69
	v_add_u32_e32 v69, 0x4c000, v202
	v_lshlrev_b32_e32 v68, 1, v69
	s_waitcnt lgkmcnt(0)
	v_add_u32_e32 v250, 0xfffff040, v68
	v_cndmask_b32_e64 v250, v68, v250, s[40:41]
	v_cndmask_b32_e64 v248, v74, v66, s[40:41]
	v_cndmask_b32_e64 v249, v75, v67, s[40:41]
	global_store_dwordx2 v250, v[248:249], s[54:55]
	v_cndmask_b32_e64 v246, v66, v74, s[40:41]
	v_cndmask_b32_e64 v247, v67, v75, s[40:41]
	v_mul_f32_e32 v35, v35, v35
	v_fmac_f32_e32 v35, v34, v34
	v_mul_f32_e32 v34, v37, v37
	v_mul_f32_e32 v45, v45, v45
	v_fmac_f32_e32 v34, v36, v36
	v_mul_f32_e32 v43, v43, v43
	v_fmac_f32_e32 v45, v44, v44
	v_mul_f32_e32 v44, v47, v47
	v_mul_f32_e32 v47, v49, v49
	v_add_f32_e32 v34, v35, v34
	v_mul_f32_e32 v35, v39, v39
	v_mul_f32_e32 v36, v41, v41
	v_fmac_f32_e32 v47, v48, v48
	v_fmac_f32_e32 v35, v38, v38
	v_fmac_f32_e32 v36, v40, v40
	v_fmac_f32_e32 v43, v42, v42
	v_fmac_f32_e32 v44, v46, v46
	v_add_f32_e32 v35, v35, v36
	v_add_f32_e32 v36, v43, v45
	v_add_f32_e32 v37, v44, v47
	v_add_f32_e32 v34, v36, v34
	v_add_f32_e32 v35, v37, v35
	ds_bpermute_b32 v36, v204, v34
	ds_bpermute_b32 v37, v204, v35
	s_waitcnt lgkmcnt(1)
	v_add_f32_e32 v34, v34, v36
	s_waitcnt lgkmcnt(0)
	v_add_f32_e32 v37, v35, v37
	ds_bpermute_b32 v36, v205, v34
	ds_bpermute_b32 v38, v205, v37
	s_waitcnt lgkmcnt(1)
	v_add_f32_e32 v34, v34, v36
	s_waitcnt lgkmcnt(0)
	v_add_f32_e32 v36, v37, v38
	ds_bpermute_b32 v35, v206, v34
	ds_bpermute_b32 v37, v206, v36
	v_add_u32_e32 v38, 0x1040, v68
	v_cndmask_b32_e64 v38, v68, v38, s[38:39]
	global_store_dwordx2 v38, v[246:247], s[54:55]
	s_and_saveexec_b64 s[16:17], s[42:43]
	s_cbranch_execz .LBB0_380
	s_waitcnt lgkmcnt(1)
	v_add_f32_e32 v34, v34, v35
	s_waitcnt lgkmcnt(0)
	v_add_f32_e32 v35, v36, v37
	ds_write2_b32 v194, v34, v35 offset0:80 offset1:88
; #define LAS __attribute__((address_space(3)))
; #define ERN_EOFF(q, m) (eb + (unsigned)((((q) & 1) * HALF + (m) * 16) * DM + ERN_COL((q) >> 1)))
;     __device__ __forceinline__ void operator()(const f32x4 (&acc)[2][2][4][2], const Unit& u, int wr, int wc, int fr, int fq) const {
;     ...
;         ERN_LOADX(0);
; #pragma unroll
;         for (int g = 0; g < 8; ++g) { const int ai = g >> 2, m = g & 3;
;             if (g + 1 < 8) ERN_LOADX(g + 1);
;             float sq0 = 0.f, sq1 = 0.f; u32x2 hw[2][2];
; #pragma unroll
;             for (int bj = 0; bj < 2; ++bj) {
;                 *(LAS f32x4*)(st + wr_off) = acc[ai][bj][m][0]; *(LAS f32x4*)(st + wr_off + 64) = acc[ai][bj][m][1];
;                 const f32x4 a0 = *(const LAS f32x4*)(st + rd_off), a1 = *(const LAS f32x4*)(st + rd_off + 8 * 144);
;                 { const f32x4 xv = xb[g & 1][bj][0] + gv[bj] * a0; __builtin_nontemporal_store(xv, (f32x4*)((char*)xo + 4u * ERN_EOFF(g, bj, 0)));
;                   sq0 += (xv.x * xv.x + xv.y * xv.y) + (xv.z * xv.z + xv.w * xv.w);
;                   const f32x4 hv = xv * gsn[bj]; hw[bj][0].x = cvt_pk_bf16(hv.x, hv.y); hw[bj][0].y = cvt_pk_bf16(hv.z, hv.w); }
;                 { const f32x4 xv = xb[g & 1][bj][1] + gv[bj] * a1; __builtin_nontemporal_store(xv, (f32x4*)((char*)xo + 4u * ERN_EOFF(g, bj, 1)));
;                   sq1 += (xv.x * xv.x + xv.y * xv.y) + (xv.z * xv.z + xv.w * xv.w);
;                   const f32x4 hv = xv * gsn[bj]; hw[bj][1].x = cvt_pk_bf16(hv.x, hv.y); hw[bj][1].y = cvt_pk_bf16(hv.z, hv.w); }
;             }
;             if (!NOH && !PLAIN) {
; #pragma unroll
;                 for (int rh = 0; rh < 2; ++rh) { u32x2 rv; rv.x = __shfl_xor(hw[1][rh].x, 8); rv.y = __shfl_xor(hw[1][rh].y, 8);
;                     const unsigned e0 = ERN_EOFF(g, 0, rh);
;                     const unsigned ee = odd ? (e0 - DM + 32) : e0, eo2 = odd ? e0 : (e0 + DM + 32);
;                     *(u32x2*)((char*)ho + 2u * ee) = odd ? rv : hw[0][rh];
;                     *(u32x2*)((char*)ho + 2u * eo2) = odd ? hw[0][rh] : rv; }
;             }
;             if (!PLAIN) { sq0 += __shfl_xor(sq0, 1); sq0 += __shfl_xor(sq0, 2); sq0 += __shfl_xor(sq0, 4);
;             sq1 += __shfl_xor(sq1, 1); sq1 += __shfl_xor(sq1, 2); sq1 += __shfl_xor(sq1, 4); }
;             if (!PLAIN && pc == 0) { sst[g * 16 + rr] = sq0; sst[g * 16 + 8 + rr] = sq1; }
.LBB0_380:
	s_or_b64 exec, exec, s[16:17]
	v_add_u32_e32 v154, 0x160000, v207
	v_add_u32_e32 v68, 0x160080, v207
	v_add_u32_e32 v70, 0x170000, v207
	v_add_u32_e32 v66, 0x170080, v207
	s_waitcnt lgkmcnt(0)
	ds_write_b128 v200, v[30:33]
	ds_write_b128 v200, v[26:29] offset:64
	ds_read_b128 v[26:29], v201
	ds_read_b128 v[30:33], v201 offset:1152
	v_mov_b32_e32 v89, v155
	v_mov_b32_e32 v87, v155
	v_mov_b32_e32 v85, v155
	s_waitcnt vmcnt(18) lgkmcnt(1)
	v_mov_b64_e32 v[62:63], v[184:185]
	v_mov_b64_e32 v[64:65], v[186:187]
	v_mov_b64_e32 v[58:59], v[188:189]
	v_mov_b64_e32 v[60:61], v[190:191]
	v_mov_b64_e32 v[54:55], v[208:209]
	v_mov_b64_e32 v[56:57], v[210:211]
	v_mov_b64_e32 v[50:51], v[212:213]
	v_mov_b64_e32 v[52:53], v[214:215]
	v_pk_fma_f32 v[28:29], v[178:179], v[28:29], v[64:65]
	v_pk_fma_f32 v[26:27], v[180:181], v[26:27], v[62:63]
	v_lshl_add_u64 v[62:63], s[56:57], 0, v[88:89]
	global_store_dwordx4 v[62:63], v[26:29], off nt
	v_pk_mul_f32 v[62:63], v[176:177], v[26:27]
	s_waitcnt lgkmcnt(0)
	v_pk_fma_f32 v[32:33], v[178:179], v[32:33], v[60:61]
	v_pk_fma_f32 v[30:31], v[180:181], v[30:31], v[58:59]
	v_lshl_add_u64 v[58:59], s[56:57], 0, v[86:87]
	v_pk_mul_f32 v[64:65], v[174:175], v[28:29]
	v_cvt_pk_bf16_f32 v62, v62, v63
	v_pk_mul_f32 v[60:61], v[174:175], v[32:33]
	v_cvt_pk_bf16_f32 v63, v64, v65
	global_store_dwordx4 v[58:59], v[30:33], off nt
	v_pk_mul_f32 v[58:59], v[176:177], v[30:31]
	v_mov_b32_e32 v83, v155
	v_cvt_pk_bf16_f32 v58, v58, v59
	v_cvt_pk_bf16_f32 v59, v60, v61
	ds_write_b128 v200, v[22:25]
	ds_write_b128 v200, v[18:21] offset:64
	ds_read_b128 v[18:21], v201
	ds_read_b128 v[22:25], v201 offset:1152
	s_waitcnt lgkmcnt(1)
	v_pk_fma_f32 v[18:19], v[168:169], v[18:19], v[54:55]
	v_pk_fma_f32 v[20:21], v[166:167], v[20:21], v[56:57]
	v_lshl_add_u64 v[54:55], s[56:57], 0, v[84:85]
	v_pk_mul_f32 v[56:57], v[172:173], v[18:19]
	s_waitcnt lgkmcnt(0)
	v_pk_fma_f32 v[24:25], v[166:167], v[24:25], v[52:53]
	v_pk_fma_f32 v[22:23], v[168:169], v[22:23], v[50:51]
	v_lshl_add_u64 v[50:51], s[56:57], 0, v[82:83]
	global_store_dwordx4 v[54:55], v[18:21], off nt
	v_pk_mul_f32 v[54:55], v[170:171], v[20:21]
	v_cvt_pk_bf16_f32 v56, v56, v57
	v_pk_mul_f32 v[52:53], v[172:173], v[22:23]
	v_cvt_pk_bf16_f32 v57, v54, v55
	global_store_dwordx4 v[50:51], v[22:25], off nt
	ds_bpermute_b32 v50, v203, v56
	ds_bpermute_b32 v51, v203, v57
	v_pk_mul_f32 v[54:55], v[170:171], v[24:25]
	v_cvt_pk_bf16_f32 v52, v52, v53
	s_nop 0
	v_cvt_pk_bf16_f32 v53, v54, v55
	v_add_u32_e32 v55, 0x50000, v202
	v_lshlrev_b32_e32 v54, 1, v55
	s_waitcnt lgkmcnt(0)
	v_add_u32_e32 v250, 0xfffff040, v54
	v_cndmask_b32_e64 v250, v54, v250, s[40:41]
	v_cndmask_b32_e64 v248, v62, v50, s[40:41]
	v_cndmask_b32_e64 v249, v63, v51, s[40:41]
	global_store_dwordx2 v250, v[248:249], s[54:55]
	v_cndmask_b32_e64 v246, v50, v62, s[40:41]
	v_cndmask_b32_e64 v247, v51, v63, s[40:41]
	s_waitcnt lgkmcnt(1)
	v_add_u32_e32 v50, 0x1040, v54
	v_cndmask_b32_e64 v50, v54, v50, s[38:39]
	global_store_dwordx2 v50, v[246:247], s[54:55]
	ds_bpermute_b32 v50, v203, v52
	s_waitcnt lgkmcnt(1)
	ds_bpermute_b32 v51, v203, v53
	v_add_u32_e32 v53, 0x54000, v202
	v_lshlrev_b32_e32 v52, 1, v53
	s_waitcnt lgkmcnt(0)
	v_add_u32_e32 v250, 0xfffff040, v52
	v_cndmask_b32_e64 v250, v52, v250, s[40:41]
	v_cndmask_b32_e64 v248, v58, v50, s[40:41]
	v_cndmask_b32_e64 v249, v59, v51, s[40:41]
	global_store_dwordx2 v250, v[248:249], s[54:55]
	v_cndmask_b32_e64 v246, v50, v58, s[40:41]
	v_cndmask_b32_e64 v247, v51, v59, s[40:41]
	v_mul_f32_e32 v19, v19, v19
	v_fmac_f32_e32 v19, v18, v18
	v_mul_f32_e32 v18, v21, v21
	v_mul_f32_e32 v29, v29, v29
	v_fmac_f32_e32 v18, v20, v20
	v_mul_f32_e32 v27, v27, v27
	v_fmac_f32_e32 v29, v28, v28
	v_mul_f32_e32 v28, v31, v31
	v_mul_f32_e32 v31, v33, v33
	v_add_f32_e32 v18, v19, v18
	v_mul_f32_e32 v19, v23, v23
	v_mul_f32_e32 v20, v25, v25
	v_fmac_f32_e32 v31, v32, v32
	v_fmac_f32_e32 v19, v22, v22
	v_fmac_f32_e32 v20, v24, v24
	v_fmac_f32_e32 v27, v26, v26
	v_fmac_f32_e32 v28, v30, v30
	v_add_f32_e32 v19, v19, v20
	v_add_f32_e32 v20, v27, v29
	v_add_f32_e32 v21, v28, v31
	v_add_f32_e32 v18, v20, v18
	v_add_f32_e32 v19, v21, v19
	ds_bpermute_b32 v20, v204, v18
	ds_bpermute_b32 v21, v204, v19
	s_waitcnt lgkmcnt(1)
	v_add_f32_e32 v18, v18, v20
	s_waitcnt lgkmcnt(0)
	v_add_f32_e32 v21, v19, v21
	ds_bpermute_b32 v20, v205, v18
	ds_bpermute_b32 v22, v205, v21
	s_waitcnt lgkmcnt(1)
	v_add_f32_e32 v18, v18, v20
	s_waitcnt lgkmcnt(0)
	v_add_f32_e32 v20, v21, v22
	ds_bpermute_b32 v19, v206, v18
	ds_bpermute_b32 v21, v206, v20
	v_add_u32_e32 v22, 0x1040, v52
	v_cndmask_b32_e64 v22, v52, v22, s[38:39]
	global_store_dwordx2 v22, v[246:247], s[54:55]
	s_and_saveexec_b64 s[16:17], s[42:43]
	s_cbranch_execz .LBB0_390
	s_waitcnt lgkmcnt(1)
	v_add_f32_e32 v18, v18, v19
	s_waitcnt lgkmcnt(0)
	v_add_f32_e32 v19, v20, v21
	ds_write2_b32 v194, v18, v19 offset0:96 offset1:104
; #define LAS __attribute__((address_space(3)))
; #define ERN_EOFF(q, m) (eb + (unsigned)((((q) & 1) * HALF + (m) * 16) * DM + ERN_COL((q) >> 1)))
;     __device__ __forceinline__ void operator()(const f32x4 (&acc)[2][2][4][2], const Unit& u, int wr, int wc, int fr, int fq) const {
;     ...
;         ERN_LOADX(0);
; #pragma unroll
;         for (int g = 0; g < 8; ++g) { const int ai = g >> 2, m = g & 3;
;             if (g + 1 < 8) ERN_LOADX(g + 1);
;             float sq0 = 0.f, sq1 = 0.f; u32x2 hw[2][2];
; #pragma unroll
;             for (int bj = 0; bj < 2; ++bj) {
;                 *(LAS f32x4*)(st + wr_off) = acc[ai][bj][m][0]; *(LAS f32x4*)(st + wr_off + 64) = acc[ai][bj][m][1];
;                 const f32x4 a0 = *(const LAS f32x4*)(st + rd_off), a1 = *(const LAS f32x4*)(st + rd_off + 8 * 144);
;                 { const f32x4 xv = xb[g & 1][bj][0] + gv[bj] * a0; __builtin_nontemporal_store(xv, (f32x4*)((char*)xo + 4u * ERN_EOFF(g, bj, 0)));
;                   sq0 += (xv.x * xv.x + xv.y * xv.y) + (xv.z * xv.z + xv.w * xv.w);
;                   const f32x4 hv = xv * gsn[bj]; hw[bj][0].x = cvt_pk_bf16(hv.x, hv.y); hw[bj][0].y = cvt_pk_bf16(hv.z, hv.w); }
;                 { const f32x4 xv = xb[g & 1][bj][1] + gv[bj] * a1; __builtin_nontemporal_store(xv, (f32x4*)((char*)xo + 4u * ERN_EOFF(g, bj, 1)));
;                   sq1 += (xv.x * xv.x + xv.y * xv.y) + (xv.z * xv.z + xv.w * xv.w);
;                   const f32x4 hv = xv * gsn[bj]; hw[bj][1].x = cvt_pk_bf16(hv.x, hv.y); hw[bj][1].y = cvt_pk_bf16(hv.z, hv.w); }
;             }
;             if (!NOH && !PLAIN) {
; #pragma unroll
;                 for (int rh = 0; rh < 2; ++rh) { u32x2 rv; rv.x = __shfl_xor(hw[1][rh].x, 8); rv.y = __shfl_xor(hw[1][rh].y, 8);
;                     const unsigned e0 = ERN_EOFF(g, 0, rh);
;                     const unsigned ee = odd ? (e0 - DM + 32) : e0, eo2 = odd ? e0 : (e0 + DM + 32);
;                     *(u32x2*)((char*)ho + 2u * ee) = odd ? rv : hw[0][rh];
;                     *(u32x2*)((char*)ho + 2u * eo2) = odd ? hw[0][rh] : rv; }
;             }
;             if (!PLAIN) { sq0 += __shfl_xor(sq0, 1); sq0 += __shfl_xor(sq0, 2); sq0 += __shfl_xor(sq0, 4);
;             sq1 += __shfl_xor(sq1, 1); sq1 += __shfl_xor(sq1, 2); sq1 += __shfl_xor(sq1, 4); }
;             if (!PLAIN && pc == 0) { sst[g * 16 + rr] = sq0; sst[g * 16 + 8 + rr] = sq1; }
.LBB0_390:
	s_or_b64 exec, exec, s[16:17]
	ds_write_b128 v200, v[14:17]
	ds_write_b128 v200, v[10:13] offset:64
	ds_read_b128 v[10:13], v201
	ds_read_b128 v[14:17], v201 offset:1152
	s_waitcnt lgkmcnt(5)
	v_lshl_add_u64 v[18:19], s[56:57], 0, v[154:155]
	v_mov_b32_e32 v71, v155
	v_mov_b32_e32 v69, v155
	s_waitcnt vmcnt(14) lgkmcnt(1)
	v_mov_b64_e32 v[46:47], v[120:121]
	v_mov_b64_e32 v[48:49], v[122:123]
	v_mov_b64_e32 v[42:43], v[124:125]
	v_mov_b64_e32 v[44:45], v[126:127]
	v_mov_b64_e32 v[38:39], v[136:137]
	v_mov_b64_e32 v[40:41], v[138:139]
	v_mov_b64_e32 v[34:35], v[140:141]
	v_mov_b64_e32 v[36:37], v[142:143]
	v_pk_fma_f32 v[12:13], v[178:179], v[12:13], v[48:49]
	v_pk_fma_f32 v[10:11], v[180:181], v[10:11], v[46:47]
	global_store_dwordx4 v[18:19], v[10:13], off nt
	v_pk_mul_f32 v[18:19], v[174:175], v[12:13]
	v_pk_mul_f32 v[20:21], v[176:177], v[10:11]
	s_waitcnt lgkmcnt(0)
	v_pk_fma_f32 v[16:17], v[178:179], v[16:17], v[44:45]
	v_cvt_pk_bf16_f32 v20, v20, v21
	v_cvt_pk_bf16_f32 v21, v18, v19
	v_pk_fma_f32 v[14:15], v[180:181], v[14:15], v[42:43]
	v_lshl_add_u64 v[18:19], s[56:57], 0, v[70:71]
	global_store_dwordx4 v[18:19], v[14:17], off nt
	v_pk_mul_f32 v[18:19], v[176:177], v[14:15]
	v_pk_mul_f32 v[22:23], v[174:175], v[16:17]
	v_cvt_pk_bf16_f32 v18, v18, v19
	v_mov_b32_e32 v67, v155
	v_cvt_pk_bf16_f32 v19, v22, v23
	ds_write_b128 v200, v[6:9]
	ds_write_b128 v200, v[2:5] offset:64
	ds_read_b128 v[2:5], v201
	ds_read_b128 v[6:9], v201 offset:1152
	v_lshl_add_u64 v[22:23], s[56:57], 0, v[68:69]
	s_waitcnt lgkmcnt(1)
	v_pk_fma_f32 v[4:5], v[166:167], v[4:5], v[40:41]
	v_pk_fma_f32 v[2:3], v[168:169], v[2:3], v[38:39]
	global_store_dwordx4 v[22:23], v[2:5], off nt
	v_pk_mul_f32 v[22:23], v[170:171], v[4:5]
	v_pk_mul_f32 v[24:25], v[172:173], v[2:3]
	s_waitcnt lgkmcnt(0)
	v_pk_fma_f32 v[8:9], v[166:167], v[8:9], v[36:37]
	v_cvt_pk_bf16_f32 v28, v24, v25
	v_cvt_pk_bf16_f32 v29, v22, v23
	v_pk_fma_f32 v[6:7], v[168:169], v[6:7], v[34:35]
	v_lshl_add_u64 v[22:23], s[56:57], 0, v[66:67]
	global_store_dwordx4 v[22:23], v[6:9], off nt
	ds_bpermute_b32 v22, v203, v28
	ds_bpermute_b32 v23, v203, v29
	v_pk_mul_f32 v[26:27], v[170:171], v[8:9]
	v_pk_mul_f32 v[24:25], v[172:173], v[6:7]
	s_nop 0
	v_cvt_pk_bf16_f32 v24, v24, v25
	v_cvt_pk_bf16_f32 v25, v26, v27
	v_add_u32_e32 v27, 0x58000, v202
	v_lshlrev_b32_e32 v26, 1, v27
	s_waitcnt lgkmcnt(0)
	v_add_u32_e32 v250, 0xfffff040, v26
	v_cndmask_b32_e64 v250, v26, v250, s[40:41]
	v_cndmask_b32_e64 v248, v20, v22, s[40:41]
	v_cndmask_b32_e64 v249, v21, v23, s[40:41]
	global_store_dwordx2 v250, v[248:249], s[54:55]
	v_cndmask_b32_e64 v246, v22, v20, s[40:41]
	v_cndmask_b32_e64 v247, v23, v21, s[40:41]
	s_waitcnt lgkmcnt(1)
	v_add_u32_e32 v22, 0x1040, v26
	v_cndmask_b32_e64 v22, v26, v22, s[38:39]
	global_store_dwordx2 v22, v[246:247], s[54:55]
	ds_bpermute_b32 v20, v203, v24
	ds_bpermute_b32 v21, v203, v25
	s_waitcnt lgkmcnt(2)
	v_add_u32_e32 v23, 0x5c000, v202
	v_lshlrev_b32_e32 v22, 1, v23
	s_waitcnt lgkmcnt(0)
	v_add_u32_e32 v250, 0xfffff040, v22
	v_cndmask_b32_e64 v250, v22, v250, s[40:41]
	v_cndmask_b32_e64 v248, v18, v20, s[40:41]
	v_cndmask_b32_e64 v249, v19, v21, s[40:41]
	global_store_dwordx2 v250, v[248:249], s[54:55]
	v_cndmask_b32_e64 v246, v20, v18, s[40:41]
	v_cndmask_b32_e64 v247, v21, v19, s[40:41]
	v_mul_f32_e32 v3, v3, v3
	v_fmac_f32_e32 v3, v2, v2
	v_mul_f32_e32 v2, v5, v5
	v_mul_f32_e32 v13, v13, v13
	v_fmac_f32_e32 v2, v4, v4
	v_mul_f32_e32 v11, v11, v11
	v_fmac_f32_e32 v13, v12, v12
	v_mul_f32_e32 v12, v15, v15
	v_mul_f32_e32 v15, v17, v17
	v_add_f32_e32 v2, v3, v2
	v_mul_f32_e32 v3, v7, v7
	v_mul_f32_e32 v4, v9, v9
	v_fmac_f32_e32 v15, v16, v16
	v_fmac_f32_e32 v3, v6, v6
	v_fmac_f32_e32 v4, v8, v8
	v_fmac_f32_e32 v11, v10, v10
	v_fmac_f32_e32 v12, v14, v14
	v_add_f32_e32 v3, v3, v4
	v_add_f32_e32 v4, v11, v13
	v_add_f32_e32 v5, v12, v15
	v_add_f32_e32 v2, v4, v2
	v_add_f32_e32 v3, v5, v3
	ds_bpermute_b32 v4, v204, v2
	ds_bpermute_b32 v5, v204, v3
	s_waitcnt lgkmcnt(1)
	v_add_f32_e32 v2, v2, v4
	s_waitcnt lgkmcnt(0)
	v_add_f32_e32 v5, v3, v5
	ds_bpermute_b32 v4, v205, v2
	ds_bpermute_b32 v6, v205, v5
	s_waitcnt lgkmcnt(1)
	v_add_f32_e32 v2, v2, v4
	s_waitcnt lgkmcnt(0)
	v_add_f32_e32 v4, v5, v6
	ds_bpermute_b32 v3, v206, v2
	ds_bpermute_b32 v5, v206, v4
	v_add_u32_e32 v6, 0x1040, v22
	v_cndmask_b32_e64 v6, v22, v6, s[38:39]
	global_store_dwordx2 v6, v[246:247], s[54:55]
	s_and_saveexec_b64 s[16:17], s[42:43]
	s_cbranch_execz .LBB0_400
	s_waitcnt lgkmcnt(1)
	v_add_f32_e32 v2, v2, v3
	s_waitcnt lgkmcnt(0)
	v_add_f32_e32 v3, v4, v5
	ds_write2_b32 v194, v2, v3 offset0:112 offset1:120

; #define LAS __attribute__((address_space(3)))
; #define ERN_EOFF(q, m) (eb + (unsigned)((((q) & 1) * HALF + (m) * 16) * DM + ERN_COL((q) >> 1)))
;     __device__ __forceinline__ void operator()(const f32x4 (&acc)[2][2][4][2], const Unit& u, int wr, int wc, int fr, int fq) const {
;     ...
;         ERN_LOADX(0);
; #pragma unroll
;         for (int g = 0; g < 8; ++g) { const int ai = g >> 2, m = g & 3;
;             if (g + 1 < 8) ERN_LOADX(g + 1);
;             float sq0 = 0.f, sq1 = 0.f; u32x2 hw[2][2];
; #pragma unroll
;             for (int bj = 0; bj < 2; ++bj) {
;                 *(LAS f32x4*)(st + wr_off) = acc[ai][bj][m][0]; *(LAS f32x4*)(st + wr_off + 64) = acc[ai][bj][m][1];
;                 const f32x4 a0 = *(const LAS f32x4*)(st + rd_off), a1 = *(const LAS f32x4*)(st + rd_off + 8 * 144);
;                 { const f32x4 xv = xb[g & 1][bj][0] + gv[bj] * a0; __builtin_nontemporal_store(xv, (f32x4*)((char*)xo + 4u * ERN_EOFF(g, bj, 0)));
;                   sq0 += (xv.x * xv.x + xv.y * xv.y) + (xv.z * xv.z + xv.w * xv.w);
;                   const f32x4 hv = xv * gsn[bj]; hw[bj][0].x = cvt_pk_bf16(hv.x, hv.y); hw[bj][0].y = cvt_pk_bf16(hv.z, hv.w); }
;                 { const f32x4 xv = xb[g & 1][bj][1] + gv[bj] * a1; __builtin_nontemporal_store(xv, (f32x4*)((char*)xo + 4u * ERN_EOFF(g, bj, 1)));
;                   sq1 += (xv.x * xv.x + xv.y * xv.y) + (xv.z * xv.z + xv.w * xv.w);
;                   const f32x4 hv = xv * gsn[bj]; hw[bj][1].x = cvt_pk_bf16(hv.x, hv.y); hw[bj][1].y = cvt_pk_bf16(hv.z, hv.w); }
;             }
;             if (!NOH && !PLAIN) {
; #pragma unroll
;                 for (int rh = 0; rh < 2; ++rh) { u32x2 rv; rv.x = __shfl_xor(hw[1][rh].x, 8); rv.y = __shfl_xor(hw[1][rh].y, 8);
;                     const unsigned e0 = ERN_EOFF(g, 0, rh);
;                     const unsigned ee = odd ? (e0 - DM + 32) : e0, eo2 = odd ? e0 : (e0 + DM + 32);
;                     *(u32x2*)((char*)ho + 2u * ee) = odd ? rv : hw[0][rh];
;                     *(u32x2*)((char*)ho + 2u * eo2) = odd ? hw[0][rh] : rv; }
;             }
;             if (!PLAIN) { sq0 += __shfl_xor(sq0, 1); sq0 += __shfl_xor(sq0, 2); sq0 += __shfl_xor(sq0, 4);
;             sq1 += __shfl_xor(sq1, 1); sq1 += __shfl_xor(sq1, 2); sq1 += __shfl_xor(sq1, 4); }
;             if (!PLAIN && pc == 0) { sst[g * 16 + rr] = sq0; sst[g * 16 + 8 + rr] = sq1; }
.LBB0_1283:
	s_or_b64 exec, exec, s[16:17]
	v_lshl_add_u64 v[124:125], s[48:49], 0, v[162:163]
	v_add_u32_e32 v90, 0x100000, v205
	s_waitcnt lgkmcnt(1)
	v_add_u32_e32 v91, 0x110000, v205
	v_add_u32_e32 v162, 0x100080, v205
	global_load_dwordx4 v[102:105], v90, s[48:49]
	global_load_dwordx4 v[98:101], v91, s[48:49]
	v_add_u32_e32 v122, 0x110080, v205
	global_load_dwordx4 v[94:97], v162, s[48:49]
	s_waitcnt lgkmcnt(0)
	global_load_dwordx4 v[90:93], v122, s[48:49]
	v_add_u32_e32 v136, 0x120000, v205
	global_load_dwordx4 v[128:131], v136, s[48:49]
	v_add_u32_e32 v137, 0x130000, v205
	global_load_dwordx4 v[132:135], v137, s[48:49]
	v_add_u32_e32 v142, 0x120080, v205
	global_load_dwordx4 v[144:147], v142, s[48:49]
	v_add_u32_e32 v143, 0x130080, v205
	global_load_dwordx4 v[148:151], v143, s[48:49]
	ds_write_b128 v200, v[86:89]
	ds_write_b128 v200, v[82:85] offset:64
	ds_read_b128 v[82:85], v201
	ds_read_b128 v[86:89], v201 offset:1152
	v_mov_b32_e32 v139, v163
	v_mov_b32_e32 v141, v163
	s_waitcnt vmcnt(15) lgkmcnt(1)
	v_pk_fma_f32 v[84:85], v[56:57], v[84:85], v[120:121]
	v_add_u32_e32 v120, 0x18000, v202
	v_pk_fma_f32 v[82:83], v[54:55], v[82:83], v[118:119]
	v_lshlrev_b32_e32 v118, 2, v120
	s_waitcnt lgkmcnt(0)
	v_pk_fma_f32 v[86:87], v[54:55], v[86:87], v[114:115]
	global_store_dwordx4 v118, v[82:85], s[48:49] nt
	v_pk_mul_f32 v[118:119], v[180:181], v[82:83]
	v_pk_fma_f32 v[88:89], v[56:57], v[88:89], v[116:117]
	v_pk_mul_f32 v[114:115], v[180:181], v[86:87]
	v_pk_mul_f32 v[126:127], v[178:179], v[84:85]
	v_cvt_pk_bf16_f32 v118, v118, v119
	v_pk_mul_f32 v[116:117], v[178:179], v[88:89]
	v_cvt_pk_bf16_f32 v119, v126, v127
	global_store_dwordx4 v[124:125], v[86:89], off nt
	v_cvt_pk_bf16_f32 v114, v114, v115
	v_cvt_pk_bf16_f32 v115, v116, v117
	ds_write_b128 v200, v[78:81]
	ds_write_b128 v200, v[74:77] offset:64
	ds_read_b128 v[74:77], v201
	ds_read_b128 v[78:81], v201 offset:1152
	v_lshl_add_u64 v[116:117], s[48:49], 0, v[138:139]
	v_lshl_add_u64 v[124:125], s[48:49], 0, v[140:141]
	s_waitcnt lgkmcnt(1)
	v_pk_fma_f32 v[74:75], v[50:51], v[74:75], v[110:111]
	v_pk_fma_f32 v[76:77], v[52:53], v[76:77], v[112:113]
	v_pk_mul_f32 v[112:113], v[176:177], v[74:75]
	global_store_dwordx4 v[116:117], v[74:77], off nt
	v_pk_mul_f32 v[110:111], v[174:175], v[76:77]
	v_cvt_pk_bf16_f32 v112, v112, v113
	s_waitcnt vmcnt(17) lgkmcnt(0)
	v_pk_fma_f32 v[78:79], v[50:51], v[78:79], v[106:107]
	v_cvt_pk_bf16_f32 v113, v110, v111
	ds_bpermute_b32 v106, v203, v112
	ds_bpermute_b32 v107, v203, v113
	v_pk_fma_f32 v[80:81], v[52:53], v[80:81], v[108:109]
	v_pk_mul_f32 v[108:109], v[176:177], v[78:79]
	v_pk_mul_f32 v[110:111], v[174:175], v[80:81]
	global_store_dwordx4 v[124:125], v[78:81], off nt
	v_cvt_pk_bf16_f32 v108, v108, v109
	v_cvt_pk_bf16_f32 v109, v110, v111
	v_lshlrev_b32_e32 v110, 1, v120
	s_waitcnt lgkmcnt(0)
	v_add_u32_e32 v250, 0xfffff040, v110
	v_cndmask_b32_e64 v250, v110, v250, s[40:41]
	v_cndmask_b32_e64 v248, v118, v106, s[40:41]
	v_cndmask_b32_e64 v249, v119, v107, s[40:41]
	global_store_dwordx2 v250, v[248:249], s[46:47]
	v_cndmask_b32_e64 v246, v106, v118, s[40:41]
	v_cndmask_b32_e64 v247, v107, v119, s[40:41]
	s_waitcnt lgkmcnt(1)
	v_add_u32_e32 v106, 0x1040, v110
	v_cndmask_b32_e64 v106, v110, v106, s[38:39]
	global_store_dwordx2 v106, v[246:247], s[46:47]
	ds_bpermute_b32 v106, v203, v108
	s_waitcnt lgkmcnt(1)
	ds_bpermute_b32 v107, v203, v109
	v_add_u32_e32 v109, 0x1c000, v202
	v_lshlrev_b32_e32 v108, 1, v109
	s_waitcnt lgkmcnt(0)
	v_add_u32_e32 v250, 0xfffff040, v108
	v_cndmask_b32_e64 v250, v108, v250, s[40:41]
	v_cndmask_b32_e64 v248, v114, v106, s[40:41]
	v_cndmask_b32_e64 v249, v115, v107, s[40:41]
	global_store_dwordx2 v250, v[248:249], s[46:47]
	v_cndmask_b32_e64 v246, v106, v114, s[40:41]
	v_cndmask_b32_e64 v247, v107, v115, s[40:41]
	v_mul_f32_e32 v75, v75, v75
	v_fmac_f32_e32 v75, v74, v74
	v_mul_f32_e32 v74, v77, v77
	v_mul_f32_e32 v85, v85, v85
	v_fmac_f32_e32 v74, v76, v76
	v_mul_f32_e32 v83, v83, v83
	v_fmac_f32_e32 v85, v84, v84
	v_mul_f32_e32 v84, v87, v87
	v_mul_f32_e32 v87, v89, v89
	v_add_f32_e32 v74, v75, v74
	v_mul_f32_e32 v75, v79, v79
	v_mul_f32_e32 v76, v81, v81
	v_fmac_f32_e32 v87, v88, v88
	v_fmac_f32_e32 v75, v78, v78
	v_fmac_f32_e32 v76, v80, v80
	v_fmac_f32_e32 v83, v82, v82
	v_fmac_f32_e32 v84, v86, v86
	v_add_f32_e32 v75, v75, v76
	v_add_f32_e32 v76, v83, v85
	v_add_f32_e32 v77, v84, v87
	v_add_f32_e32 v74, v76, v74
	v_add_f32_e32 v75, v77, v75
	ds_bpermute_b32 v76, v190, v74
	ds_bpermute_b32 v77, v190, v75
	s_waitcnt lgkmcnt(1)
	v_add_f32_e32 v74, v74, v76
	s_waitcnt lgkmcnt(0)
	v_add_f32_e32 v77, v75, v77
	ds_bpermute_b32 v76, v191, v74
	ds_bpermute_b32 v78, v191, v77
	s_waitcnt lgkmcnt(1)
	v_add_f32_e32 v74, v74, v76
	s_waitcnt lgkmcnt(0)
	v_add_f32_e32 v76, v77, v78
	ds_bpermute_b32 v75, v204, v74
	ds_bpermute_b32 v77, v204, v76
	v_add_u32_e32 v78, 0x1040, v108
	v_cndmask_b32_e64 v78, v108, v78, s[38:39]
	global_store_dwordx2 v78, v[246:247], s[46:47]
	s_and_saveexec_b64 s[16:17], s[42:43]
	s_cbranch_execz .LBB0_1293
	s_waitcnt lgkmcnt(1)
	v_add_f32_e32 v74, v74, v75
	s_waitcnt lgkmcnt(0)
	v_add_f32_e32 v75, v76, v77
	ds_write2_b32 v194, v74, v75 offset0:48 offset1:56
; #define LAS __attribute__((address_space(3)))
; #define ERN_EOFF(q, m) (eb + (unsigned)((((q) & 1) * HALF + (m) * 16) * DM + ERN_COL((q) >> 1)))
;     __device__ __forceinline__ void operator()(const f32x4 (&acc)[2][2][4][2], const Unit& u, int wr, int wc, int fr, int fq) const {
;     ...
;         ERN_LOADX(0);
; #pragma unroll
;         for (int g = 0; g < 8; ++g) { const int ai = g >> 2, m = g & 3;
;             if (g + 1 < 8) ERN_LOADX(g + 1);
;             float sq0 = 0.f, sq1 = 0.f; u32x2 hw[2][2];
; #pragma unroll
;             for (int bj = 0; bj < 2; ++bj) {
;                 *(LAS f32x4*)(st + wr_off) = acc[ai][bj][m][0]; *(LAS f32x4*)(st + wr_off + 64) = acc[ai][bj][m][1];
;                 const f32x4 a0 = *(const LAS f32x4*)(st + rd_off), a1 = *(const LAS f32x4*)(st + rd_off + 8 * 144);
;                 { const f32x4 xv = xb[g & 1][bj][0] + gv[bj] * a0; __builtin_nontemporal_store(xv, (f32x4*)((char*)xo + 4u * ERN_EOFF(g, bj, 0)));
;                   sq0 += (xv.x * xv.x + xv.y * xv.y) + (xv.z * xv.z + xv.w * xv.w);
;                   const f32x4 hv = xv * gsn[bj]; hw[bj][0].x = cvt_pk_bf16(hv.x, hv.y); hw[bj][0].y = cvt_pk_bf16(hv.z, hv.w); }
;                 { const f32x4 xv = xb[g & 1][bj][1] + gv[bj] * a1; __builtin_nontemporal_store(xv, (f32x4*)((char*)xo + 4u * ERN_EOFF(g, bj, 1)));
;                   sq1 += (xv.x * xv.x + xv.y * xv.y) + (xv.z * xv.z + xv.w * xv.w);
;                   const f32x4 hv = xv * gsn[bj]; hw[bj][1].x = cvt_pk_bf16(hv.x, hv.y); hw[bj][1].y = cvt_pk_bf16(hv.z, hv.w); }
;             }
;             if (!NOH && !PLAIN) {
; #pragma unroll
;                 for (int rh = 0; rh < 2; ++rh) { u32x2 rv; rv.x = __shfl_xor(hw[1][rh].x, 8); rv.y = __shfl_xor(hw[1][rh].y, 8);
;                     const unsigned e0 = ERN_EOFF(g, 0, rh);
;                     const unsigned ee = odd ? (e0 - DM + 32) : e0, eo2 = odd ? e0 : (e0 + DM + 32);
;                     *(u32x2*)((char*)ho + 2u * ee) = odd ? rv : hw[0][rh];
;                     *(u32x2*)((char*)ho + 2u * eo2) = odd ? hw[0][rh] : rv; }
;             }
;             if (!PLAIN) { sq0 += __shfl_xor(sq0, 1); sq0 += __shfl_xor(sq0, 2); sq0 += __shfl_xor(sq0, 4);
;             sq1 += __shfl_xor(sq1, 1); sq1 += __shfl_xor(sq1, 2); sq1 += __shfl_xor(sq1, 4); }
;             if (!PLAIN && pc == 0) { sst[g * 16 + rr] = sq0; sst[g * 16 + 8 + rr] = sq1; }
.LBB0_1293:
	s_or_b64 exec, exec, s[16:17]
	v_lshl_add_u64 v[112:113], s[48:49], 0, v[162:163]
	v_add_u32_e32 v162, 0x120000, v205
	v_add_u32_e32 v108, 0x120080, v205
	v_add_u32_e32 v110, 0x130000, v205
	v_add_u32_e32 v106, 0x130080, v205
	s_waitcnt lgkmcnt(0)
	v_add_u32_e32 v136, 0x140000, v205
	global_load_dwordx4 v[184:187], v136, s[48:49]
	v_add_u32_e32 v137, 0x150000, v205
	global_load_dwordx4 v[208:211], v137, s[48:49]
	v_add_u32_e32 v142, 0x140080, v205
	global_load_dwordx4 v[212:215], v142, s[48:49]
	v_add_u32_e32 v143, 0x150080, v205
	global_load_dwordx4 v[216:219], v143, s[48:49]
	ds_write_b128 v200, v[70:73]
	ds_write_b128 v200, v[66:69] offset:64
	ds_read_b128 v[66:69], v201
	ds_read_b128 v[70:73], v201 offset:1152
	v_mov_b32_e32 v123, v163
	s_waitcnt vmcnt(17) lgkmcnt(1)
	v_pk_fma_f32 v[68:69], v[56:57], v[68:69], v[104:105]
	v_add_u32_e32 v104, 0x40000, v202
	v_pk_fma_f32 v[66:67], v[54:55], v[66:67], v[102:103]
	v_lshlrev_b32_e32 v102, 2, v104
	s_waitcnt vmcnt(16) lgkmcnt(0)
	v_pk_fma_f32 v[72:73], v[56:57], v[72:73], v[100:101]
	v_add_u32_e32 v100, 0x44000, v202
	global_store_dwordx4 v102, v[66:69], s[48:49] nt
	v_pk_mul_f32 v[102:103], v[180:181], v[66:67]
	v_pk_fma_f32 v[70:71], v[54:55], v[70:71], v[98:99]
	v_lshlrev_b32_e32 v98, 2, v100
	v_pk_mul_f32 v[114:115], v[178:179], v[68:69]
	v_cvt_pk_bf16_f32 v102, v102, v103
	s_nop 0
	v_cvt_pk_bf16_f32 v103, v114, v115
	global_store_dwordx4 v98, v[70:73], s[48:49] nt
	v_pk_mul_f32 v[98:99], v[180:181], v[70:71]
	v_pk_mul_f32 v[114:115], v[178:179], v[72:73]
	v_cvt_pk_bf16_f32 v98, v98, v99
	s_nop 0
	v_cvt_pk_bf16_f32 v99, v114, v115
	ds_write_b128 v200, v[62:65]
	ds_write_b128 v200, v[58:61] offset:64
	ds_read_b128 v[58:61], v201
	ds_read_b128 v[62:65], v201 offset:1152
	v_lshl_add_u64 v[114:115], s[48:49], 0, v[122:123]
	s_waitcnt vmcnt(17) lgkmcnt(1)
	v_pk_fma_f32 v[58:59], v[50:51], v[58:59], v[94:95]
	v_pk_fma_f32 v[60:61], v[52:53], v[60:61], v[96:97]
	v_pk_mul_f32 v[96:97], v[176:177], v[58:59]
	global_store_dwordx4 v[112:113], v[58:61], off nt
	v_pk_mul_f32 v[94:95], v[174:175], v[60:61]
	v_cvt_pk_bf16_f32 v96, v96, v97
	s_waitcnt vmcnt(17) lgkmcnt(0)
	v_pk_fma_f32 v[62:63], v[50:51], v[62:63], v[90:91]
	v_cvt_pk_bf16_f32 v97, v94, v95
	ds_bpermute_b32 v90, v203, v96
	ds_bpermute_b32 v91, v203, v97
	v_pk_fma_f32 v[64:65], v[52:53], v[64:65], v[92:93]
	v_pk_mul_f32 v[92:93], v[176:177], v[62:63]
	v_pk_mul_f32 v[94:95], v[174:175], v[64:65]
	global_store_dwordx4 v[114:115], v[62:65], off nt
	v_cvt_pk_bf16_f32 v92, v92, v93
	v_cvt_pk_bf16_f32 v93, v94, v95
	v_lshlrev_b32_e32 v94, 1, v104
	s_waitcnt lgkmcnt(0)
	v_add_u32_e32 v250, 0xfffff040, v94
	v_cndmask_b32_e64 v250, v94, v250, s[40:41]
	v_cndmask_b32_e64 v248, v102, v90, s[40:41]
	v_cndmask_b32_e64 v249, v103, v91, s[40:41]
	global_store_dwordx2 v250, v[248:249], s[46:47]
	v_cndmask_b32_e64 v246, v90, v102, s[40:41]
	v_cndmask_b32_e64 v247, v91, v103, s[40:41]
	s_waitcnt lgkmcnt(1)
	v_add_u32_e32 v90, 0x1040, v94
	v_cndmask_b32_e64 v90, v94, v90, s[38:39]
	global_store_dwordx2 v90, v[246:247], s[46:47]
	ds_bpermute_b32 v90, v203, v92
	s_waitcnt lgkmcnt(1)
	ds_bpermute_b32 v91, v203, v93
	v_lshlrev_b32_e32 v92, 1, v100
	s_waitcnt lgkmcnt(0)
	v_add_u32_e32 v250, 0xfffff040, v92
	v_cndmask_b32_e64 v250, v92, v250, s[40:41]
	v_cndmask_b32_e64 v248, v98, v90, s[40:41]
	v_cndmask_b32_e64 v249, v99, v91, s[40:41]
	global_store_dwordx2 v250, v[248:249], s[46:47]
	v_cndmask_b32_e64 v246, v90, v98, s[40:41]
	v_cndmask_b32_e64 v247, v91, v99, s[40:41]
	v_mul_f32_e32 v59, v59, v59
	v_fmac_f32_e32 v59, v58, v58
	v_mul_f32_e32 v58, v61, v61
	v_mul_f32_e32 v69, v69, v69
	v_fmac_f32_e32 v58, v60, v60
	v_mul_f32_e32 v67, v67, v67
	v_fmac_f32_e32 v69, v68, v68
	v_mul_f32_e32 v68, v71, v71
	v_mul_f32_e32 v71, v73, v73
	v_add_f32_e32 v58, v59, v58
	v_mul_f32_e32 v59, v63, v63
	v_mul_f32_e32 v60, v65, v65
	v_fmac_f32_e32 v71, v72, v72
	v_fmac_f32_e32 v59, v62, v62
	v_fmac_f32_e32 v60, v64, v64
	v_fmac_f32_e32 v67, v66, v66
	v_fmac_f32_e32 v68, v70, v70
	v_add_f32_e32 v59, v59, v60
	v_add_f32_e32 v60, v67, v69
	v_add_f32_e32 v61, v68, v71
	v_add_f32_e32 v58, v60, v58
	v_add_f32_e32 v59, v61, v59
	ds_bpermute_b32 v60, v190, v58
	ds_bpermute_b32 v61, v190, v59
	s_waitcnt lgkmcnt(1)
	v_add_f32_e32 v58, v58, v60
	s_waitcnt lgkmcnt(0)
	v_add_f32_e32 v61, v59, v61
	ds_bpermute_b32 v60, v191, v58
	ds_bpermute_b32 v62, v191, v61
	s_waitcnt lgkmcnt(1)
	v_add_f32_e32 v58, v58, v60
	s_waitcnt lgkmcnt(0)
	v_add_f32_e32 v60, v61, v62
	ds_bpermute_b32 v59, v204, v58
	ds_bpermute_b32 v61, v204, v60
	v_add_u32_e32 v62, 0x1040, v92
	v_cndmask_b32_e64 v62, v92, v62, s[38:39]
	global_store_dwordx2 v62, v[246:247], s[46:47]
	s_and_saveexec_b64 s[16:17], s[42:43]
	s_cbranch_execz .LBB0_1303
	s_waitcnt lgkmcnt(1)
	v_add_f32_e32 v58, v58, v59
	s_waitcnt lgkmcnt(0)
	v_add_f32_e32 v59, v60, v61
	ds_write2_b32 v194, v58, v59 offset0:64 offset1:72
; #define LAS __attribute__((address_space(3)))
; #define ERN_EOFF(q, m) (eb + (unsigned)((((q) & 1) * HALF + (m) * 16) * DM + ERN_COL((q) >> 1)))
;     __device__ __forceinline__ void operator()(const f32x4 (&acc)[2][2][4][2], const Unit& u, int wr, int wc, int fr, int fq) const {
;     ...
;         ERN_LOADX(0);
; #pragma unroll
;         for (int g = 0; g < 8; ++g) { const int ai = g >> 2, m = g & 3;
;             if (g + 1 < 8) ERN_LOADX(g + 1);
;             float sq0 = 0.f, sq1 = 0.f; u32x2 hw[2][2];
; #pragma unroll
;             for (int bj = 0; bj < 2; ++bj) {
;                 *(LAS f32x4*)(st + wr_off) = acc[ai][bj][m][0]; *(LAS f32x4*)(st + wr_off + 64) = acc[ai][bj][m][1];
;                 const f32x4 a0 = *(const LAS f32x4*)(st + rd_off), a1 = *(const LAS f32x4*)(st + rd_off + 8 * 144);
;                 { const f32x4 xv = xb[g & 1][bj][0] + gv[bj] * a0; __builtin_nontemporal_store(xv, (f32x4*)((char*)xo + 4u * ERN_EOFF(g, bj, 0)));
;                   sq0 += (xv.x * xv.x + xv.y * xv.y) + (xv.z * xv.z + xv.w * xv.w);
;                   const f32x4 hv = xv * gsn[bj]; hw[bj][0].x = cvt_pk_bf16(hv.x, hv.y); hw[bj][0].y = cvt_pk_bf16(hv.z, hv.w); }
;                 { const f32x4 xv = xb[g & 1][bj][1] + gv[bj] * a1; __builtin_nontemporal_store(xv, (f32x4*)((char*)xo + 4u * ERN_EOFF(g, bj, 1)));
;                   sq1 += (xv.x * xv.x + xv.y * xv.y) + (xv.z * xv.z + xv.w * xv.w);
;                   const f32x4 hv = xv * gsn[bj]; hw[bj][1].x = cvt_pk_bf16(hv.x, hv.y); hw[bj][1].y = cvt_pk_bf16(hv.z, hv.w); }
;             }
;             if (!NOH && !PLAIN) {
; #pragma unroll
;                 for (int rh = 0; rh < 2; ++rh) { u32x2 rv; rv.x = __shfl_xor(hw[1][rh].x, 8); rv.y = __shfl_xor(hw[1][rh].y, 8);
;                     const unsigned e0 = ERN_EOFF(g, 0, rh);
;                     const unsigned ee = odd ? (e0 - DM + 32) : e0, eo2 = odd ? e0 : (e0 + DM + 32);
;                     *(u32x2*)((char*)ho + 2u * ee) = odd ? rv : hw[0][rh];
;                     *(u32x2*)((char*)ho + 2u * eo2) = odd ? hw[0][rh] : rv; }
;             }
;             if (!PLAIN) { sq0 += __shfl_xor(sq0, 1); sq0 += __shfl_xor(sq0, 2); sq0 += __shfl_xor(sq0, 4);
;             sq1 += __shfl_xor(sq1, 1); sq1 += __shfl_xor(sq1, 2); sq1 += __shfl_xor(sq1, 4); }
;             if (!PLAIN && pc == 0) { sst[g * 16 + rr] = sq0; sst[g * 16 + 8 + rr] = sq1; }
.LBB0_1303:
	s_or_b64 exec, exec, s[16:17]
	v_lshl_add_u64 v[96:97], s[48:49], 0, v[162:163]
	v_add_u32_e32 v162, 0x140000, v205
	v_add_u32_e32 v92, 0x140080, v205
	v_add_u32_e32 v94, 0x150000, v205
	v_add_u32_e32 v90, 0x150080, v205
	s_waitcnt lgkmcnt(0)
	ds_write_b128 v200, v[46:49]
	ds_write_b128 v200, v[42:45] offset:64
	ds_read_b128 v[42:45], v201
	ds_read_b128 v[46:49], v201 offset:1152
	v_mov_b32_e32 v111, v163
	v_lshl_add_u64 v[98:99], s[48:49], 0, v[110:111]
	v_mov_b32_e32 v109, v163
	s_waitcnt vmcnt(18) lgkmcnt(1)
	v_mov_b64_e32 v[86:87], v[128:129]
	v_mov_b64_e32 v[88:89], v[130:131]
	v_mov_b64_e32 v[82:83], v[132:133]
	v_mov_b64_e32 v[84:85], v[134:135]
	v_mov_b64_e32 v[78:79], v[144:145]
	v_mov_b64_e32 v[80:81], v[146:147]
	v_mov_b64_e32 v[74:75], v[148:149]
	v_mov_b64_e32 v[76:77], v[150:151]
	v_add_u32_e32 v136, 0x160000, v205
	global_load_dwordx4 v[128:131], v136, s[48:49]
	v_add_u32_e32 v137, 0x170000, v205
	global_load_dwordx4 v[132:135], v137, s[48:49]
	v_add_u32_e32 v142, 0x160080, v205
	global_load_dwordx4 v[144:147], v142, s[48:49]
	v_add_u32_e32 v143, 0x170080, v205
	global_load_dwordx4 v[148:151], v143, s[48:49]
	v_pk_fma_f32 v[42:43], v[54:55], v[42:43], v[86:87]
	s_waitcnt lgkmcnt(0)
	v_pk_fma_f32 v[46:47], v[54:55], v[46:47], v[82:83]
	v_pk_fma_f32 v[44:45], v[56:57], v[44:45], v[88:89]
	v_pk_mul_f32 v[86:87], v[180:181], v[42:43]
	v_pk_fma_f32 v[48:49], v[56:57], v[48:49], v[84:85]
	v_pk_mul_f32 v[82:83], v[180:181], v[46:47]
	global_store_dwordx4 v[96:97], v[42:45], off nt
	v_pk_mul_f32 v[88:89], v[178:179], v[44:45]
	v_cvt_pk_bf16_f32 v86, v86, v87
	v_pk_mul_f32 v[84:85], v[178:179], v[48:49]
	v_cvt_pk_bf16_f32 v87, v88, v89
	global_store_dwordx4 v[98:99], v[46:49], off nt
	v_cvt_pk_bf16_f32 v82, v82, v83
	v_cvt_pk_bf16_f32 v83, v84, v85
	ds_write_b128 v200, v[38:41]
	ds_write_b128 v200, v[34:37] offset:64
	ds_read_b128 v[34:37], v201
	ds_read_b128 v[38:41], v201 offset:1152
	v_lshl_add_u64 v[84:85], s[48:49], 0, v[108:109]
	v_mov_b32_e32 v107, v163
	v_lshl_add_u64 v[88:89], s[48:49], 0, v[106:107]
	s_waitcnt lgkmcnt(1)
	v_pk_fma_f32 v[34:35], v[50:51], v[34:35], v[78:79]
	v_pk_fma_f32 v[36:37], v[52:53], v[36:37], v[80:81]
	v_pk_mul_f32 v[80:81], v[176:177], v[34:35]
	global_store_dwordx4 v[84:85], v[34:37], off nt
	v_pk_mul_f32 v[78:79], v[174:175], v[36:37]
	v_cvt_pk_bf16_f32 v80, v80, v81
	s_waitcnt lgkmcnt(0)
	v_pk_fma_f32 v[38:39], v[50:51], v[38:39], v[74:75]
	v_cvt_pk_bf16_f32 v81, v78, v79
	ds_bpermute_b32 v74, v203, v80
	ds_bpermute_b32 v75, v203, v81
	v_pk_fma_f32 v[40:41], v[52:53], v[40:41], v[76:77]
	v_pk_mul_f32 v[76:77], v[176:177], v[38:39]
	v_pk_mul_f32 v[78:79], v[174:175], v[40:41]
	global_store_dwordx4 v[88:89], v[38:41], off nt
	v_cvt_pk_bf16_f32 v76, v76, v77
	v_cvt_pk_bf16_f32 v77, v78, v79
	v_add_u32_e32 v79, 0x48000, v202
	v_lshlrev_b32_e32 v78, 1, v79
	s_waitcnt lgkmcnt(0)
	v_add_u32_e32 v250, 0xfffff040, v78
	v_cndmask_b32_e64 v250, v78, v250, s[40:41]
	v_cndmask_b32_e64 v248, v86, v74, s[40:41]
	v_cndmask_b32_e64 v249, v87, v75, s[40:41]
	global_store_dwordx2 v250, v[248:249], s[46:47]
	v_cndmask_b32_e64 v246, v74, v86, s[40:41]
	v_cndmask_b32_e64 v247, v75, v87, s[40:41]
	s_waitcnt lgkmcnt(1)
	v_add_u32_e32 v74, 0x1040, v78
	v_cndmask_b32_e64 v74, v78, v74, s[38:39]
	global_store_dwordx2 v74, v[246:247], s[46:47]
	ds_bpermute_b32 v74, v203, v76
	s_waitcnt lgkmcnt(1)
	ds_bpermute_b32 v75, v203, v77
	v_add_u32_e32 v77, 0x4c000, v202
	v_lshlrev_b32_e32 v76, 1, v77
	s_waitcnt lgkmcnt(0)
	v_add_u32_e32 v250, 0xfffff040, v76
	v_cndmask_b32_e64 v250, v76, v250, s[40:41]
	v_cndmask_b32_e64 v248, v82, v74, s[40:41]
	v_cndmask_b32_e64 v249, v83, v75, s[40:41]
	global_store_dwordx2 v250, v[248:249], s[46:47]
	v_cndmask_b32_e64 v246, v74, v82, s[40:41]
	v_cndmask_b32_e64 v247, v75, v83, s[40:41]
	v_mul_f32_e32 v35, v35, v35
	v_fmac_f32_e32 v35, v34, v34
	v_mul_f32_e32 v34, v37, v37
	v_mul_f32_e32 v45, v45, v45
	v_fmac_f32_e32 v34, v36, v36
	v_mul_f32_e32 v43, v43, v43
	v_fmac_f32_e32 v45, v44, v44
	v_mul_f32_e32 v44, v47, v47
	v_mul_f32_e32 v47, v49, v49
	v_add_f32_e32 v34, v35, v34
	v_mul_f32_e32 v35, v39, v39
	v_mul_f32_e32 v36, v41, v41
	v_fmac_f32_e32 v47, v48, v48
	v_fmac_f32_e32 v35, v38, v38
	v_fmac_f32_e32 v36, v40, v40
	v_fmac_f32_e32 v43, v42, v42
	v_fmac_f32_e32 v44, v46, v46
	v_add_f32_e32 v35, v35, v36
	v_add_f32_e32 v36, v43, v45
	v_add_f32_e32 v37, v44, v47
	v_add_f32_e32 v34, v36, v34
	v_add_f32_e32 v35, v37, v35
	ds_bpermute_b32 v36, v190, v34
	ds_bpermute_b32 v37, v190, v35
	s_waitcnt lgkmcnt(1)
	v_add_f32_e32 v34, v34, v36
	s_waitcnt lgkmcnt(0)
	v_add_f32_e32 v37, v35, v37
	ds_bpermute_b32 v36, v191, v34
	ds_bpermute_b32 v38, v191, v37
	s_waitcnt lgkmcnt(1)
	v_add_f32_e32 v34, v34, v36
	s_waitcnt lgkmcnt(0)
	v_add_f32_e32 v36, v37, v38
	ds_bpermute_b32 v35, v204, v34
	ds_bpermute_b32 v37, v204, v36
	v_add_u32_e32 v38, 0x1040, v76
	v_cndmask_b32_e64 v38, v76, v38, s[38:39]
	global_store_dwordx2 v38, v[246:247], s[46:47]
	s_and_saveexec_b64 s[16:17], s[42:43]
	s_cbranch_execz .LBB0_1313
	s_waitcnt lgkmcnt(1)
	v_add_f32_e32 v34, v34, v35
	s_waitcnt lgkmcnt(0)
	v_add_f32_e32 v35, v36, v37
	ds_write2_b32 v194, v34, v35 offset0:80 offset1:88
; #define LAS __attribute__((address_space(3)))
; #define ERN_EOFF(q, m) (eb + (unsigned)((((q) & 1) * HALF + (m) * 16) * DM + ERN_COL((q) >> 1)))
;     __device__ __forceinline__ void operator()(const f32x4 (&acc)[2][2][4][2], const Unit& u, int wr, int wc, int fr, int fq) const {
;     ...
;         ERN_LOADX(0);
; #pragma unroll
;         for (int g = 0; g < 8; ++g) { const int ai = g >> 2, m = g & 3;
;             if (g + 1 < 8) ERN_LOADX(g + 1);
;             float sq0 = 0.f, sq1 = 0.f; u32x2 hw[2][2];
; #pragma unroll
;             for (int bj = 0; bj < 2; ++bj) {
;                 *(LAS f32x4*)(st + wr_off) = acc[ai][bj][m][0]; *(LAS f32x4*)(st + wr_off + 64) = acc[ai][bj][m][1];
;                 const f32x4 a0 = *(const LAS f32x4*)(st + rd_off), a1 = *(const LAS f32x4*)(st + rd_off + 8 * 144);
;                 { const f32x4 xv = xb[g & 1][bj][0] + gv[bj] * a0; __builtin_nontemporal_store(xv, (f32x4*)((char*)xo + 4u * ERN_EOFF(g, bj, 0)));
;                   sq0 += (xv.x * xv.x + xv.y * xv.y) + (xv.z * xv.z + xv.w * xv.w);
;                   const f32x4 hv = xv * gsn[bj]; hw[bj][0].x = cvt_pk_bf16(hv.x, hv.y); hw[bj][0].y = cvt_pk_bf16(hv.z, hv.w); }
;                 { const f32x4 xv = xb[g & 1][bj][1] + gv[bj] * a1; __builtin_nontemporal_store(xv, (f32x4*)((char*)xo + 4u * ERN_EOFF(g, bj, 1)));
;                   sq1 += (xv.x * xv.x + xv.y * xv.y) + (xv.z * xv.z + xv.w * xv.w);
;                   const f32x4 hv = xv * gsn[bj]; hw[bj][1].x = cvt_pk_bf16(hv.x, hv.y); hw[bj][1].y = cvt_pk_bf16(hv.z, hv.w); }
;             }
;             if (!NOH && !PLAIN) {
; #pragma unroll
;                 for (int rh = 0; rh < 2; ++rh) { u32x2 rv; rv.x = __shfl_xor(hw[1][rh].x, 8); rv.y = __shfl_xor(hw[1][rh].y, 8);
;                     const unsigned e0 = ERN_EOFF(g, 0, rh);
;                     const unsigned ee = odd ? (e0 - DM + 32) : e0, eo2 = odd ? e0 : (e0 + DM + 32);
;                     *(u32x2*)((char*)ho + 2u * ee) = odd ? rv : hw[0][rh];
;                     *(u32x2*)((char*)ho + 2u * eo2) = odd ? hw[0][rh] : rv; }
;             }
;             if (!PLAIN) { sq0 += __shfl_xor(sq0, 1); sq0 += __shfl_xor(sq0, 2); sq0 += __shfl_xor(sq0, 4);
;             sq1 += __shfl_xor(sq1, 1); sq1 += __shfl_xor(sq1, 2); sq1 += __shfl_xor(sq1, 4); }
;             if (!PLAIN && pc == 0) { sst[g * 16 + rr] = sq0; sst[g * 16 + 8 + rr] = sq1; }
.LBB0_1313:
	s_or_b64 exec, exec, s[16:17]
	v_lshl_add_u64 v[80:81], s[48:49], 0, v[162:163]
	v_add_u32_e32 v162, 0x160000, v205
	v_add_u32_e32 v76, 0x160080, v205
	v_add_u32_e32 v78, 0x170000, v205
	v_add_u32_e32 v74, 0x170080, v205
	s_waitcnt lgkmcnt(0)
	ds_write_b128 v200, v[30:33]
	ds_write_b128 v200, v[26:29] offset:64
	ds_read_b128 v[26:29], v201
	ds_read_b128 v[30:33], v201 offset:1152
	v_mov_b32_e32 v95, v163
	v_lshl_add_u64 v[82:83], s[48:49], 0, v[94:95]
	v_mov_b32_e32 v93, v163
	s_waitcnt vmcnt(18) lgkmcnt(1)
	v_mov_b64_e32 v[70:71], v[184:185]
	v_mov_b64_e32 v[72:73], v[186:187]
	v_mov_b64_e32 v[66:67], v[208:209]
	v_mov_b64_e32 v[68:69], v[210:211]
	v_mov_b64_e32 v[62:63], v[212:213]
	v_mov_b64_e32 v[64:65], v[214:215]
	v_mov_b64_e32 v[58:59], v[216:217]
	v_mov_b64_e32 v[60:61], v[218:219]
	v_pk_fma_f32 v[26:27], v[54:55], v[26:27], v[70:71]
	s_waitcnt lgkmcnt(0)
	v_pk_fma_f32 v[30:31], v[54:55], v[30:31], v[66:67]
	v_pk_fma_f32 v[28:29], v[56:57], v[28:29], v[72:73]
	v_pk_mul_f32 v[70:71], v[180:181], v[26:27]
	v_pk_fma_f32 v[32:33], v[56:57], v[32:33], v[68:69]
	v_pk_mul_f32 v[66:67], v[180:181], v[30:31]
	global_store_dwordx4 v[80:81], v[26:29], off nt
	v_pk_mul_f32 v[72:73], v[178:179], v[28:29]
	v_cvt_pk_bf16_f32 v70, v70, v71
	v_pk_mul_f32 v[68:69], v[178:179], v[32:33]
	v_cvt_pk_bf16_f32 v71, v72, v73
	global_store_dwordx4 v[82:83], v[30:33], off nt
	v_cvt_pk_bf16_f32 v66, v66, v67
	v_cvt_pk_bf16_f32 v67, v68, v69
	ds_write_b128 v200, v[22:25]
	ds_write_b128 v200, v[18:21] offset:64
	ds_read_b128 v[18:21], v201
	ds_read_b128 v[22:25], v201 offset:1152
	v_lshl_add_u64 v[68:69], s[48:49], 0, v[92:93]
	v_mov_b32_e32 v91, v163
	v_lshl_add_u64 v[72:73], s[48:49], 0, v[90:91]
	s_waitcnt lgkmcnt(1)
	v_pk_fma_f32 v[18:19], v[50:51], v[18:19], v[62:63]
	v_pk_fma_f32 v[20:21], v[52:53], v[20:21], v[64:65]
	v_pk_mul_f32 v[64:65], v[176:177], v[18:19]
	global_store_dwordx4 v[68:69], v[18:21], off nt
	v_pk_mul_f32 v[62:63], v[174:175], v[20:21]
	v_cvt_pk_bf16_f32 v64, v64, v65
	s_waitcnt lgkmcnt(0)
	v_pk_fma_f32 v[22:23], v[50:51], v[22:23], v[58:59]
	v_cvt_pk_bf16_f32 v65, v62, v63
	ds_bpermute_b32 v58, v203, v64
	ds_bpermute_b32 v59, v203, v65
	v_pk_fma_f32 v[24:25], v[52:53], v[24:25], v[60:61]
	v_pk_mul_f32 v[60:61], v[176:177], v[22:23]
	v_pk_mul_f32 v[62:63], v[174:175], v[24:25]
	global_store_dwordx4 v[72:73], v[22:25], off nt
	v_cvt_pk_bf16_f32 v60, v60, v61
	v_cvt_pk_bf16_f32 v61, v62, v63
	v_add_u32_e32 v63, 0x50000, v202
	v_lshlrev_b32_e32 v62, 1, v63
	s_waitcnt lgkmcnt(0)
	v_add_u32_e32 v250, 0xfffff040, v62
	v_cndmask_b32_e64 v250, v62, v250, s[40:41]
	v_cndmask_b32_e64 v248, v70, v58, s[40:41]
	v_cndmask_b32_e64 v249, v71, v59, s[40:41]
	global_store_dwordx2 v250, v[248:249], s[46:47]
	v_cndmask_b32_e64 v246, v58, v70, s[40:41]
	v_cndmask_b32_e64 v247, v59, v71, s[40:41]
	s_waitcnt lgkmcnt(1)
	v_add_u32_e32 v58, 0x1040, v62
	v_cndmask_b32_e64 v58, v62, v58, s[38:39]
	global_store_dwordx2 v58, v[246:247], s[46:47]
	ds_bpermute_b32 v58, v203, v60
	s_waitcnt lgkmcnt(1)
	ds_bpermute_b32 v59, v203, v61
	v_add_u32_e32 v61, 0x54000, v202
	v_lshlrev_b32_e32 v60, 1, v61
	s_waitcnt lgkmcnt(0)
	v_add_u32_e32 v250, 0xfffff040, v60
	v_cndmask_b32_e64 v250, v60, v250, s[40:41]
	v_cndmask_b32_e64 v248, v66, v58, s[40:41]
	v_cndmask_b32_e64 v249, v67, v59, s[40:41]
	global_store_dwordx2 v250, v[248:249], s[46:47]
	v_cndmask_b32_e64 v246, v58, v66, s[40:41]
	v_cndmask_b32_e64 v247, v59, v67, s[40:41]
	v_mul_f32_e32 v19, v19, v19
	v_fmac_f32_e32 v19, v18, v18
	v_mul_f32_e32 v18, v21, v21
	v_mul_f32_e32 v29, v29, v29
	v_fmac_f32_e32 v18, v20, v20
	v_mul_f32_e32 v27, v27, v27
	v_fmac_f32_e32 v29, v28, v28
	v_mul_f32_e32 v28, v31, v31
	v_mul_f32_e32 v31, v33, v33
	v_add_f32_e32 v18, v19, v18
	v_mul_f32_e32 v19, v23, v23
	v_mul_f32_e32 v20, v25, v25
	v_fmac_f32_e32 v31, v32, v32
	v_fmac_f32_e32 v19, v22, v22
	v_fmac_f32_e32 v20, v24, v24
	v_fmac_f32_e32 v27, v26, v26
	v_fmac_f32_e32 v28, v30, v30
	v_add_f32_e32 v19, v19, v20
	v_add_f32_e32 v20, v27, v29
	v_add_f32_e32 v21, v28, v31
	v_add_f32_e32 v18, v20, v18
	v_add_f32_e32 v19, v21, v19
	ds_bpermute_b32 v20, v190, v18
	ds_bpermute_b32 v21, v190, v19
	s_waitcnt lgkmcnt(1)
	v_add_f32_e32 v18, v18, v20
	s_waitcnt lgkmcnt(0)
	v_add_f32_e32 v21, v19, v21
	ds_bpermute_b32 v20, v191, v18
	ds_bpermute_b32 v22, v191, v21
	s_waitcnt lgkmcnt(1)
	v_add_f32_e32 v18, v18, v20
	s_waitcnt lgkmcnt(0)
	v_add_f32_e32 v20, v21, v22
	ds_bpermute_b32 v19, v204, v18
	ds_bpermute_b32 v21, v204, v20
	v_add_u32_e32 v22, 0x1040, v60
	v_cndmask_b32_e64 v22, v60, v22, s[38:39]
	global_store_dwordx2 v22, v[246:247], s[46:47]
	s_and_saveexec_b64 s[16:17], s[42:43]
	s_cbranch_execz .LBB0_1323
	s_waitcnt lgkmcnt(1)
	v_add_f32_e32 v18, v18, v19
	s_waitcnt lgkmcnt(0)
	v_add_f32_e32 v19, v20, v21
	ds_write2_b32 v194, v18, v19 offset0:96 offset1:104
; #define LAS __attribute__((address_space(3)))
; #define ERN_EOFF(q, m) (eb + (unsigned)((((q) & 1) * HALF + (m) * 16) * DM + ERN_COL((q) >> 1)))
;     __device__ __forceinline__ void operator()(const f32x4 (&acc)[2][2][4][2], const Unit& u, int wr, int wc, int fr, int fq) const {
;     ...
;         for (int g = 0; g < 8; ++g) { const int ai = g >> 2, m = g & 3;
;             if (g + 1 < 8) ERN_LOADX(g + 1);
;             float sq0 = 0.f, sq1 = 0.f; u32x2 hw[2][2];
; #pragma unroll
;             for (int bj = 0; bj < 2; ++bj) {
;                 *(LAS f32x4*)(st + wr_off) = acc[ai][bj][m][0]; *(LAS f32x4*)(st + wr_off + 64) = acc[ai][bj][m][1];
;                 const f32x4 a0 = *(const LAS f32x4*)(st + rd_off), a1 = *(const LAS f32x4*)(st + rd_off + 8 * 144);
;                 { const f32x4 xv = xb[g & 1][bj][0] + gv[bj] * a0; __builtin_nontemporal_store(xv, (f32x4*)((char*)xo + 4u * ERN_EOFF(g, bj, 0)));
;                   sq0 += (xv.x * xv.x + xv.y * xv.y) + (xv.z * xv.z + xv.w * xv.w);
;                   const f32x4 hv = xv * gsn[bj]; hw[bj][0].x = cvt_pk_bf16(hv.x, hv.y); hw[bj][0].y = cvt_pk_bf16(hv.z, hv.w); }
;                 { const f32x4 xv = xb[g & 1][bj][1] + gv[bj] * a1; __builtin_nontemporal_store(xv, (f32x4*)((char*)xo + 4u * ERN_EOFF(g, bj, 1)));
;                   sq1 += (xv.x * xv.x + xv.y * xv.y) + (xv.z * xv.z + xv.w * xv.w);
;                   const f32x4 hv = xv * gsn[bj]; hw[bj][1].x = cvt_pk_bf16(hv.x, hv.y); hw[bj][1].y = cvt_pk_bf16(hv.z, hv.w); }
;             }
;             if (!NOH && !PLAIN) {
; #pragma unroll
;                 for (int rh = 0; rh < 2; ++rh) { u32x2 rv; rv.x = __shfl_xor(hw[1][rh].x, 8); rv.y = __shfl_xor(hw[1][rh].y, 8);
;                     const unsigned e0 = ERN_EOFF(g, 0, rh);
;                     const unsigned ee = odd ? (e0 - DM + 32) : e0, eo2 = odd ? e0 : (e0 + DM + 32);
;                     *(u32x2*)((char*)ho + 2u * ee) = odd ? rv : hw[0][rh];
;                     *(u32x2*)((char*)ho + 2u * eo2) = odd ? hw[0][rh] : rv; }
;             }
;             if (!PLAIN) { sq0 += __shfl_xor(sq0, 1); sq0 += __shfl_xor(sq0, 2); sq0 += __shfl_xor(sq0, 4);
;             sq1 += __shfl_xor(sq1, 1); sq1 += __shfl_xor(sq1, 2); sq1 += __shfl_xor(sq1, 4); }
;             if (!PLAIN && pc == 0) { sst[g * 16 + rr] = sq0; sst[g * 16 + 8 + rr] = sq1; }
.LBB0_1323:
	s_or_b64 exec, exec, s[16:17]
	ds_write_b128 v200, v[14:17]
	ds_write_b128 v200, v[10:13] offset:64
	ds_read_b128 v[10:13], v201
	ds_read_b128 v[14:17], v201 offset:1152
	s_waitcnt lgkmcnt(5)
	v_lshl_add_u64 v[18:19], s[48:49], 0, v[162:163]
	v_mov_b32_e32 v79, v163
	v_lshl_add_u64 v[22:23], s[48:49], 0, v[78:79]
	s_waitcnt vmcnt(14) lgkmcnt(1)
	v_mov_b64_e32 v[46:47], v[128:129]
	v_mov_b64_e32 v[48:49], v[130:131]
	v_mov_b64_e32 v[42:43], v[132:133]
	v_mov_b64_e32 v[44:45], v[134:135]
	v_mov_b64_e32 v[38:39], v[144:145]
	v_mov_b64_e32 v[40:41], v[146:147]
	v_mov_b64_e32 v[34:35], v[148:149]
	v_mov_b64_e32 v[36:37], v[150:151]
	v_pk_fma_f32 v[12:13], v[56:57], v[12:13], v[48:49]
	v_pk_fma_f32 v[10:11], v[54:55], v[10:11], v[46:47]
	global_store_dwordx4 v[18:19], v[10:13], off nt
	v_pk_mul_f32 v[18:19], v[178:179], v[12:13]
	v_pk_mul_f32 v[20:21], v[180:181], v[10:11]
	s_waitcnt lgkmcnt(0)
	v_pk_fma_f32 v[14:15], v[54:55], v[14:15], v[42:43]
	v_cvt_pk_bf16_f32 v20, v20, v21
	v_cvt_pk_bf16_f32 v21, v18, v19
	v_pk_fma_f32 v[16:17], v[56:57], v[16:17], v[44:45]
	v_pk_mul_f32 v[18:19], v[180:181], v[14:15]
	global_store_dwordx4 v[22:23], v[14:17], off nt
	v_pk_mul_f32 v[22:23], v[178:179], v[16:17]
	v_cvt_pk_bf16_f32 v18, v18, v19
	v_mov_b32_e32 v77, v163
	v_cvt_pk_bf16_f32 v19, v22, v23
	ds_write_b128 v200, v[6:9]
	ds_write_b128 v200, v[2:5] offset:64
	ds_read_b128 v[2:5], v201
	ds_read_b128 v[6:9], v201 offset:1152
	v_lshl_add_u64 v[22:23], s[48:49], 0, v[76:77]
	v_mov_b32_e32 v75, v163
	v_lshl_add_u64 v[24:25], s[48:49], 0, v[74:75]
	s_waitcnt lgkmcnt(1)
	v_pk_fma_f32 v[4:5], v[52:53], v[4:5], v[40:41]
	v_pk_fma_f32 v[2:3], v[50:51], v[2:3], v[38:39]
	global_store_dwordx4 v[22:23], v[2:5], off nt
	v_pk_mul_f32 v[22:23], v[174:175], v[4:5]
	v_pk_mul_f32 v[26:27], v[176:177], v[2:3]
	s_waitcnt lgkmcnt(0)
	v_pk_fma_f32 v[8:9], v[52:53], v[8:9], v[36:37]
	v_cvt_pk_bf16_f32 v28, v26, v27
	v_cvt_pk_bf16_f32 v23, v22, v23
	ds_bpermute_b32 v22, v203, v28
	ds_bpermute_b32 v23, v203, v23
	v_pk_fma_f32 v[6:7], v[50:51], v[6:7], v[34:35]
	global_store_dwordx4 v[24:25], v[6:9], off nt
	v_pk_mul_f32 v[26:27], v[174:175], v[8:9]
	v_pk_mul_f32 v[24:25], v[176:177], v[6:7]
	s_nop 0
	v_cvt_pk_bf16_f32 v24, v24, v25
	v_cvt_pk_bf16_f32 v25, v26, v27
	v_add_u32_e32 v27, 0x58000, v202
	v_lshlrev_b32_e32 v26, 1, v27
	s_waitcnt lgkmcnt(0)
	v_add_u32_e32 v250, 0xfffff040, v26
	v_cndmask_b32_e64 v250, v26, v250, s[40:41]
	v_cndmask_b32_e64 v248, v20, v22, s[40:41]
	v_cndmask_b32_e64 v249, v21, v23, s[40:41]
	global_store_dwordx2 v250, v[248:249], s[46:47]
	v_cndmask_b32_e64 v246, v22, v20, s[40:41]
	v_cndmask_b32_e64 v247, v23, v21, s[40:41]
	s_waitcnt lgkmcnt(1)
	v_add_u32_e32 v22, 0x1040, v26
	v_cndmask_b32_e64 v22, v26, v22, s[38:39]
	global_store_dwordx2 v22, v[246:247], s[46:47]
	ds_bpermute_b32 v20, v203, v24
	ds_bpermute_b32 v21, v203, v25
	s_waitcnt lgkmcnt(2)
	v_add_u32_e32 v23, 0x5c000, v202
	v_lshlrev_b32_e32 v22, 1, v23
	s_waitcnt lgkmcnt(0)
	v_add_u32_e32 v250, 0xfffff040, v22
	v_cndmask_b32_e64 v250, v22, v250, s[40:41]
	v_cndmask_b32_e64 v248, v18, v20, s[40:41]
	v_cndmask_b32_e64 v249, v19, v21, s[40:41]
	global_store_dwordx2 v250, v[248:249], s[46:47]
	v_cndmask_b32_e64 v246, v20, v18, s[40:41]
	v_cndmask_b32_e64 v247, v21, v19, s[40:41]
	v_mul_f32_e32 v3, v3, v3
	v_fmac_f32_e32 v3, v2, v2
	v_mul_f32_e32 v2, v5, v5
	v_mul_f32_e32 v13, v13, v13
	v_fmac_f32_e32 v2, v4, v4
	v_mul_f32_e32 v11, v11, v11
	v_fmac_f32_e32 v13, v12, v12
	v_mul_f32_e32 v12, v15, v15
	v_mul_f32_e32 v15, v17, v17
	v_add_f32_e32 v2, v3, v2
	v_mul_f32_e32 v3, v7, v7
	v_mul_f32_e32 v4, v9, v9
	v_fmac_f32_e32 v15, v16, v16
	v_fmac_f32_e32 v3, v6, v6
	v_fmac_f32_e32 v4, v8, v8
	v_fmac_f32_e32 v11, v10, v10
	v_fmac_f32_e32 v12, v14, v14
	v_add_f32_e32 v3, v3, v4
	v_add_f32_e32 v4, v11, v13
	v_add_f32_e32 v5, v12, v15
	v_add_f32_e32 v2, v4, v2
	v_add_f32_e32 v3, v5, v3
	ds_bpermute_b32 v4, v190, v2
	ds_bpermute_b32 v5, v190, v3
	s_waitcnt lgkmcnt(1)
	v_add_f32_e32 v2, v2, v4
	s_waitcnt lgkmcnt(0)
	v_add_f32_e32 v5, v3, v5
	ds_bpermute_b32 v4, v191, v2
	ds_bpermute_b32 v6, v191, v5
	s_waitcnt lgkmcnt(1)
	v_add_f32_e32 v2, v2, v4
	s_waitcnt lgkmcnt(0)
	v_add_f32_e32 v4, v5, v6
	ds_bpermute_b32 v3, v204, v2
	ds_bpermute_b32 v5, v204, v4
	v_add_u32_e32 v6, 0x1040, v22
	v_cndmask_b32_e64 v6, v22, v6, s[38:39]
	global_store_dwordx2 v6, v[246:247], s[46:47]
	s_and_saveexec_b64 s[16:17], s[42:43]
	s_cbranch_execz .LBB0_1333
	s_waitcnt lgkmcnt(1)
	v_add_f32_e32 v2, v2, v3
	s_waitcnt lgkmcnt(0)
	v_add_f32_e32 v3, v4, v5
	ds_write2_b32 v194, v2, v3 offset0:112 offset1:120

; #define LAS __attribute__((address_space(3)))
; #define ERN_EOFF(q, m) (eb + (unsigned)((((q) & 1) * HALF + (m) * 16) * DM + ERN_COL((q) >> 1)))
;     __device__ __forceinline__ void operator()(const f32x4 (&acc)[2][2][4][2], const Unit& u, int wr, int wc, int fr, int fq) const {
;     ...
;         ERN_LOADX(0);
; #pragma unroll
;         for (int g = 0; g < 8; ++g) { const int ai = g >> 2, m = g & 3;
;             if (g + 1 < 8) ERN_LOADX(g + 1);
;             float sq0 = 0.f, sq1 = 0.f; u32x2 hw[2][2];
; #pragma unroll
;             for (int bj = 0; bj < 2; ++bj) {
;                 *(LAS f32x4*)(st + wr_off) = acc[ai][bj][m][0]; *(LAS f32x4*)(st + wr_off + 64) = acc[ai][bj][m][1];
;                 const f32x4 a0 = *(const LAS f32x4*)(st + rd_off), a1 = *(const LAS f32x4*)(st + rd_off + 8 * 144);
;                 { const f32x4 xv = xb[g & 1][bj][0] + gv[bj] * a0; __builtin_nontemporal_store(xv, (f32x4*)((char*)xo + 4u * ERN_EOFF(g, bj, 0)));
;                   sq0 += (xv.x * xv.x + xv.y * xv.y) + (xv.z * xv.z + xv.w * xv.w);
;                   const f32x4 hv = xv * gsn[bj]; hw[bj][0].x = cvt_pk_bf16(hv.x, hv.y); hw[bj][0].y = cvt_pk_bf16(hv.z, hv.w); }
;                 { const f32x4 xv = xb[g & 1][bj][1] + gv[bj] * a1; __builtin_nontemporal_store(xv, (f32x4*)((char*)xo + 4u * ERN_EOFF(g, bj, 1)));
;                   sq1 += (xv.x * xv.x + xv.y * xv.y) + (xv.z * xv.z + xv.w * xv.w);
;                   const f32x4 hv = xv * gsn[bj]; hw[bj][1].x = cvt_pk_bf16(hv.x, hv.y); hw[bj][1].y = cvt_pk_bf16(hv.z, hv.w); }
;             }
;             if (!NOH && !PLAIN) {
; #pragma unroll
;                 for (int rh = 0; rh < 2; ++rh) { u32x2 rv; rv.x = __shfl_xor(hw[1][rh].x, 8); rv.y = __shfl_xor(hw[1][rh].y, 8);
;                     const unsigned e0 = ERN_EOFF(g, 0, rh);
;                     const unsigned ee = odd ? (e0 - DM + 32) : e0, eo2 = odd ? e0 : (e0 + DM + 32);
;                     *(u32x2*)((char*)ho + 2u * ee) = odd ? rv : hw[0][rh];
;                     *(u32x2*)((char*)ho + 2u * eo2) = odd ? hw[0][rh] : rv; }
;             }
;             if (!PLAIN) { sq0 += __shfl_xor(sq0, 1); sq0 += __shfl_xor(sq0, 2); sq0 += __shfl_xor(sq0, 4);
;             sq1 += __shfl_xor(sq1, 1); sq1 += __shfl_xor(sq1, 2); sq1 += __shfl_xor(sq1, 4); }
;             if (!PLAIN && pc == 0) { sst[g * 16 + rr] = sq0; sst[g * 16 + 8 + rr] = sq1; }
.LBB0_1628:
	s_or_b64 exec, exec, s[16:17]
	v_lshl_add_u64 v[116:117], s[22:23], 0, v[154:155]
	v_add_u32_e32 v82, 0x100000, v205
	s_waitcnt lgkmcnt(1)
	v_add_u32_e32 v83, 0x110000, v205
	v_add_u32_e32 v154, 0x100080, v205
	global_load_dwordx4 v[94:97], v82, s[22:23]
	global_load_dwordx4 v[90:93], v83, s[22:23]
	v_add_u32_e32 v114, 0x110080, v205
	global_load_dwordx4 v[86:89], v154, s[22:23]
	s_waitcnt lgkmcnt(0)
	global_load_dwordx4 v[82:85], v114, s[22:23]
	v_add_u32_e32 v128, 0x120000, v205
	global_load_dwordx4 v[120:123], v128, s[22:23]
	v_add_u32_e32 v129, 0x130000, v205
	global_load_dwordx4 v[124:127], v129, s[22:23]
	v_add_u32_e32 v134, 0x120080, v205
	global_load_dwordx4 v[136:139], v134, s[22:23]
	v_add_u32_e32 v135, 0x130080, v205
	global_load_dwordx4 v[140:143], v135, s[22:23]
	ds_write_b128 v200, v[78:81]
	ds_write_b128 v200, v[74:77] offset:64
	ds_read_b128 v[74:77], v201
	ds_read_b128 v[78:81], v201 offset:1152
	v_mov_b32_e32 v131, v155
	v_mov_b32_e32 v133, v155
	s_waitcnt vmcnt(15) lgkmcnt(1)
	v_pk_fma_f32 v[76:77], v[176:177], v[76:77], v[112:113]
	v_add_u32_e32 v112, 0x18000, v202
	v_pk_fma_f32 v[74:75], v[180:181], v[74:75], v[110:111]
	v_lshlrev_b32_e32 v110, 2, v112
	s_waitcnt lgkmcnt(0)
	v_pk_fma_f32 v[78:79], v[180:181], v[78:79], v[106:107]
	global_store_dwordx4 v110, v[74:77], s[22:23] nt
	v_pk_mul_f32 v[110:111], v[178:179], v[74:75]
	v_pk_fma_f32 v[80:81], v[176:177], v[80:81], v[108:109]
	v_pk_mul_f32 v[106:107], v[178:179], v[78:79]
	v_pk_mul_f32 v[118:119], v[174:175], v[76:77]
	v_cvt_pk_bf16_f32 v110, v110, v111
	v_pk_mul_f32 v[108:109], v[174:175], v[80:81]
	v_cvt_pk_bf16_f32 v111, v118, v119
	global_store_dwordx4 v[116:117], v[78:81], off nt
	v_cvt_pk_bf16_f32 v106, v106, v107
	v_cvt_pk_bf16_f32 v107, v108, v109
	ds_write_b128 v200, v[70:73]
	ds_write_b128 v200, v[66:69] offset:64
	ds_read_b128 v[66:69], v201
	ds_read_b128 v[70:73], v201 offset:1152
	v_lshl_add_u64 v[108:109], s[22:23], 0, v[130:131]
	v_lshl_add_u64 v[116:117], s[22:23], 0, v[132:133]
	s_waitcnt lgkmcnt(1)
	v_pk_fma_f32 v[66:67], v[168:169], v[66:67], v[102:103]
	v_pk_fma_f32 v[68:69], v[166:167], v[68:69], v[104:105]
	v_pk_mul_f32 v[104:105], v[172:173], v[66:67]
	global_store_dwordx4 v[108:109], v[66:69], off nt
	v_pk_mul_f32 v[102:103], v[170:171], v[68:69]
	v_cvt_pk_bf16_f32 v104, v104, v105
	s_waitcnt vmcnt(17) lgkmcnt(0)
	v_pk_fma_f32 v[70:71], v[168:169], v[70:71], v[98:99]
	v_cvt_pk_bf16_f32 v105, v102, v103
	ds_bpermute_b32 v98, v203, v104
	ds_bpermute_b32 v99, v203, v105
	v_pk_fma_f32 v[72:73], v[166:167], v[72:73], v[100:101]
	v_pk_mul_f32 v[100:101], v[172:173], v[70:71]
	v_pk_mul_f32 v[102:103], v[170:171], v[72:73]
	global_store_dwordx4 v[116:117], v[70:73], off nt
	v_cvt_pk_bf16_f32 v100, v100, v101
	v_cvt_pk_bf16_f32 v101, v102, v103
	v_lshlrev_b32_e32 v102, 1, v112
	s_waitcnt lgkmcnt(0)
	v_add_u32_e32 v250, 0xfffff040, v102
	v_cndmask_b32_e64 v250, v102, v250, s[40:41]
	v_cndmask_b32_e64 v248, v110, v98, s[40:41]
	v_cndmask_b32_e64 v249, v111, v99, s[40:41]
	global_store_dwordx2 v250, v[248:249], s[20:21]
	v_cndmask_b32_e64 v246, v98, v110, s[40:41]
	v_cndmask_b32_e64 v247, v99, v111, s[40:41]
	s_waitcnt lgkmcnt(1)
	v_add_u32_e32 v98, 0x1040, v102
	v_cndmask_b32_e64 v98, v102, v98, s[38:39]
	global_store_dwordx2 v98, v[246:247], s[20:21]
	ds_bpermute_b32 v98, v203, v100
	s_waitcnt lgkmcnt(1)
	ds_bpermute_b32 v99, v203, v101
	v_add_u32_e32 v101, 0x1c000, v202
	v_lshlrev_b32_e32 v100, 1, v101
	s_waitcnt lgkmcnt(0)
	v_add_u32_e32 v250, 0xfffff040, v100
	v_cndmask_b32_e64 v250, v100, v250, s[40:41]
	v_cndmask_b32_e64 v248, v106, v98, s[40:41]
	v_cndmask_b32_e64 v249, v107, v99, s[40:41]
	global_store_dwordx2 v250, v[248:249], s[20:21]
	v_cndmask_b32_e64 v246, v98, v106, s[40:41]
	v_cndmask_b32_e64 v247, v99, v107, s[40:41]
	v_mul_f32_e32 v67, v67, v67
	v_fmac_f32_e32 v67, v66, v66
	v_mul_f32_e32 v66, v69, v69
	v_mul_f32_e32 v77, v77, v77
	v_fmac_f32_e32 v66, v68, v68
	v_mul_f32_e32 v75, v75, v75
	v_fmac_f32_e32 v77, v76, v76
	v_mul_f32_e32 v76, v79, v79
	v_mul_f32_e32 v79, v81, v81
	v_add_f32_e32 v66, v67, v66
	v_mul_f32_e32 v67, v71, v71
	v_mul_f32_e32 v68, v73, v73
	v_fmac_f32_e32 v79, v80, v80
	v_fmac_f32_e32 v67, v70, v70
	v_fmac_f32_e32 v68, v72, v72
	v_fmac_f32_e32 v75, v74, v74
	v_fmac_f32_e32 v76, v78, v78
	v_add_f32_e32 v67, v67, v68
	v_add_f32_e32 v68, v75, v77
	v_add_f32_e32 v69, v76, v79
	v_add_f32_e32 v66, v68, v66
	v_add_f32_e32 v67, v69, v67
	ds_bpermute_b32 v68, v190, v66
	ds_bpermute_b32 v69, v190, v67
	s_waitcnt lgkmcnt(1)
	v_add_f32_e32 v66, v66, v68
	s_waitcnt lgkmcnt(0)
	v_add_f32_e32 v69, v67, v69
	ds_bpermute_b32 v68, v191, v66
	ds_bpermute_b32 v70, v191, v69
	s_waitcnt lgkmcnt(1)
	v_add_f32_e32 v66, v66, v68
	s_waitcnt lgkmcnt(0)
	v_add_f32_e32 v68, v69, v70
	ds_bpermute_b32 v67, v204, v66
	ds_bpermute_b32 v69, v204, v68
	v_add_u32_e32 v70, 0x1040, v100
	v_cndmask_b32_e64 v70, v100, v70, s[38:39]
	global_store_dwordx2 v70, v[246:247], s[20:21]
	s_and_saveexec_b64 s[16:17], s[42:43]
	s_cbranch_execz .LBB0_1638
	s_waitcnt lgkmcnt(1)
	v_add_f32_e32 v66, v66, v67
	s_waitcnt lgkmcnt(0)
	v_add_f32_e32 v67, v68, v69
	ds_write2_b32 v194, v66, v67 offset0:48 offset1:56
; #define LAS __attribute__((address_space(3)))
; #define ERN_EOFF(q, m) (eb + (unsigned)((((q) & 1) * HALF + (m) * 16) * DM + ERN_COL((q) >> 1)))
;     __device__ __forceinline__ void operator()(const f32x4 (&acc)[2][2][4][2], const Unit& u, int wr, int wc, int fr, int fq) const {
;     ...
;         ERN_LOADX(0);
; #pragma unroll
;         for (int g = 0; g < 8; ++g) { const int ai = g >> 2, m = g & 3;
;             if (g + 1 < 8) ERN_LOADX(g + 1);
;             float sq0 = 0.f, sq1 = 0.f; u32x2 hw[2][2];
; #pragma unroll
;             for (int bj = 0; bj < 2; ++bj) {
;                 *(LAS f32x4*)(st + wr_off) = acc[ai][bj][m][0]; *(LAS f32x4*)(st + wr_off + 64) = acc[ai][bj][m][1];
;                 const f32x4 a0 = *(const LAS f32x4*)(st + rd_off), a1 = *(const LAS f32x4*)(st + rd_off + 8 * 144);
;                 { const f32x4 xv = xb[g & 1][bj][0] + gv[bj] * a0; __builtin_nontemporal_store(xv, (f32x4*)((char*)xo + 4u * ERN_EOFF(g, bj, 0)));
;                   sq0 += (xv.x * xv.x + xv.y * xv.y) + (xv.z * xv.z + xv.w * xv.w);
;                   const f32x4 hv = xv * gsn[bj]; hw[bj][0].x = cvt_pk_bf16(hv.x, hv.y); hw[bj][0].y = cvt_pk_bf16(hv.z, hv.w); }
;                 { const f32x4 xv = xb[g & 1][bj][1] + gv[bj] * a1; __builtin_nontemporal_store(xv, (f32x4*)((char*)xo + 4u * ERN_EOFF(g, bj, 1)));
;                   sq1 += (xv.x * xv.x + xv.y * xv.y) + (xv.z * xv.z + xv.w * xv.w);
;                   const f32x4 hv = xv * gsn[bj]; hw[bj][1].x = cvt_pk_bf16(hv.x, hv.y); hw[bj][1].y = cvt_pk_bf16(hv.z, hv.w); }
;             }
;             if (!NOH && !PLAIN) {
; #pragma unroll
;                 for (int rh = 0; rh < 2; ++rh) { u32x2 rv; rv.x = __shfl_xor(hw[1][rh].x, 8); rv.y = __shfl_xor(hw[1][rh].y, 8);
;                     const unsigned e0 = ERN_EOFF(g, 0, rh);
;                     const unsigned ee = odd ? (e0 - DM + 32) : e0, eo2 = odd ? e0 : (e0 + DM + 32);
;                     *(u32x2*)((char*)ho + 2u * ee) = odd ? rv : hw[0][rh];
;                     *(u32x2*)((char*)ho + 2u * eo2) = odd ? hw[0][rh] : rv; }
;             }
;             if (!PLAIN) { sq0 += __shfl_xor(sq0, 1); sq0 += __shfl_xor(sq0, 2); sq0 += __shfl_xor(sq0, 4);
;             sq1 += __shfl_xor(sq1, 1); sq1 += __shfl_xor(sq1, 2); sq1 += __shfl_xor(sq1, 4); }
;             if (!PLAIN && pc == 0) { sst[g * 16 + rr] = sq0; sst[g * 16 + 8 + rr] = sq1; }
.LBB0_1638:
	s_or_b64 exec, exec, s[16:17]
	v_lshl_add_u64 v[104:105], s[22:23], 0, v[154:155]
	v_add_u32_e32 v154, 0x120000, v205
	v_add_u32_e32 v100, 0x120080, v205
	v_add_u32_e32 v102, 0x130000, v205
	v_add_u32_e32 v98, 0x130080, v205
	s_waitcnt lgkmcnt(0)
	v_add_u32_e32 v128, 0x140000, v205
	global_load_dwordx4 v[184:187], v128, s[22:23]
	v_add_u32_e32 v129, 0x150000, v205
	global_load_dwordx4 v[208:211], v129, s[22:23]
	v_add_u32_e32 v134, 0x140080, v205
	global_load_dwordx4 v[212:215], v134, s[22:23]
	v_add_u32_e32 v135, 0x150080, v205
	global_load_dwordx4 v[216:219], v135, s[22:23]
	ds_write_b128 v200, v[62:65]
	ds_write_b128 v200, v[58:61] offset:64
	ds_read_b128 v[58:61], v201
	ds_read_b128 v[62:65], v201 offset:1152
	v_mov_b32_e32 v115, v155
	s_waitcnt vmcnt(17) lgkmcnt(1)
	v_pk_fma_f32 v[60:61], v[176:177], v[60:61], v[96:97]
	v_add_u32_e32 v96, 0x40000, v202
	v_pk_fma_f32 v[58:59], v[180:181], v[58:59], v[94:95]
	v_lshlrev_b32_e32 v94, 2, v96
	s_waitcnt vmcnt(16) lgkmcnt(0)
	v_pk_fma_f32 v[64:65], v[176:177], v[64:65], v[92:93]
	v_add_u32_e32 v92, 0x44000, v202
	global_store_dwordx4 v94, v[58:61], s[22:23] nt
	v_pk_mul_f32 v[94:95], v[178:179], v[58:59]
	v_pk_fma_f32 v[62:63], v[180:181], v[62:63], v[90:91]
	v_lshlrev_b32_e32 v90, 2, v92
	v_pk_mul_f32 v[106:107], v[174:175], v[60:61]
	v_cvt_pk_bf16_f32 v94, v94, v95
	s_nop 0
	v_cvt_pk_bf16_f32 v95, v106, v107
	global_store_dwordx4 v90, v[62:65], s[22:23] nt
	v_pk_mul_f32 v[90:91], v[178:179], v[62:63]
	v_pk_mul_f32 v[106:107], v[174:175], v[64:65]
	v_cvt_pk_bf16_f32 v90, v90, v91
	s_nop 0
	v_cvt_pk_bf16_f32 v91, v106, v107
	ds_write_b128 v200, v[54:57]
	ds_write_b128 v200, v[50:53] offset:64
	ds_read_b128 v[50:53], v201
	ds_read_b128 v[54:57], v201 offset:1152
	v_lshl_add_u64 v[106:107], s[22:23], 0, v[114:115]
	s_waitcnt vmcnt(17) lgkmcnt(1)
	v_pk_fma_f32 v[50:51], v[168:169], v[50:51], v[86:87]
	v_pk_fma_f32 v[52:53], v[166:167], v[52:53], v[88:89]
	v_pk_mul_f32 v[88:89], v[172:173], v[50:51]
	global_store_dwordx4 v[104:105], v[50:53], off nt
	v_pk_mul_f32 v[86:87], v[170:171], v[52:53]
	v_cvt_pk_bf16_f32 v88, v88, v89
	s_waitcnt vmcnt(17) lgkmcnt(0)
	v_pk_fma_f32 v[54:55], v[168:169], v[54:55], v[82:83]
	v_cvt_pk_bf16_f32 v89, v86, v87
	ds_bpermute_b32 v82, v203, v88
	ds_bpermute_b32 v83, v203, v89
	v_pk_fma_f32 v[56:57], v[166:167], v[56:57], v[84:85]
	v_pk_mul_f32 v[84:85], v[172:173], v[54:55]
	v_pk_mul_f32 v[86:87], v[170:171], v[56:57]
	global_store_dwordx4 v[106:107], v[54:57], off nt
	v_cvt_pk_bf16_f32 v84, v84, v85
	v_cvt_pk_bf16_f32 v85, v86, v87
	v_lshlrev_b32_e32 v86, 1, v96
	s_waitcnt lgkmcnt(0)
	v_add_u32_e32 v250, 0xfffff040, v86
	v_cndmask_b32_e64 v250, v86, v250, s[40:41]
	v_cndmask_b32_e64 v248, v94, v82, s[40:41]
	v_cndmask_b32_e64 v249, v95, v83, s[40:41]
	global_store_dwordx2 v250, v[248:249], s[20:21]
	v_cndmask_b32_e64 v246, v82, v94, s[40:41]
	v_cndmask_b32_e64 v247, v83, v95, s[40:41]
	s_waitcnt lgkmcnt(1)
	v_add_u32_e32 v82, 0x1040, v86
	v_cndmask_b32_e64 v82, v86, v82, s[38:39]
	global_store_dwordx2 v82, v[246:247], s[20:21]
	ds_bpermute_b32 v82, v203, v84
	s_waitcnt lgkmcnt(1)
	ds_bpermute_b32 v83, v203, v85
	v_lshlrev_b32_e32 v84, 1, v92
	s_waitcnt lgkmcnt(0)
	v_add_u32_e32 v250, 0xfffff040, v84
	v_cndmask_b32_e64 v250, v84, v250, s[40:41]
	v_cndmask_b32_e64 v248, v90, v82, s[40:41]
	v_cndmask_b32_e64 v249, v91, v83, s[40:41]
	global_store_dwordx2 v250, v[248:249], s[20:21]
	v_cndmask_b32_e64 v246, v82, v90, s[40:41]
	v_cndmask_b32_e64 v247, v83, v91, s[40:41]
	v_mul_f32_e32 v51, v51, v51
	v_fmac_f32_e32 v51, v50, v50
	v_mul_f32_e32 v50, v53, v53
	v_mul_f32_e32 v61, v61, v61
	v_fmac_f32_e32 v50, v52, v52
	v_mul_f32_e32 v59, v59, v59
	v_fmac_f32_e32 v61, v60, v60
	v_mul_f32_e32 v60, v63, v63
	v_mul_f32_e32 v63, v65, v65
	v_add_f32_e32 v50, v51, v50
	v_mul_f32_e32 v51, v55, v55
	v_mul_f32_e32 v52, v57, v57
	v_fmac_f32_e32 v63, v64, v64
	v_fmac_f32_e32 v51, v54, v54
	v_fmac_f32_e32 v52, v56, v56
	v_fmac_f32_e32 v59, v58, v58
	v_fmac_f32_e32 v60, v62, v62
	v_add_f32_e32 v51, v51, v52
	v_add_f32_e32 v52, v59, v61
	v_add_f32_e32 v53, v60, v63
	v_add_f32_e32 v50, v52, v50
	v_add_f32_e32 v51, v53, v51
	ds_bpermute_b32 v52, v190, v50
	ds_bpermute_b32 v53, v190, v51
	s_waitcnt lgkmcnt(1)
	v_add_f32_e32 v50, v50, v52
	s_waitcnt lgkmcnt(0)
	v_add_f32_e32 v53, v51, v53
	ds_bpermute_b32 v52, v191, v50
	ds_bpermute_b32 v54, v191, v53
	s_waitcnt lgkmcnt(1)
	v_add_f32_e32 v50, v50, v52
	s_waitcnt lgkmcnt(0)
	v_add_f32_e32 v52, v53, v54
	ds_bpermute_b32 v51, v204, v50
	ds_bpermute_b32 v53, v204, v52
	v_add_u32_e32 v54, 0x1040, v84
	v_cndmask_b32_e64 v54, v84, v54, s[38:39]
	global_store_dwordx2 v54, v[246:247], s[20:21]
	s_and_saveexec_b64 s[16:17], s[42:43]
	s_cbranch_execz .LBB0_1648
	s_waitcnt lgkmcnt(1)
	v_add_f32_e32 v50, v50, v51
	s_waitcnt lgkmcnt(0)
	v_add_f32_e32 v51, v52, v53
	ds_write2_b32 v194, v50, v51 offset0:64 offset1:72
; #define LAS __attribute__((address_space(3)))
; #define ERN_EOFF(q, m) (eb + (unsigned)((((q) & 1) * HALF + (m) * 16) * DM + ERN_COL((q) >> 1)))
;     __device__ __forceinline__ void operator()(const f32x4 (&acc)[2][2][4][2], const Unit& u, int wr, int wc, int fr, int fq) const {
;     ...
;         ERN_LOADX(0);
; #pragma unroll
;         for (int g = 0; g < 8; ++g) { const int ai = g >> 2, m = g & 3;
;             if (g + 1 < 8) ERN_LOADX(g + 1);
;             float sq0 = 0.f, sq1 = 0.f; u32x2 hw[2][2];
; #pragma unroll
;             for (int bj = 0; bj < 2; ++bj) {
;                 *(LAS f32x4*)(st + wr_off) = acc[ai][bj][m][0]; *(LAS f32x4*)(st + wr_off + 64) = acc[ai][bj][m][1];
;                 const f32x4 a0 = *(const LAS f32x4*)(st + rd_off), a1 = *(const LAS f32x4*)(st + rd_off + 8 * 144);
;                 { const f32x4 xv = xb[g & 1][bj][0] + gv[bj] * a0; __builtin_nontemporal_store(xv, (f32x4*)((char*)xo + 4u * ERN_EOFF(g, bj, 0)));
;                   sq0 += (xv.x * xv.x + xv.y * xv.y) + (xv.z * xv.z + xv.w * xv.w);
;                   const f32x4 hv = xv * gsn[bj]; hw[bj][0].x = cvt_pk_bf16(hv.x, hv.y); hw[bj][0].y = cvt_pk_bf16(hv.z, hv.w); }
;                 { const f32x4 xv = xb[g & 1][bj][1] + gv[bj] * a1; __builtin_nontemporal_store(xv, (f32x4*)((char*)xo + 4u * ERN_EOFF(g, bj, 1)));
;                   sq1 += (xv.x * xv.x + xv.y * xv.y) + (xv.z * xv.z + xv.w * xv.w);
;                   const f32x4 hv = xv * gsn[bj]; hw[bj][1].x = cvt_pk_bf16(hv.x, hv.y); hw[bj][1].y = cvt_pk_bf16(hv.z, hv.w); }
;             }
;             if (!NOH && !PLAIN) {
; #pragma unroll
;                 for (int rh = 0; rh < 2; ++rh) { u32x2 rv; rv.x = __shfl_xor(hw[1][rh].x, 8); rv.y = __shfl_xor(hw[1][rh].y, 8);
;                     const unsigned e0 = ERN_EOFF(g, 0, rh);
;                     const unsigned ee = odd ? (e0 - DM + 32) : e0, eo2 = odd ? e0 : (e0 + DM + 32);
;                     *(u32x2*)((char*)ho + 2u * ee) = odd ? rv : hw[0][rh];
;                     *(u32x2*)((char*)ho + 2u * eo2) = odd ? hw[0][rh] : rv; }
;             }
;             if (!PLAIN) { sq0 += __shfl_xor(sq0, 1); sq0 += __shfl_xor(sq0, 2); sq0 += __shfl_xor(sq0, 4);
;             sq1 += __shfl_xor(sq1, 1); sq1 += __shfl_xor(sq1, 2); sq1 += __shfl_xor(sq1, 4); }
;             if (!PLAIN && pc == 0) { sst[g * 16 + rr] = sq0; sst[g * 16 + 8 + rr] = sq1; }
.LBB0_1648:
	s_or_b64 exec, exec, s[16:17]
	v_lshl_add_u64 v[88:89], s[22:23], 0, v[154:155]
	v_add_u32_e32 v154, 0x140000, v205
	v_add_u32_e32 v84, 0x140080, v205
	v_add_u32_e32 v86, 0x150000, v205
	v_add_u32_e32 v82, 0x150080, v205
	s_waitcnt lgkmcnt(0)
	ds_write_b128 v200, v[46:49]
	ds_write_b128 v200, v[42:45] offset:64
	ds_read_b128 v[42:45], v201
	ds_read_b128 v[46:49], v201 offset:1152
	v_mov_b32_e32 v103, v155
	v_lshl_add_u64 v[90:91], s[22:23], 0, v[102:103]
	v_mov_b32_e32 v101, v155
	s_waitcnt vmcnt(18) lgkmcnt(1)
	v_mov_b64_e32 v[78:79], v[120:121]
	v_mov_b64_e32 v[80:81], v[122:123]
	v_mov_b64_e32 v[74:75], v[124:125]
	v_mov_b64_e32 v[76:77], v[126:127]
	v_mov_b64_e32 v[70:71], v[136:137]
	v_mov_b64_e32 v[72:73], v[138:139]
	v_mov_b64_e32 v[66:67], v[140:141]
	v_mov_b64_e32 v[68:69], v[142:143]
	v_add_u32_e32 v128, 0x160000, v205
	global_load_dwordx4 v[120:123], v128, s[22:23]
	v_add_u32_e32 v129, 0x170000, v205
	global_load_dwordx4 v[124:127], v129, s[22:23]
	v_add_u32_e32 v134, 0x160080, v205
	global_load_dwordx4 v[136:139], v134, s[22:23]
	v_add_u32_e32 v135, 0x170080, v205
	global_load_dwordx4 v[140:143], v135, s[22:23]
	v_pk_fma_f32 v[42:43], v[180:181], v[42:43], v[78:79]
	s_waitcnt lgkmcnt(0)
	v_pk_fma_f32 v[46:47], v[180:181], v[46:47], v[74:75]
	v_pk_fma_f32 v[44:45], v[176:177], v[44:45], v[80:81]
	v_pk_mul_f32 v[78:79], v[178:179], v[42:43]
	v_pk_fma_f32 v[48:49], v[176:177], v[48:49], v[76:77]
	v_pk_mul_f32 v[74:75], v[178:179], v[46:47]
	global_store_dwordx4 v[88:89], v[42:45], off nt
	v_pk_mul_f32 v[80:81], v[174:175], v[44:45]
	v_cvt_pk_bf16_f32 v78, v78, v79
	v_pk_mul_f32 v[76:77], v[174:175], v[48:49]
	v_cvt_pk_bf16_f32 v79, v80, v81
	global_store_dwordx4 v[90:91], v[46:49], off nt
	v_cvt_pk_bf16_f32 v74, v74, v75
	v_cvt_pk_bf16_f32 v75, v76, v77
	ds_write_b128 v200, v[38:41]
	ds_write_b128 v200, v[34:37] offset:64
	ds_read_b128 v[34:37], v201
	ds_read_b128 v[38:41], v201 offset:1152
	v_lshl_add_u64 v[76:77], s[22:23], 0, v[100:101]
	v_mov_b32_e32 v99, v155
	v_lshl_add_u64 v[80:81], s[22:23], 0, v[98:99]
	s_waitcnt lgkmcnt(1)
	v_pk_fma_f32 v[34:35], v[168:169], v[34:35], v[70:71]
	v_pk_fma_f32 v[36:37], v[166:167], v[36:37], v[72:73]
	v_pk_mul_f32 v[72:73], v[172:173], v[34:35]
	global_store_dwordx4 v[76:77], v[34:37], off nt
	v_pk_mul_f32 v[70:71], v[170:171], v[36:37]
	v_cvt_pk_bf16_f32 v72, v72, v73
	s_waitcnt lgkmcnt(0)
	v_pk_fma_f32 v[38:39], v[168:169], v[38:39], v[66:67]
	v_cvt_pk_bf16_f32 v73, v70, v71
	ds_bpermute_b32 v66, v203, v72
	ds_bpermute_b32 v67, v203, v73
	v_pk_fma_f32 v[40:41], v[166:167], v[40:41], v[68:69]
	v_pk_mul_f32 v[68:69], v[172:173], v[38:39]
	v_pk_mul_f32 v[70:71], v[170:171], v[40:41]
	global_store_dwordx4 v[80:81], v[38:41], off nt
	v_cvt_pk_bf16_f32 v68, v68, v69
	v_cvt_pk_bf16_f32 v69, v70, v71
	v_add_u32_e32 v71, 0x48000, v202
	v_lshlrev_b32_e32 v70, 1, v71
	s_waitcnt lgkmcnt(0)
	v_add_u32_e32 v250, 0xfffff040, v70
	v_cndmask_b32_e64 v250, v70, v250, s[40:41]
	v_cndmask_b32_e64 v248, v78, v66, s[40:41]
	v_cndmask_b32_e64 v249, v79, v67, s[40:41]
	global_store_dwordx2 v250, v[248:249], s[20:21]
	v_cndmask_b32_e64 v246, v66, v78, s[40:41]
	v_cndmask_b32_e64 v247, v67, v79, s[40:41]
	s_waitcnt lgkmcnt(1)
	v_add_u32_e32 v66, 0x1040, v70
	v_cndmask_b32_e64 v66, v70, v66, s[38:39]
	global_store_dwordx2 v66, v[246:247], s[20:21]
	ds_bpermute_b32 v66, v203, v68
	s_waitcnt lgkmcnt(1)
	ds_bpermute_b32 v67, v203, v69
	v_add_u32_e32 v69, 0x4c000, v202
	v_lshlrev_b32_e32 v68, 1, v69
	s_waitcnt lgkmcnt(0)
	v_add_u32_e32 v250, 0xfffff040, v68
	v_cndmask_b32_e64 v250, v68, v250, s[40:41]
	v_cndmask_b32_e64 v248, v74, v66, s[40:41]
	v_cndmask_b32_e64 v249, v75, v67, s[40:41]
	global_store_dwordx2 v250, v[248:249], s[20:21]
	v_cndmask_b32_e64 v246, v66, v74, s[40:41]
	v_cndmask_b32_e64 v247, v67, v75, s[40:41]
	v_mul_f32_e32 v35, v35, v35
	v_fmac_f32_e32 v35, v34, v34
	v_mul_f32_e32 v34, v37, v37
	v_mul_f32_e32 v45, v45, v45
	v_fmac_f32_e32 v34, v36, v36
	v_mul_f32_e32 v43, v43, v43
	v_fmac_f32_e32 v45, v44, v44
	v_mul_f32_e32 v44, v47, v47
	v_mul_f32_e32 v47, v49, v49
	v_add_f32_e32 v34, v35, v34
	v_mul_f32_e32 v35, v39, v39
	v_mul_f32_e32 v36, v41, v41
	v_fmac_f32_e32 v47, v48, v48
	v_fmac_f32_e32 v35, v38, v38
	v_fmac_f32_e32 v36, v40, v40
	v_fmac_f32_e32 v43, v42, v42
	v_fmac_f32_e32 v44, v46, v46
	v_add_f32_e32 v35, v35, v36
	v_add_f32_e32 v36, v43, v45
	v_add_f32_e32 v37, v44, v47
	v_add_f32_e32 v34, v36, v34
	v_add_f32_e32 v35, v37, v35
	ds_bpermute_b32 v36, v190, v34
	ds_bpermute_b32 v37, v190, v35
	s_waitcnt lgkmcnt(1)
	v_add_f32_e32 v34, v34, v36
	s_waitcnt lgkmcnt(0)
	v_add_f32_e32 v37, v35, v37
	ds_bpermute_b32 v36, v191, v34
	ds_bpermute_b32 v38, v191, v37
	s_waitcnt lgkmcnt(1)
	v_add_f32_e32 v34, v34, v36
	s_waitcnt lgkmcnt(0)
	v_add_f32_e32 v36, v37, v38
	ds_bpermute_b32 v35, v204, v34
	ds_bpermute_b32 v37, v204, v36
	v_add_u32_e32 v38, 0x1040, v68
	v_cndmask_b32_e64 v38, v68, v38, s[38:39]
	global_store_dwordx2 v38, v[246:247], s[20:21]
	s_and_saveexec_b64 s[16:17], s[42:43]
	s_cbranch_execz .LBB0_1658
	s_waitcnt lgkmcnt(1)
	v_add_f32_e32 v34, v34, v35
	s_waitcnt lgkmcnt(0)
	v_add_f32_e32 v35, v36, v37
	ds_write2_b32 v194, v34, v35 offset0:80 offset1:88
; #define LAS __attribute__((address_space(3)))
; #define ERN_EOFF(q, m) (eb + (unsigned)((((q) & 1) * HALF + (m) * 16) * DM + ERN_COL((q) >> 1)))
;     __device__ __forceinline__ void operator()(const f32x4 (&acc)[2][2][4][2], const Unit& u, int wr, int wc, int fr, int fq) const {
;     ...
;         ERN_LOADX(0);
; #pragma unroll
;         for (int g = 0; g < 8; ++g) { const int ai = g >> 2, m = g & 3;
;             if (g + 1 < 8) ERN_LOADX(g + 1);
;             float sq0 = 0.f, sq1 = 0.f; u32x2 hw[2][2];
; #pragma unroll
;             for (int bj = 0; bj < 2; ++bj) {
;                 *(LAS f32x4*)(st + wr_off) = acc[ai][bj][m][0]; *(LAS f32x4*)(st + wr_off + 64) = acc[ai][bj][m][1];
;                 const f32x4 a0 = *(const LAS f32x4*)(st + rd_off), a1 = *(const LAS f32x4*)(st + rd_off + 8 * 144);
;                 { const f32x4 xv = xb[g & 1][bj][0] + gv[bj] * a0; __builtin_nontemporal_store(xv, (f32x4*)((char*)xo + 4u * ERN_EOFF(g, bj, 0)));
;                   sq0 += (xv.x * xv.x + xv.y * xv.y) + (xv.z * xv.z + xv.w * xv.w);
;                   const f32x4 hv = xv * gsn[bj]; hw[bj][0].x = cvt_pk_bf16(hv.x, hv.y); hw[bj][0].y = cvt_pk_bf16(hv.z, hv.w); }
;                 { const f32x4 xv = xb[g & 1][bj][1] + gv[bj] * a1; __builtin_nontemporal_store(xv, (f32x4*)((char*)xo + 4u * ERN_EOFF(g, bj, 1)));
;                   sq1 += (xv.x * xv.x + xv.y * xv.y) + (xv.z * xv.z + xv.w * xv.w);
;                   const f32x4 hv = xv * gsn[bj]; hw[bj][1].x = cvt_pk_bf16(hv.x, hv.y); hw[bj][1].y = cvt_pk_bf16(hv.z, hv.w); }
;             }
;             if (!NOH && !PLAIN) {
; #pragma unroll
;                 for (int rh = 0; rh < 2; ++rh) { u32x2 rv; rv.x = __shfl_xor(hw[1][rh].x, 8); rv.y = __shfl_xor(hw[1][rh].y, 8);
;                     const unsigned e0 = ERN_EOFF(g, 0, rh);
;                     const unsigned ee = odd ? (e0 - DM + 32) : e0, eo2 = odd ? e0 : (e0 + DM + 32);
;                     *(u32x2*)((char*)ho + 2u * ee) = odd ? rv : hw[0][rh];
;                     *(u32x2*)((char*)ho + 2u * eo2) = odd ? hw[0][rh] : rv; }
;             }
;             if (!PLAIN) { sq0 += __shfl_xor(sq0, 1); sq0 += __shfl_xor(sq0, 2); sq0 += __shfl_xor(sq0, 4);
;             sq1 += __shfl_xor(sq1, 1); sq1 += __shfl_xor(sq1, 2); sq1 += __shfl_xor(sq1, 4); }
;             if (!PLAIN && pc == 0) { sst[g * 16 + rr] = sq0; sst[g * 16 + 8 + rr] = sq1; }
.LBB0_1658:
	s_or_b64 exec, exec, s[16:17]
	v_lshl_add_u64 v[72:73], s[22:23], 0, v[154:155]
	v_add_u32_e32 v154, 0x160000, v205
	v_add_u32_e32 v68, 0x160080, v205
	v_add_u32_e32 v70, 0x170000, v205
	v_add_u32_e32 v66, 0x170080, v205
	s_waitcnt lgkmcnt(0)
	ds_write_b128 v200, v[30:33]
	ds_write_b128 v200, v[26:29] offset:64
	ds_read_b128 v[26:29], v201
	ds_read_b128 v[30:33], v201 offset:1152
	v_mov_b32_e32 v87, v155
	v_lshl_add_u64 v[74:75], s[22:23], 0, v[86:87]
	v_mov_b32_e32 v85, v155
	s_waitcnt vmcnt(18) lgkmcnt(1)
	v_mov_b64_e32 v[62:63], v[184:185]
	v_mov_b64_e32 v[64:65], v[186:187]
	v_mov_b64_e32 v[58:59], v[208:209]
	v_mov_b64_e32 v[60:61], v[210:211]
	v_mov_b64_e32 v[54:55], v[212:213]
	v_mov_b64_e32 v[56:57], v[214:215]
	v_mov_b64_e32 v[50:51], v[216:217]
	v_mov_b64_e32 v[52:53], v[218:219]
	v_pk_fma_f32 v[26:27], v[180:181], v[26:27], v[62:63]
	s_waitcnt lgkmcnt(0)
	v_pk_fma_f32 v[30:31], v[180:181], v[30:31], v[58:59]
	v_pk_fma_f32 v[28:29], v[176:177], v[28:29], v[64:65]
	v_pk_mul_f32 v[62:63], v[178:179], v[26:27]
	v_pk_fma_f32 v[32:33], v[176:177], v[32:33], v[60:61]
	v_pk_mul_f32 v[58:59], v[178:179], v[30:31]
	global_store_dwordx4 v[72:73], v[26:29], off nt
	v_pk_mul_f32 v[64:65], v[174:175], v[28:29]
	v_cvt_pk_bf16_f32 v62, v62, v63
	v_pk_mul_f32 v[60:61], v[174:175], v[32:33]
	v_cvt_pk_bf16_f32 v63, v64, v65
	global_store_dwordx4 v[74:75], v[30:33], off nt
	v_cvt_pk_bf16_f32 v58, v58, v59
	v_cvt_pk_bf16_f32 v59, v60, v61
	ds_write_b128 v200, v[22:25]
	ds_write_b128 v200, v[18:21] offset:64
	ds_read_b128 v[18:21], v201
	ds_read_b128 v[22:25], v201 offset:1152
	v_lshl_add_u64 v[60:61], s[22:23], 0, v[84:85]
	v_mov_b32_e32 v83, v155
	v_lshl_add_u64 v[64:65], s[22:23], 0, v[82:83]
	s_waitcnt lgkmcnt(1)
	v_pk_fma_f32 v[18:19], v[168:169], v[18:19], v[54:55]
	v_pk_fma_f32 v[20:21], v[166:167], v[20:21], v[56:57]
	v_pk_mul_f32 v[56:57], v[172:173], v[18:19]
	global_store_dwordx4 v[60:61], v[18:21], off nt
	v_pk_mul_f32 v[54:55], v[170:171], v[20:21]
	v_cvt_pk_bf16_f32 v56, v56, v57
	s_waitcnt lgkmcnt(0)
	v_pk_fma_f32 v[22:23], v[168:169], v[22:23], v[50:51]
	v_cvt_pk_bf16_f32 v57, v54, v55
	ds_bpermute_b32 v50, v203, v56
	ds_bpermute_b32 v51, v203, v57
	v_pk_fma_f32 v[24:25], v[166:167], v[24:25], v[52:53]
	v_pk_mul_f32 v[52:53], v[172:173], v[22:23]
	v_pk_mul_f32 v[54:55], v[170:171], v[24:25]
	global_store_dwordx4 v[64:65], v[22:25], off nt
	v_cvt_pk_bf16_f32 v52, v52, v53
	v_cvt_pk_bf16_f32 v53, v54, v55
	v_add_u32_e32 v55, 0x50000, v202
	v_lshlrev_b32_e32 v54, 1, v55
	s_waitcnt lgkmcnt(0)
	v_add_u32_e32 v250, 0xfffff040, v54
	v_cndmask_b32_e64 v250, v54, v250, s[40:41]
	v_cndmask_b32_e64 v248, v62, v50, s[40:41]
	v_cndmask_b32_e64 v249, v63, v51, s[40:41]
	global_store_dwordx2 v250, v[248:249], s[20:21]
	v_cndmask_b32_e64 v246, v50, v62, s[40:41]
	v_cndmask_b32_e64 v247, v51, v63, s[40:41]
	s_waitcnt lgkmcnt(1)
	v_add_u32_e32 v50, 0x1040, v54
	v_cndmask_b32_e64 v50, v54, v50, s[38:39]
	global_store_dwordx2 v50, v[246:247], s[20:21]
	ds_bpermute_b32 v50, v203, v52
	s_waitcnt lgkmcnt(1)
	ds_bpermute_b32 v51, v203, v53
	v_add_u32_e32 v53, 0x54000, v202
	v_lshlrev_b32_e32 v52, 1, v53
	s_waitcnt lgkmcnt(0)
	v_add_u32_e32 v250, 0xfffff040, v52
	v_cndmask_b32_e64 v250, v52, v250, s[40:41]
	v_cndmask_b32_e64 v248, v58, v50, s[40:41]
	v_cndmask_b32_e64 v249, v59, v51, s[40:41]
	global_store_dwordx2 v250, v[248:249], s[20:21]
	v_cndmask_b32_e64 v246, v50, v58, s[40:41]
	v_cndmask_b32_e64 v247, v51, v59, s[40:41]
	v_mul_f32_e32 v19, v19, v19
	v_fmac_f32_e32 v19, v18, v18
	v_mul_f32_e32 v18, v21, v21
	v_mul_f32_e32 v29, v29, v29
	v_fmac_f32_e32 v18, v20, v20
	v_mul_f32_e32 v27, v27, v27
	v_fmac_f32_e32 v29, v28, v28
	v_mul_f32_e32 v28, v31, v31
	v_mul_f32_e32 v31, v33, v33
	v_add_f32_e32 v18, v19, v18
	v_mul_f32_e32 v19, v23, v23
	v_mul_f32_e32 v20, v25, v25
	v_fmac_f32_e32 v31, v32, v32
	v_fmac_f32_e32 v19, v22, v22
	v_fmac_f32_e32 v20, v24, v24
	v_fmac_f32_e32 v27, v26, v26
	v_fmac_f32_e32 v28, v30, v30
	v_add_f32_e32 v19, v19, v20
	v_add_f32_e32 v20, v27, v29
	v_add_f32_e32 v21, v28, v31
	v_add_f32_e32 v18, v20, v18
	v_add_f32_e32 v19, v21, v19
	ds_bpermute_b32 v20, v190, v18
	ds_bpermute_b32 v21, v190, v19
	s_waitcnt lgkmcnt(1)
	v_add_f32_e32 v18, v18, v20
	s_waitcnt lgkmcnt(0)
	v_add_f32_e32 v21, v19, v21
	ds_bpermute_b32 v20, v191, v18
	ds_bpermute_b32 v22, v191, v21
	s_waitcnt lgkmcnt(1)
	v_add_f32_e32 v18, v18, v20
	s_waitcnt lgkmcnt(0)
	v_add_f32_e32 v20, v21, v22
	ds_bpermute_b32 v19, v204, v18
	ds_bpermute_b32 v21, v204, v20
	v_add_u32_e32 v22, 0x1040, v52
	v_cndmask_b32_e64 v22, v52, v22, s[38:39]
	global_store_dwordx2 v22, v[246:247], s[20:21]
	s_and_saveexec_b64 s[16:17], s[42:43]
	s_cbranch_execz .LBB0_1668
	s_waitcnt lgkmcnt(1)
	v_add_f32_e32 v18, v18, v19
	s_waitcnt lgkmcnt(0)
	v_add_f32_e32 v19, v20, v21
	ds_write2_b32 v194, v18, v19 offset0:96 offset1:104
; #define LAS __attribute__((address_space(3)))
; #define ERN_EOFF(q, m) (eb + (unsigned)((((q) & 1) * HALF + (m) * 16) * DM + ERN_COL((q) >> 1)))
;     __device__ __forceinline__ void operator()(const f32x4 (&acc)[2][2][4][2], const Unit& u, int wr, int wc, int fr, int fq) const {
;     ...
;         for (int g = 0; g < 8; ++g) { const int ai = g >> 2, m = g & 3;
;             if (g + 1 < 8) ERN_LOADX(g + 1);
;             float sq0 = 0.f, sq1 = 0.f; u32x2 hw[2][2];
; #pragma unroll
;             for (int bj = 0; bj < 2; ++bj) {
;                 *(LAS f32x4*)(st + wr_off) = acc[ai][bj][m][0]; *(LAS f32x4*)(st + wr_off + 64) = acc[ai][bj][m][1];
;                 const f32x4 a0 = *(const LAS f32x4*)(st + rd_off), a1 = *(const LAS f32x4*)(st + rd_off + 8 * 144);
;                 { const f32x4 xv = xb[g & 1][bj][0] + gv[bj] * a0; __builtin_nontemporal_store(xv, (f32x4*)((char*)xo + 4u * ERN_EOFF(g, bj, 0)));
;                   sq0 += (xv.x * xv.x + xv.y * xv.y) + (xv.z * xv.z + xv.w * xv.w);
;                   const f32x4 hv = xv * gsn[bj]; hw[bj][0].x = cvt_pk_bf16(hv.x, hv.y); hw[bj][0].y = cvt_pk_bf16(hv.z, hv.w); }
;                 { const f32x4 xv = xb[g & 1][bj][1] + gv[bj] * a1; __builtin_nontemporal_store(xv, (f32x4*)((char*)xo + 4u * ERN_EOFF(g, bj, 1)));
;                   sq1 += (xv.x * xv.x + xv.y * xv.y) + (xv.z * xv.z + xv.w * xv.w);
;                   const f32x4 hv = xv * gsn[bj]; hw[bj][1].x = cvt_pk_bf16(hv.x, hv.y); hw[bj][1].y = cvt_pk_bf16(hv.z, hv.w); }
;             }
;             if (!NOH && !PLAIN) {
; #pragma unroll
;                 for (int rh = 0; rh < 2; ++rh) { u32x2 rv; rv.x = __shfl_xor(hw[1][rh].x, 8); rv.y = __shfl_xor(hw[1][rh].y, 8);
;                     const unsigned e0 = ERN_EOFF(g, 0, rh);
;                     const unsigned ee = odd ? (e0 - DM + 32) : e0, eo2 = odd ? e0 : (e0 + DM + 32);
;                     *(u32x2*)((char*)ho + 2u * ee) = odd ? rv : hw[0][rh];
;                     *(u32x2*)((char*)ho + 2u * eo2) = odd ? hw[0][rh] : rv; }
;             }
;             if (!PLAIN) { sq0 += __shfl_xor(sq0, 1); sq0 += __shfl_xor(sq0, 2); sq0 += __shfl_xor(sq0, 4);
;             sq1 += __shfl_xor(sq1, 1); sq1 += __shfl_xor(sq1, 2); sq1 += __shfl_xor(sq1, 4); }
;             if (!PLAIN && pc == 0) { sst[g * 16 + rr] = sq0; sst[g * 16 + 8 + rr] = sq1; }
.LBB0_1668:
	s_or_b64 exec, exec, s[16:17]
	ds_write_b128 v200, v[14:17]
	ds_write_b128 v200, v[10:13] offset:64
	ds_read_b128 v[10:13], v201
	ds_read_b128 v[14:17], v201 offset:1152
	s_waitcnt lgkmcnt(5)
	v_lshl_add_u64 v[18:19], s[22:23], 0, v[154:155]
	v_mov_b32_e32 v71, v155
	v_lshl_add_u64 v[22:23], s[22:23], 0, v[70:71]
	s_waitcnt vmcnt(14) lgkmcnt(1)
	v_mov_b64_e32 v[46:47], v[120:121]
	v_mov_b64_e32 v[48:49], v[122:123]
	v_mov_b64_e32 v[42:43], v[124:125]
	v_mov_b64_e32 v[44:45], v[126:127]
	v_mov_b64_e32 v[38:39], v[136:137]
	v_mov_b64_e32 v[40:41], v[138:139]
	v_mov_b64_e32 v[34:35], v[140:141]
	v_mov_b64_e32 v[36:37], v[142:143]
	v_pk_fma_f32 v[12:13], v[176:177], v[12:13], v[48:49]
	v_pk_fma_f32 v[10:11], v[180:181], v[10:11], v[46:47]
	global_store_dwordx4 v[18:19], v[10:13], off nt
	v_pk_mul_f32 v[18:19], v[174:175], v[12:13]
	v_pk_mul_f32 v[20:21], v[178:179], v[10:11]
	s_waitcnt lgkmcnt(0)
	v_pk_fma_f32 v[14:15], v[180:181], v[14:15], v[42:43]
	v_cvt_pk_bf16_f32 v20, v20, v21
	v_cvt_pk_bf16_f32 v21, v18, v19
	v_pk_fma_f32 v[16:17], v[176:177], v[16:17], v[44:45]
	v_pk_mul_f32 v[18:19], v[178:179], v[14:15]
	global_store_dwordx4 v[22:23], v[14:17], off nt
	v_pk_mul_f32 v[22:23], v[174:175], v[16:17]
	v_cvt_pk_bf16_f32 v18, v18, v19
	v_mov_b32_e32 v69, v155
	v_cvt_pk_bf16_f32 v19, v22, v23
	ds_write_b128 v200, v[6:9]
	ds_write_b128 v200, v[2:5] offset:64
	ds_read_b128 v[2:5], v201
	ds_read_b128 v[6:9], v201 offset:1152
	v_lshl_add_u64 v[22:23], s[22:23], 0, v[68:69]
	v_mov_b32_e32 v67, v155
	v_lshl_add_u64 v[24:25], s[22:23], 0, v[66:67]
	s_waitcnt lgkmcnt(1)
	v_pk_fma_f32 v[4:5], v[166:167], v[4:5], v[40:41]
	v_pk_fma_f32 v[2:3], v[168:169], v[2:3], v[38:39]
	global_store_dwordx4 v[22:23], v[2:5], off nt
	v_pk_mul_f32 v[22:23], v[170:171], v[4:5]
	v_pk_mul_f32 v[26:27], v[172:173], v[2:3]
	s_waitcnt lgkmcnt(0)
	v_pk_fma_f32 v[8:9], v[166:167], v[8:9], v[36:37]
	v_cvt_pk_bf16_f32 v28, v26, v27
	v_cvt_pk_bf16_f32 v23, v22, v23
	ds_bpermute_b32 v22, v203, v28
	ds_bpermute_b32 v23, v203, v23
	v_pk_fma_f32 v[6:7], v[168:169], v[6:7], v[34:35]
	global_store_dwordx4 v[24:25], v[6:9], off nt
	v_pk_mul_f32 v[26:27], v[170:171], v[8:9]
	v_pk_mul_f32 v[24:25], v[172:173], v[6:7]
	s_nop 0
	v_cvt_pk_bf16_f32 v24, v24, v25
	v_cvt_pk_bf16_f32 v25, v26, v27
	v_add_u32_e32 v27, 0x58000, v202
	v_lshlrev_b32_e32 v26, 1, v27
	s_waitcnt lgkmcnt(0)
	v_add_u32_e32 v250, 0xfffff040, v26
	v_cndmask_b32_e64 v250, v26, v250, s[40:41]
	v_cndmask_b32_e64 v248, v20, v22, s[40:41]
	v_cndmask_b32_e64 v249, v21, v23, s[40:41]
	global_store_dwordx2 v250, v[248:249], s[20:21]
	v_cndmask_b32_e64 v246, v22, v20, s[40:41]
	v_cndmask_b32_e64 v247, v23, v21, s[40:41]
	s_waitcnt lgkmcnt(1)
	v_add_u32_e32 v22, 0x1040, v26
	v_cndmask_b32_e64 v22, v26, v22, s[38:39]
	global_store_dwordx2 v22, v[246:247], s[20:21]
	ds_bpermute_b32 v20, v203, v24
	ds_bpermute_b32 v21, v203, v25
	s_waitcnt lgkmcnt(2)
	v_add_u32_e32 v23, 0x5c000, v202
	v_lshlrev_b32_e32 v22, 1, v23
	s_waitcnt lgkmcnt(0)
	v_add_u32_e32 v250, 0xfffff040, v22
	v_cndmask_b32_e64 v250, v22, v250, s[40:41]
	v_cndmask_b32_e64 v248, v18, v20, s[40:41]
	v_cndmask_b32_e64 v249, v19, v21, s[40:41]
	global_store_dwordx2 v250, v[248:249], s[20:21]
	v_cndmask_b32_e64 v246, v20, v18, s[40:41]
	v_cndmask_b32_e64 v247, v21, v19, s[40:41]
	v_mul_f32_e32 v3, v3, v3
	v_fmac_f32_e32 v3, v2, v2
	v_mul_f32_e32 v2, v5, v5
	v_mul_f32_e32 v13, v13, v13
	v_fmac_f32_e32 v2, v4, v4
	v_mul_f32_e32 v11, v11, v11
	v_fmac_f32_e32 v13, v12, v12
	v_mul_f32_e32 v12, v15, v15
	v_mul_f32_e32 v15, v17, v17
	v_add_f32_e32 v2, v3, v2
	v_mul_f32_e32 v3, v7, v7
	v_mul_f32_e32 v4, v9, v9
	v_fmac_f32_e32 v15, v16, v16
	v_fmac_f32_e32 v3, v6, v6
	v_fmac_f32_e32 v4, v8, v8
	v_fmac_f32_e32 v11, v10, v10
	v_fmac_f32_e32 v12, v14, v14
	v_add_f32_e32 v3, v3, v4
	v_add_f32_e32 v4, v11, v13
	v_add_f32_e32 v5, v12, v15
	v_add_f32_e32 v2, v4, v2
	v_add_f32_e32 v3, v5, v3
	ds_bpermute_b32 v4, v190, v2
	ds_bpermute_b32 v5, v190, v3
	s_waitcnt lgkmcnt(1)
	v_add_f32_e32 v2, v2, v4
	s_waitcnt lgkmcnt(0)
	v_add_f32_e32 v5, v3, v5
	ds_bpermute_b32 v4, v191, v2
	ds_bpermute_b32 v6, v191, v5
	s_waitcnt lgkmcnt(1)
	v_add_f32_e32 v2, v2, v4
	s_waitcnt lgkmcnt(0)
	v_add_f32_e32 v4, v5, v6
	ds_bpermute_b32 v3, v204, v2
	ds_bpermute_b32 v5, v204, v4
	v_add_u32_e32 v6, 0x1040, v22
	v_cndmask_b32_e64 v6, v22, v6, s[38:39]
	global_store_dwordx2 v6, v[246:247], s[20:21]
	s_and_saveexec_b64 s[16:17], s[42:43]
	s_cbranch_execz .LBB0_1678
	s_waitcnt lgkmcnt(1)
	v_add_f32_e32 v2, v2, v3
	s_waitcnt lgkmcnt(0)
	v_add_f32_e32 v3, v4, v5
	ds_write2_b32 v194, v2, v3 offset0:112 offset1:120

; #define LAS __attribute__((address_space(3)))
; #define ERN_EOFF(q, m) (eb + (unsigned)((((q) & 1) * HALF + (m) * 16) * DM + ERN_COL((q) >> 1)))
;     __device__ __forceinline__ void operator()(const f32x4 (&acc)[2][2][4][2], const Unit& u, int wr, int wc, int fr, int fq) const {
;     ...
;         ERN_LOADX(0);
; #pragma unroll
;         for (int g = 0; g < 8; ++g) { const int ai = g >> 2, m = g & 3;
;             if (g + 1 < 8) ERN_LOADX(g + 1);
;             float sq0 = 0.f, sq1 = 0.f; u32x2 hw[2][2];
; #pragma unroll
;             for (int bj = 0; bj < 2; ++bj) {
;                 *(LAS f32x4*)(st + wr_off) = acc[ai][bj][m][0]; *(LAS f32x4*)(st + wr_off + 64) = acc[ai][bj][m][1];
;                 const f32x4 a0 = *(const LAS f32x4*)(st + rd_off), a1 = *(const LAS f32x4*)(st + rd_off + 8 * 144);
;                 { const f32x4 xv = xb[g & 1][bj][0] + gv[bj] * a0; __builtin_nontemporal_store(xv, (f32x4*)((char*)xo + 4u * ERN_EOFF(g, bj, 0)));
;                   sq0 += (xv.x * xv.x + xv.y * xv.y) + (xv.z * xv.z + xv.w * xv.w);
;                   const f32x4 hv = xv * gsn[bj]; hw[bj][0].x = cvt_pk_bf16(hv.x, hv.y); hw[bj][0].y = cvt_pk_bf16(hv.z, hv.w); }
;                 { const f32x4 xv = xb[g & 1][bj][1] + gv[bj] * a1; __builtin_nontemporal_store(xv, (f32x4*)((char*)xo + 4u * ERN_EOFF(g, bj, 1)));
;                   sq1 += (xv.x * xv.x + xv.y * xv.y) + (xv.z * xv.z + xv.w * xv.w);
;                   const f32x4 hv = xv * gsn[bj]; hw[bj][1].x = cvt_pk_bf16(hv.x, hv.y); hw[bj][1].y = cvt_pk_bf16(hv.z, hv.w); }
;             }
;             if (!NOH && !PLAIN) {
; #pragma unroll
;                 for (int rh = 0; rh < 2; ++rh) { u32x2 rv; rv.x = __shfl_xor(hw[1][rh].x, 8); rv.y = __shfl_xor(hw[1][rh].y, 8);
;                     const unsigned e0 = ERN_EOFF(g, 0, rh);
;                     const unsigned ee = odd ? (e0 - DM + 32) : e0, eo2 = odd ? e0 : (e0 + DM + 32);
;                     *(u32x2*)((char*)ho + 2u * ee) = odd ? rv : hw[0][rh];
;                     *(u32x2*)((char*)ho + 2u * eo2) = odd ? hw[0][rh] : rv; }
;             }
;             if (!PLAIN) { sq0 += __shfl_xor(sq0, 1); sq0 += __shfl_xor(sq0, 2); sq0 += __shfl_xor(sq0, 4);
;             sq1 += __shfl_xor(sq1, 1); sq1 += __shfl_xor(sq1, 2); sq1 += __shfl_xor(sq1, 4); }
;             if (!PLAIN && pc == 0) { sst[g * 16 + rr] = sq0; sst[g * 16 + 8 + rr] = sq1; }
.LBB0_1959:
	s_or_b64 exec, exec, s[22:23]
	v_lshl_add_u64 v[116:117], s[20:21], 0, v[154:155]
	v_add_u32_e32 v82, 0x100000, v205
	s_waitcnt lgkmcnt(1)
	v_add_u32_e32 v83, 0x110000, v205
	v_add_u32_e32 v154, 0x100080, v205
	global_load_dwordx4 v[94:97], v82, s[20:21]
	global_load_dwordx4 v[90:93], v83, s[20:21]
	v_add_u32_e32 v114, 0x110080, v205
	global_load_dwordx4 v[86:89], v154, s[20:21]
	s_waitcnt lgkmcnt(0)
	global_load_dwordx4 v[82:85], v114, s[20:21]
	v_add_u32_e32 v128, 0x120000, v205
	global_load_dwordx4 v[120:123], v128, s[20:21]
	v_add_u32_e32 v129, 0x130000, v205
	global_load_dwordx4 v[124:127], v129, s[20:21]
	v_add_u32_e32 v134, 0x120080, v205
	global_load_dwordx4 v[136:139], v134, s[20:21]
	v_add_u32_e32 v135, 0x130080, v205
	global_load_dwordx4 v[140:143], v135, s[20:21]
	ds_write_b128 v200, v[78:81]
	ds_write_b128 v200, v[74:77] offset:64
	ds_read_b128 v[74:77], v201
	ds_read_b128 v[78:81], v201 offset:1152
	v_mov_b32_e32 v131, v155
	v_mov_b32_e32 v133, v155
	s_waitcnt vmcnt(15) lgkmcnt(1)
	v_pk_fma_f32 v[76:77], v[176:177], v[76:77], v[112:113]
	v_add_u32_e32 v112, 0x18000, v202
	v_pk_fma_f32 v[74:75], v[180:181], v[74:75], v[110:111]
	v_lshlrev_b32_e32 v110, 2, v112
	s_waitcnt lgkmcnt(0)
	v_pk_fma_f32 v[78:79], v[180:181], v[78:79], v[106:107]
	global_store_dwordx4 v110, v[74:77], s[20:21] nt
	v_pk_mul_f32 v[110:111], v[178:179], v[74:75]
	v_pk_fma_f32 v[80:81], v[176:177], v[80:81], v[108:109]
	v_pk_mul_f32 v[106:107], v[178:179], v[78:79]
	v_pk_mul_f32 v[118:119], v[174:175], v[76:77]
	v_cvt_pk_bf16_f32 v110, v110, v111
	v_pk_mul_f32 v[108:109], v[174:175], v[80:81]
	v_cvt_pk_bf16_f32 v111, v118, v119
	global_store_dwordx4 v[116:117], v[78:81], off nt
	v_cvt_pk_bf16_f32 v106, v106, v107
	v_cvt_pk_bf16_f32 v107, v108, v109
	ds_write_b128 v200, v[70:73]
	ds_write_b128 v200, v[66:69] offset:64
	ds_read_b128 v[66:69], v201
	ds_read_b128 v[70:73], v201 offset:1152
	v_lshl_add_u64 v[108:109], s[20:21], 0, v[130:131]
	v_lshl_add_u64 v[116:117], s[20:21], 0, v[132:133]
	s_waitcnt lgkmcnt(1)
	v_pk_fma_f32 v[66:67], v[168:169], v[66:67], v[102:103]
	v_pk_fma_f32 v[68:69], v[166:167], v[68:69], v[104:105]
	v_pk_mul_f32 v[104:105], v[172:173], v[66:67]
	global_store_dwordx4 v[108:109], v[66:69], off nt
	v_pk_mul_f32 v[102:103], v[170:171], v[68:69]
	v_cvt_pk_bf16_f32 v104, v104, v105
	s_waitcnt vmcnt(17) lgkmcnt(0)
	v_pk_fma_f32 v[70:71], v[168:169], v[70:71], v[98:99]
	v_cvt_pk_bf16_f32 v105, v102, v103
	ds_bpermute_b32 v98, v203, v104
	ds_bpermute_b32 v99, v203, v105
	v_pk_fma_f32 v[72:73], v[166:167], v[72:73], v[100:101]
	v_pk_mul_f32 v[100:101], v[172:173], v[70:71]
	v_pk_mul_f32 v[102:103], v[170:171], v[72:73]
	global_store_dwordx4 v[116:117], v[70:73], off nt
	v_cvt_pk_bf16_f32 v100, v100, v101
	v_cvt_pk_bf16_f32 v101, v102, v103
	v_lshlrev_b32_e32 v102, 1, v112
	s_waitcnt lgkmcnt(0)
	v_add_u32_e32 v250, 0xfffff040, v102
	v_cndmask_b32_e64 v250, v102, v250, s[40:41]
	v_cndmask_b32_e64 v248, v110, v98, s[40:41]
	v_cndmask_b32_e64 v249, v111, v99, s[40:41]
	global_store_dwordx2 v250, v[248:249], s[18:19]
	v_cndmask_b32_e64 v246, v98, v110, s[40:41]
	v_cndmask_b32_e64 v247, v99, v111, s[40:41]
	s_waitcnt lgkmcnt(1)
	v_add_u32_e32 v98, 0x1040, v102
	v_cndmask_b32_e64 v98, v102, v98, s[38:39]
	global_store_dwordx2 v98, v[246:247], s[18:19]
	ds_bpermute_b32 v98, v203, v100
	s_waitcnt lgkmcnt(1)
	ds_bpermute_b32 v99, v203, v101
	v_add_u32_e32 v101, 0x1c000, v202
	v_lshlrev_b32_e32 v100, 1, v101
	s_waitcnt lgkmcnt(0)
	v_add_u32_e32 v250, 0xfffff040, v100
	v_cndmask_b32_e64 v250, v100, v250, s[40:41]
	v_cndmask_b32_e64 v248, v106, v98, s[40:41]
	v_cndmask_b32_e64 v249, v107, v99, s[40:41]
	global_store_dwordx2 v250, v[248:249], s[18:19]
	v_cndmask_b32_e64 v246, v98, v106, s[40:41]
	v_cndmask_b32_e64 v247, v99, v107, s[40:41]
	v_mul_f32_e32 v67, v67, v67
	v_fmac_f32_e32 v67, v66, v66
	v_mul_f32_e32 v66, v69, v69
	v_mul_f32_e32 v77, v77, v77
	v_fmac_f32_e32 v66, v68, v68
	v_mul_f32_e32 v75, v75, v75
	v_fmac_f32_e32 v77, v76, v76
	v_mul_f32_e32 v76, v79, v79
	v_mul_f32_e32 v79, v81, v81
	v_add_f32_e32 v66, v67, v66
	v_mul_f32_e32 v67, v71, v71
	v_mul_f32_e32 v68, v73, v73
	v_fmac_f32_e32 v79, v80, v80
	v_fmac_f32_e32 v67, v70, v70
	v_fmac_f32_e32 v68, v72, v72
	v_fmac_f32_e32 v75, v74, v74
	v_fmac_f32_e32 v76, v78, v78
	v_add_f32_e32 v67, v67, v68
	v_add_f32_e32 v68, v75, v77
	v_add_f32_e32 v69, v76, v79
	v_add_f32_e32 v66, v68, v66
	v_add_f32_e32 v67, v69, v67
	ds_bpermute_b32 v68, v190, v66
	ds_bpermute_b32 v69, v190, v67
	s_waitcnt lgkmcnt(1)
	v_add_f32_e32 v66, v66, v68
	s_waitcnt lgkmcnt(0)
	v_add_f32_e32 v69, v67, v69
	ds_bpermute_b32 v68, v191, v66
	ds_bpermute_b32 v70, v191, v69
	s_waitcnt lgkmcnt(1)
	v_add_f32_e32 v66, v66, v68
	s_waitcnt lgkmcnt(0)
	v_add_f32_e32 v68, v69, v70
	ds_bpermute_b32 v67, v204, v66
	ds_bpermute_b32 v69, v204, v68
	v_add_u32_e32 v70, 0x1040, v100
	v_cndmask_b32_e64 v70, v100, v70, s[38:39]
	global_store_dwordx2 v70, v[246:247], s[18:19]
	s_and_saveexec_b64 s[22:23], s[42:43]
	s_cbranch_execz .LBB0_1969
	s_waitcnt lgkmcnt(1)
	v_add_f32_e32 v66, v66, v67
	s_waitcnt lgkmcnt(0)
	v_add_f32_e32 v67, v68, v69
	ds_write2_b32 v194, v66, v67 offset0:48 offset1:56
; #define LAS __attribute__((address_space(3)))
; #define ERN_EOFF(q, m) (eb + (unsigned)((((q) & 1) * HALF + (m) * 16) * DM + ERN_COL((q) >> 1)))
;     __device__ __forceinline__ void operator()(const f32x4 (&acc)[2][2][4][2], const Unit& u, int wr, int wc, int fr, int fq) const {
;     ...
;         ERN_LOADX(0);
; #pragma unroll
;         for (int g = 0; g < 8; ++g) { const int ai = g >> 2, m = g & 3;
;             if (g + 1 < 8) ERN_LOADX(g + 1);
;             float sq0 = 0.f, sq1 = 0.f; u32x2 hw[2][2];
; #pragma unroll
;             for (int bj = 0; bj < 2; ++bj) {
;                 *(LAS f32x4*)(st + wr_off) = acc[ai][bj][m][0]; *(LAS f32x4*)(st + wr_off + 64) = acc[ai][bj][m][1];
;                 const f32x4 a0 = *(const LAS f32x4*)(st + rd_off), a1 = *(const LAS f32x4*)(st + rd_off + 8 * 144);
;                 { const f32x4 xv = xb[g & 1][bj][0] + gv[bj] * a0; __builtin_nontemporal_store(xv, (f32x4*)((char*)xo + 4u * ERN_EOFF(g, bj, 0)));
;                   sq0 += (xv.x * xv.x + xv.y * xv.y) + (xv.z * xv.z + xv.w * xv.w);
;                   const f32x4 hv = xv * gsn[bj]; hw[bj][0].x = cvt_pk_bf16(hv.x, hv.y); hw[bj][0].y = cvt_pk_bf16(hv.z, hv.w); }
;                 { const f32x4 xv = xb[g & 1][bj][1] + gv[bj] * a1; __builtin_nontemporal_store(xv, (f32x4*)((char*)xo + 4u * ERN_EOFF(g, bj, 1)));
;                   sq1 += (xv.x * xv.x + xv.y * xv.y) + (xv.z * xv.z + xv.w * xv.w);
;                   const f32x4 hv = xv * gsn[bj]; hw[bj][1].x = cvt_pk_bf16(hv.x, hv.y); hw[bj][1].y = cvt_pk_bf16(hv.z, hv.w); }
;             }
;             if (!NOH && !PLAIN) {
; #pragma unroll
;                 for (int rh = 0; rh < 2; ++rh) { u32x2 rv; rv.x = __shfl_xor(hw[1][rh].x, 8); rv.y = __shfl_xor(hw[1][rh].y, 8);
;                     const unsigned e0 = ERN_EOFF(g, 0, rh);
;                     const unsigned ee = odd ? (e0 - DM + 32) : e0, eo2 = odd ? e0 : (e0 + DM + 32);
;                     *(u32x2*)((char*)ho + 2u * ee) = odd ? rv : hw[0][rh];
;                     *(u32x2*)((char*)ho + 2u * eo2) = odd ? hw[0][rh] : rv; }
;             }
;             if (!PLAIN) { sq0 += __shfl_xor(sq0, 1); sq0 += __shfl_xor(sq0, 2); sq0 += __shfl_xor(sq0, 4);
;             sq1 += __shfl_xor(sq1, 1); sq1 += __shfl_xor(sq1, 2); sq1 += __shfl_xor(sq1, 4); }
;             if (!PLAIN && pc == 0) { sst[g * 16 + rr] = sq0; sst[g * 16 + 8 + rr] = sq1; }
.LBB0_1969:
	s_or_b64 exec, exec, s[22:23]
	v_lshl_add_u64 v[104:105], s[20:21], 0, v[154:155]
	v_add_u32_e32 v154, 0x120000, v205
	v_add_u32_e32 v100, 0x120080, v205
	v_add_u32_e32 v102, 0x130000, v205
	v_add_u32_e32 v98, 0x130080, v205
	s_waitcnt lgkmcnt(0)
	v_add_u32_e32 v128, 0x140000, v205
	global_load_dwordx4 v[184:187], v128, s[20:21]
	v_add_u32_e32 v129, 0x150000, v205
	global_load_dwordx4 v[208:211], v129, s[20:21]
	v_add_u32_e32 v134, 0x140080, v205
	global_load_dwordx4 v[212:215], v134, s[20:21]
	v_add_u32_e32 v135, 0x150080, v205
	global_load_dwordx4 v[216:219], v135, s[20:21]
	ds_write_b128 v200, v[62:65]
	ds_write_b128 v200, v[58:61] offset:64
	ds_read_b128 v[58:61], v201
	ds_read_b128 v[62:65], v201 offset:1152
	v_mov_b32_e32 v115, v155
	s_waitcnt vmcnt(17) lgkmcnt(1)
	v_pk_fma_f32 v[60:61], v[176:177], v[60:61], v[96:97]
	v_add_u32_e32 v96, 0x40000, v202
	v_pk_fma_f32 v[58:59], v[180:181], v[58:59], v[94:95]
	v_lshlrev_b32_e32 v94, 2, v96
	s_waitcnt vmcnt(16) lgkmcnt(0)
	v_pk_fma_f32 v[64:65], v[176:177], v[64:65], v[92:93]
	v_add_u32_e32 v92, 0x44000, v202
	global_store_dwordx4 v94, v[58:61], s[20:21] nt
	v_pk_mul_f32 v[94:95], v[178:179], v[58:59]
	v_pk_fma_f32 v[62:63], v[180:181], v[62:63], v[90:91]
	v_lshlrev_b32_e32 v90, 2, v92
	v_pk_mul_f32 v[106:107], v[174:175], v[60:61]
	v_cvt_pk_bf16_f32 v94, v94, v95
	s_nop 0
	v_cvt_pk_bf16_f32 v95, v106, v107
	global_store_dwordx4 v90, v[62:65], s[20:21] nt
	v_pk_mul_f32 v[90:91], v[178:179], v[62:63]
	v_pk_mul_f32 v[106:107], v[174:175], v[64:65]
	v_cvt_pk_bf16_f32 v90, v90, v91
	s_nop 0
	v_cvt_pk_bf16_f32 v91, v106, v107
	ds_write_b128 v200, v[54:57]
	ds_write_b128 v200, v[50:53] offset:64
	ds_read_b128 v[50:53], v201
	ds_read_b128 v[54:57], v201 offset:1152
	v_lshl_add_u64 v[106:107], s[20:21], 0, v[114:115]
	s_waitcnt vmcnt(17) lgkmcnt(1)
	v_pk_fma_f32 v[50:51], v[168:169], v[50:51], v[86:87]
	v_pk_fma_f32 v[52:53], v[166:167], v[52:53], v[88:89]
	v_pk_mul_f32 v[88:89], v[172:173], v[50:51]
	global_store_dwordx4 v[104:105], v[50:53], off nt
	v_pk_mul_f32 v[86:87], v[170:171], v[52:53]
	v_cvt_pk_bf16_f32 v88, v88, v89
	s_waitcnt vmcnt(17) lgkmcnt(0)
	v_pk_fma_f32 v[54:55], v[168:169], v[54:55], v[82:83]
	v_cvt_pk_bf16_f32 v89, v86, v87
	ds_bpermute_b32 v82, v203, v88
	ds_bpermute_b32 v83, v203, v89
	v_pk_fma_f32 v[56:57], v[166:167], v[56:57], v[84:85]
	v_pk_mul_f32 v[84:85], v[172:173], v[54:55]
	v_pk_mul_f32 v[86:87], v[170:171], v[56:57]
	global_store_dwordx4 v[106:107], v[54:57], off nt
	v_cvt_pk_bf16_f32 v84, v84, v85
	v_cvt_pk_bf16_f32 v85, v86, v87
	v_lshlrev_b32_e32 v86, 1, v96
	s_waitcnt lgkmcnt(0)
	v_add_u32_e32 v250, 0xfffff040, v86
	v_cndmask_b32_e64 v250, v86, v250, s[40:41]
	v_cndmask_b32_e64 v248, v94, v82, s[40:41]
	v_cndmask_b32_e64 v249, v95, v83, s[40:41]
	global_store_dwordx2 v250, v[248:249], s[18:19]
	v_cndmask_b32_e64 v246, v82, v94, s[40:41]
	v_cndmask_b32_e64 v247, v83, v95, s[40:41]
	s_waitcnt lgkmcnt(1)
	v_add_u32_e32 v82, 0x1040, v86
	v_cndmask_b32_e64 v82, v86, v82, s[38:39]
	global_store_dwordx2 v82, v[246:247], s[18:19]
	ds_bpermute_b32 v82, v203, v84
	s_waitcnt lgkmcnt(1)
	ds_bpermute_b32 v83, v203, v85
	v_lshlrev_b32_e32 v84, 1, v92
	s_waitcnt lgkmcnt(0)
	v_add_u32_e32 v250, 0xfffff040, v84
	v_cndmask_b32_e64 v250, v84, v250, s[40:41]
	v_cndmask_b32_e64 v248, v90, v82, s[40:41]
	v_cndmask_b32_e64 v249, v91, v83, s[40:41]
	global_store_dwordx2 v250, v[248:249], s[18:19]
	v_cndmask_b32_e64 v246, v82, v90, s[40:41]
	v_cndmask_b32_e64 v247, v83, v91, s[40:41]
	v_mul_f32_e32 v51, v51, v51
	v_fmac_f32_e32 v51, v50, v50
	v_mul_f32_e32 v50, v53, v53
	v_mul_f32_e32 v61, v61, v61
	v_fmac_f32_e32 v50, v52, v52
	v_mul_f32_e32 v59, v59, v59
	v_fmac_f32_e32 v61, v60, v60
	v_mul_f32_e32 v60, v63, v63
	v_mul_f32_e32 v63, v65, v65
	v_add_f32_e32 v50, v51, v50
	v_mul_f32_e32 v51, v55, v55
	v_mul_f32_e32 v52, v57, v57
	v_fmac_f32_e32 v63, v64, v64
	v_fmac_f32_e32 v51, v54, v54
	v_fmac_f32_e32 v52, v56, v56
	v_fmac_f32_e32 v59, v58, v58
	v_fmac_f32_e32 v60, v62, v62
	v_add_f32_e32 v51, v51, v52
	v_add_f32_e32 v52, v59, v61
	v_add_f32_e32 v53, v60, v63
	v_add_f32_e32 v50, v52, v50
	v_add_f32_e32 v51, v53, v51
	ds_bpermute_b32 v52, v190, v50
	ds_bpermute_b32 v53, v190, v51
	s_waitcnt lgkmcnt(1)
	v_add_f32_e32 v50, v50, v52
	s_waitcnt lgkmcnt(0)
	v_add_f32_e32 v53, v51, v53
	ds_bpermute_b32 v52, v191, v50
	ds_bpermute_b32 v54, v191, v53
	s_waitcnt lgkmcnt(1)
	v_add_f32_e32 v50, v50, v52
	s_waitcnt lgkmcnt(0)
	v_add_f32_e32 v52, v53, v54
	ds_bpermute_b32 v51, v204, v50
	ds_bpermute_b32 v53, v204, v52
	v_add_u32_e32 v54, 0x1040, v84
	v_cndmask_b32_e64 v54, v84, v54, s[38:39]
	global_store_dwordx2 v54, v[246:247], s[18:19]
	s_and_saveexec_b64 s[22:23], s[42:43]
	s_cbranch_execz .LBB0_1979
	s_waitcnt lgkmcnt(1)
	v_add_f32_e32 v50, v50, v51
	s_waitcnt lgkmcnt(0)
	v_add_f32_e32 v51, v52, v53
	ds_write2_b32 v194, v50, v51 offset0:64 offset1:72
; #define LAS __attribute__((address_space(3)))
; #define ERN_EOFF(q, m) (eb + (unsigned)((((q) & 1) * HALF + (m) * 16) * DM + ERN_COL((q) >> 1)))
;     __device__ __forceinline__ void operator()(const f32x4 (&acc)[2][2][4][2], const Unit& u, int wr, int wc, int fr, int fq) const {
;     ...
;         ERN_LOADX(0);
; #pragma unroll
;         for (int g = 0; g < 8; ++g) { const int ai = g >> 2, m = g & 3;
;             if (g + 1 < 8) ERN_LOADX(g + 1);
;             float sq0 = 0.f, sq1 = 0.f; u32x2 hw[2][2];
; #pragma unroll
;             for (int bj = 0; bj < 2; ++bj) {
;                 *(LAS f32x4*)(st + wr_off) = acc[ai][bj][m][0]; *(LAS f32x4*)(st + wr_off + 64) = acc[ai][bj][m][1];
;                 const f32x4 a0 = *(const LAS f32x4*)(st + rd_off), a1 = *(const LAS f32x4*)(st + rd_off + 8 * 144);
;                 { const f32x4 xv = xb[g & 1][bj][0] + gv[bj] * a0; __builtin_nontemporal_store(xv, (f32x4*)((char*)xo + 4u * ERN_EOFF(g, bj, 0)));
;                   sq0 += (xv.x * xv.x + xv.y * xv.y) + (xv.z * xv.z + xv.w * xv.w);
;                   const f32x4 hv = xv * gsn[bj]; hw[bj][0].x = cvt_pk_bf16(hv.x, hv.y); hw[bj][0].y = cvt_pk_bf16(hv.z, hv.w); }
;                 { const f32x4 xv = xb[g & 1][bj][1] + gv[bj] * a1; __builtin_nontemporal_store(xv, (f32x4*)((char*)xo + 4u * ERN_EOFF(g, bj, 1)));
;                   sq1 += (xv.x * xv.x + xv.y * xv.y) + (xv.z * xv.z + xv.w * xv.w);
;                   const f32x4 hv = xv * gsn[bj]; hw[bj][1].x = cvt_pk_bf16(hv.x, hv.y); hw[bj][1].y = cvt_pk_bf16(hv.z, hv.w); }
;             }
;             if (!NOH && !PLAIN) {
; #pragma unroll
;                 for (int rh = 0; rh < 2; ++rh) { u32x2 rv; rv.x = __shfl_xor(hw[1][rh].x, 8); rv.y = __shfl_xor(hw[1][rh].y, 8);
;                     const unsigned e0 = ERN_EOFF(g, 0, rh);
;                     const unsigned ee = odd ? (e0 - DM + 32) : e0, eo2 = odd ? e0 : (e0 + DM + 32);
;                     *(u32x2*)((char*)ho + 2u * ee) = odd ? rv : hw[0][rh];
;                     *(u32x2*)((char*)ho + 2u * eo2) = odd ? hw[0][rh] : rv; }
;             }
;             if (!PLAIN) { sq0 += __shfl_xor(sq0, 1); sq0 += __shfl_xor(sq0, 2); sq0 += __shfl_xor(sq0, 4);
;             sq1 += __shfl_xor(sq1, 1); sq1 += __shfl_xor(sq1, 2); sq1 += __shfl_xor(sq1, 4); }
;             if (!PLAIN && pc == 0) { sst[g * 16 + rr] = sq0; sst[g * 16 + 8 + rr] = sq1; }
.LBB0_1979:
	s_or_b64 exec, exec, s[22:23]
	v_lshl_add_u64 v[88:89], s[20:21], 0, v[154:155]
	v_add_u32_e32 v154, 0x140000, v205
	v_add_u32_e32 v84, 0x140080, v205
	v_add_u32_e32 v86, 0x150000, v205
	v_add_u32_e32 v82, 0x150080, v205
	s_waitcnt lgkmcnt(0)
	ds_write_b128 v200, v[46:49]
	ds_write_b128 v200, v[42:45] offset:64
	ds_read_b128 v[42:45], v201
	ds_read_b128 v[46:49], v201 offset:1152
	v_mov_b32_e32 v103, v155
	v_lshl_add_u64 v[90:91], s[20:21], 0, v[102:103]
	v_mov_b32_e32 v101, v155
	s_waitcnt vmcnt(18) lgkmcnt(1)
	v_mov_b64_e32 v[78:79], v[120:121]
	v_mov_b64_e32 v[80:81], v[122:123]
	v_mov_b64_e32 v[74:75], v[124:125]
	v_mov_b64_e32 v[76:77], v[126:127]
	v_mov_b64_e32 v[70:71], v[136:137]
	v_mov_b64_e32 v[72:73], v[138:139]
	v_mov_b64_e32 v[66:67], v[140:141]
	v_mov_b64_e32 v[68:69], v[142:143]
	v_add_u32_e32 v128, 0x160000, v205
	global_load_dwordx4 v[120:123], v128, s[20:21]
	v_add_u32_e32 v129, 0x170000, v205
	global_load_dwordx4 v[124:127], v129, s[20:21]
	v_add_u32_e32 v134, 0x160080, v205
	global_load_dwordx4 v[136:139], v134, s[20:21]
	v_add_u32_e32 v135, 0x170080, v205
	global_load_dwordx4 v[140:143], v135, s[20:21]
	v_pk_fma_f32 v[42:43], v[180:181], v[42:43], v[78:79]
	s_waitcnt lgkmcnt(0)
	v_pk_fma_f32 v[46:47], v[180:181], v[46:47], v[74:75]
	v_pk_fma_f32 v[44:45], v[176:177], v[44:45], v[80:81]
	v_pk_mul_f32 v[78:79], v[178:179], v[42:43]
	v_pk_fma_f32 v[48:49], v[176:177], v[48:49], v[76:77]
	v_pk_mul_f32 v[74:75], v[178:179], v[46:47]
	global_store_dwordx4 v[88:89], v[42:45], off nt
	v_pk_mul_f32 v[80:81], v[174:175], v[44:45]
	v_cvt_pk_bf16_f32 v78, v78, v79
	v_pk_mul_f32 v[76:77], v[174:175], v[48:49]
	v_cvt_pk_bf16_f32 v79, v80, v81
	global_store_dwordx4 v[90:91], v[46:49], off nt
	v_cvt_pk_bf16_f32 v74, v74, v75
	v_cvt_pk_bf16_f32 v75, v76, v77
	ds_write_b128 v200, v[38:41]
	ds_write_b128 v200, v[34:37] offset:64
	ds_read_b128 v[34:37], v201
	ds_read_b128 v[38:41], v201 offset:1152
	v_lshl_add_u64 v[76:77], s[20:21], 0, v[100:101]
	v_mov_b32_e32 v99, v155
	v_lshl_add_u64 v[80:81], s[20:21], 0, v[98:99]
	s_waitcnt lgkmcnt(1)
	v_pk_fma_f32 v[34:35], v[168:169], v[34:35], v[70:71]
	v_pk_fma_f32 v[36:37], v[166:167], v[36:37], v[72:73]
	v_pk_mul_f32 v[72:73], v[172:173], v[34:35]
	global_store_dwordx4 v[76:77], v[34:37], off nt
	v_pk_mul_f32 v[70:71], v[170:171], v[36:37]
	v_cvt_pk_bf16_f32 v72, v72, v73
	s_waitcnt lgkmcnt(0)
	v_pk_fma_f32 v[38:39], v[168:169], v[38:39], v[66:67]
	v_cvt_pk_bf16_f32 v73, v70, v71
	ds_bpermute_b32 v66, v203, v72
	ds_bpermute_b32 v67, v203, v73
	v_pk_fma_f32 v[40:41], v[166:167], v[40:41], v[68:69]
	v_pk_mul_f32 v[68:69], v[172:173], v[38:39]
	v_pk_mul_f32 v[70:71], v[170:171], v[40:41]
	global_store_dwordx4 v[80:81], v[38:41], off nt
	v_cvt_pk_bf16_f32 v68, v68, v69
	v_cvt_pk_bf16_f32 v69, v70, v71
	v_add_u32_e32 v71, 0x48000, v202
	v_lshlrev_b32_e32 v70, 1, v71
	s_waitcnt lgkmcnt(0)
	v_add_u32_e32 v250, 0xfffff040, v70
	v_cndmask_b32_e64 v250, v70, v250, s[40:41]
	v_cndmask_b32_e64 v248, v78, v66, s[40:41]
	v_cndmask_b32_e64 v249, v79, v67, s[40:41]
	global_store_dwordx2 v250, v[248:249], s[18:19]
	v_cndmask_b32_e64 v246, v66, v78, s[40:41]
	v_cndmask_b32_e64 v247, v67, v79, s[40:41]
	s_waitcnt lgkmcnt(1)
	v_add_u32_e32 v66, 0x1040, v70
	v_cndmask_b32_e64 v66, v70, v66, s[38:39]
	global_store_dwordx2 v66, v[246:247], s[18:19]
	ds_bpermute_b32 v66, v203, v68
	s_waitcnt lgkmcnt(1)
	ds_bpermute_b32 v67, v203, v69
	v_add_u32_e32 v69, 0x4c000, v202
	v_lshlrev_b32_e32 v68, 1, v69
	s_waitcnt lgkmcnt(0)
	v_add_u32_e32 v250, 0xfffff040, v68
	v_cndmask_b32_e64 v250, v68, v250, s[40:41]
	v_cndmask_b32_e64 v248, v74, v66, s[40:41]
	v_cndmask_b32_e64 v249, v75, v67, s[40:41]
	global_store_dwordx2 v250, v[248:249], s[18:19]
	v_cndmask_b32_e64 v246, v66, v74, s[40:41]
	v_cndmask_b32_e64 v247, v67, v75, s[40:41]
	v_mul_f32_e32 v35, v35, v35
	v_fmac_f32_e32 v35, v34, v34
	v_mul_f32_e32 v34, v37, v37
	v_mul_f32_e32 v45, v45, v45
	v_fmac_f32_e32 v34, v36, v36
	v_mul_f32_e32 v43, v43, v43
	v_fmac_f32_e32 v45, v44, v44
	v_mul_f32_e32 v44, v47, v47
	v_mul_f32_e32 v47, v49, v49
	v_add_f32_e32 v34, v35, v34
	v_mul_f32_e32 v35, v39, v39
	v_mul_f32_e32 v36, v41, v41
	v_fmac_f32_e32 v47, v48, v48
	v_fmac_f32_e32 v35, v38, v38
	v_fmac_f32_e32 v36, v40, v40
	v_fmac_f32_e32 v43, v42, v42
	v_fmac_f32_e32 v44, v46, v46
	v_add_f32_e32 v35, v35, v36
	v_add_f32_e32 v36, v43, v45
	v_add_f32_e32 v37, v44, v47
	v_add_f32_e32 v34, v36, v34
	v_add_f32_e32 v35, v37, v35
	ds_bpermute_b32 v36, v190, v34
	ds_bpermute_b32 v37, v190, v35
	s_waitcnt lgkmcnt(1)
	v_add_f32_e32 v34, v34, v36
	s_waitcnt lgkmcnt(0)
	v_add_f32_e32 v37, v35, v37
	ds_bpermute_b32 v36, v191, v34
	ds_bpermute_b32 v38, v191, v37
	s_waitcnt lgkmcnt(1)
	v_add_f32_e32 v34, v34, v36
	s_waitcnt lgkmcnt(0)
	v_add_f32_e32 v36, v37, v38
	ds_bpermute_b32 v35, v204, v34
	ds_bpermute_b32 v37, v204, v36
	v_add_u32_e32 v38, 0x1040, v68
	v_cndmask_b32_e64 v38, v68, v38, s[38:39]
	global_store_dwordx2 v38, v[246:247], s[18:19]
	s_and_saveexec_b64 s[22:23], s[42:43]
	s_cbranch_execz .LBB0_1989
	s_waitcnt lgkmcnt(1)
	v_add_f32_e32 v34, v34, v35
	s_waitcnt lgkmcnt(0)
	v_add_f32_e32 v35, v36, v37
	ds_write2_b32 v194, v34, v35 offset0:80 offset1:88
; #define LAS __attribute__((address_space(3)))
; #define ERN_EOFF(q, m) (eb + (unsigned)((((q) & 1) * HALF + (m) * 16) * DM + ERN_COL((q) >> 1)))
;     __device__ __forceinline__ void operator()(const f32x4 (&acc)[2][2][4][2], const Unit& u, int wr, int wc, int fr, int fq) const {
;     ...
;         ERN_LOADX(0);
; #pragma unroll
;         for (int g = 0; g < 8; ++g) { const int ai = g >> 2, m = g & 3;
;             if (g + 1 < 8) ERN_LOADX(g + 1);
;             float sq0 = 0.f, sq1 = 0.f; u32x2 hw[2][2];
; #pragma unroll
;             for (int bj = 0; bj < 2; ++bj) {
;                 *(LAS f32x4*)(st + wr_off) = acc[ai][bj][m][0]; *(LAS f32x4*)(st + wr_off + 64) = acc[ai][bj][m][1];
;                 const f32x4 a0 = *(const LAS f32x4*)(st + rd_off), a1 = *(const LAS f32x4*)(st + rd_off + 8 * 144);
;                 { const f32x4 xv = xb[g & 1][bj][0] + gv[bj] * a0; __builtin_nontemporal_store(xv, (f32x4*)((char*)xo + 4u * ERN_EOFF(g, bj, 0)));
;                   sq0 += (xv.x * xv.x + xv.y * xv.y) + (xv.z * xv.z + xv.w * xv.w);
;                   const f32x4 hv = xv * gsn[bj]; hw[bj][0].x = cvt_pk_bf16(hv.x, hv.y); hw[bj][0].y = cvt_pk_bf16(hv.z, hv.w); }
;                 { const f32x4 xv = xb[g & 1][bj][1] + gv[bj] * a1; __builtin_nontemporal_store(xv, (f32x4*)((char*)xo + 4u * ERN_EOFF(g, bj, 1)));
;                   sq1 += (xv.x * xv.x + xv.y * xv.y) + (xv.z * xv.z + xv.w * xv.w);
;                   const f32x4 hv = xv * gsn[bj]; hw[bj][1].x = cvt_pk_bf16(hv.x, hv.y); hw[bj][1].y = cvt_pk_bf16(hv.z, hv.w); }
;             }
;             if (!NOH && !PLAIN) {
; #pragma unroll
;                 for (int rh = 0; rh < 2; ++rh) { u32x2 rv; rv.x = __shfl_xor(hw[1][rh].x, 8); rv.y = __shfl_xor(hw[1][rh].y, 8);
;                     const unsigned e0 = ERN_EOFF(g, 0, rh);
;                     const unsigned ee = odd ? (e0 - DM + 32) : e0, eo2 = odd ? e0 : (e0 + DM + 32);
;                     *(u32x2*)((char*)ho + 2u * ee) = odd ? rv : hw[0][rh];
;                     *(u32x2*)((char*)ho + 2u * eo2) = odd ? hw[0][rh] : rv; }
;             }
;             if (!PLAIN) { sq0 += __shfl_xor(sq0, 1); sq0 += __shfl_xor(sq0, 2); sq0 += __shfl_xor(sq0, 4);
;             sq1 += __shfl_xor(sq1, 1); sq1 += __shfl_xor(sq1, 2); sq1 += __shfl_xor(sq1, 4); }
;             if (!PLAIN && pc == 0) { sst[g * 16 + rr] = sq0; sst[g * 16 + 8 + rr] = sq1; }
.LBB0_1989:
	s_or_b64 exec, exec, s[22:23]
	v_lshl_add_u64 v[72:73], s[20:21], 0, v[154:155]
	v_add_u32_e32 v154, 0x160000, v205
	v_add_u32_e32 v68, 0x160080, v205
	v_add_u32_e32 v70, 0x170000, v205
	v_add_u32_e32 v66, 0x170080, v205
	s_waitcnt lgkmcnt(0)
	ds_write_b128 v200, v[30:33]
	ds_write_b128 v200, v[26:29] offset:64
	ds_read_b128 v[26:29], v201
	ds_read_b128 v[30:33], v201 offset:1152
	v_mov_b32_e32 v87, v155
	v_lshl_add_u64 v[74:75], s[20:21], 0, v[86:87]
	v_mov_b32_e32 v85, v155
	s_waitcnt vmcnt(18) lgkmcnt(1)
	v_mov_b64_e32 v[62:63], v[184:185]
	v_mov_b64_e32 v[64:65], v[186:187]
	v_mov_b64_e32 v[58:59], v[208:209]
	v_mov_b64_e32 v[60:61], v[210:211]
	v_mov_b64_e32 v[54:55], v[212:213]
	v_mov_b64_e32 v[56:57], v[214:215]
	v_mov_b64_e32 v[50:51], v[216:217]
	v_mov_b64_e32 v[52:53], v[218:219]
	v_pk_fma_f32 v[26:27], v[180:181], v[26:27], v[62:63]
	s_waitcnt lgkmcnt(0)
	v_pk_fma_f32 v[30:31], v[180:181], v[30:31], v[58:59]
	v_pk_fma_f32 v[28:29], v[176:177], v[28:29], v[64:65]
	v_pk_mul_f32 v[62:63], v[178:179], v[26:27]
	v_pk_fma_f32 v[32:33], v[176:177], v[32:33], v[60:61]
	v_pk_mul_f32 v[58:59], v[178:179], v[30:31]
	global_store_dwordx4 v[72:73], v[26:29], off nt
	v_pk_mul_f32 v[64:65], v[174:175], v[28:29]
	v_cvt_pk_bf16_f32 v62, v62, v63
	v_pk_mul_f32 v[60:61], v[174:175], v[32:33]
	v_cvt_pk_bf16_f32 v63, v64, v65
	global_store_dwordx4 v[74:75], v[30:33], off nt
	v_cvt_pk_bf16_f32 v58, v58, v59
	v_cvt_pk_bf16_f32 v59, v60, v61
	ds_write_b128 v200, v[22:25]
	ds_write_b128 v200, v[18:21] offset:64
	ds_read_b128 v[18:21], v201
	ds_read_b128 v[22:25], v201 offset:1152
	v_lshl_add_u64 v[60:61], s[20:21], 0, v[84:85]
	v_mov_b32_e32 v83, v155
	v_lshl_add_u64 v[64:65], s[20:21], 0, v[82:83]
	s_waitcnt lgkmcnt(1)
	v_pk_fma_f32 v[18:19], v[168:169], v[18:19], v[54:55]
	v_pk_fma_f32 v[20:21], v[166:167], v[20:21], v[56:57]
	v_pk_mul_f32 v[56:57], v[172:173], v[18:19]
	global_store_dwordx4 v[60:61], v[18:21], off nt
	v_pk_mul_f32 v[54:55], v[170:171], v[20:21]
	v_cvt_pk_bf16_f32 v56, v56, v57
	s_waitcnt lgkmcnt(0)
	v_pk_fma_f32 v[22:23], v[168:169], v[22:23], v[50:51]
	v_cvt_pk_bf16_f32 v57, v54, v55
	ds_bpermute_b32 v50, v203, v56
	ds_bpermute_b32 v51, v203, v57
	v_pk_fma_f32 v[24:25], v[166:167], v[24:25], v[52:53]
	v_pk_mul_f32 v[52:53], v[172:173], v[22:23]
	v_pk_mul_f32 v[54:55], v[170:171], v[24:25]
	global_store_dwordx4 v[64:65], v[22:25], off nt
	v_cvt_pk_bf16_f32 v52, v52, v53
	v_cvt_pk_bf16_f32 v53, v54, v55
	v_add_u32_e32 v55, 0x50000, v202
	v_lshlrev_b32_e32 v54, 1, v55
	s_waitcnt lgkmcnt(0)
	v_add_u32_e32 v250, 0xfffff040, v54
	v_cndmask_b32_e64 v250, v54, v250, s[40:41]
	v_cndmask_b32_e64 v248, v62, v50, s[40:41]
	v_cndmask_b32_e64 v249, v63, v51, s[40:41]
	global_store_dwordx2 v250, v[248:249], s[18:19]
	v_cndmask_b32_e64 v246, v50, v62, s[40:41]
	v_cndmask_b32_e64 v247, v51, v63, s[40:41]
	s_waitcnt lgkmcnt(1)
	v_add_u32_e32 v50, 0x1040, v54
	v_cndmask_b32_e64 v50, v54, v50, s[38:39]
	global_store_dwordx2 v50, v[246:247], s[18:19]
	ds_bpermute_b32 v50, v203, v52
	s_waitcnt lgkmcnt(1)
	ds_bpermute_b32 v51, v203, v53
	v_add_u32_e32 v53, 0x54000, v202
	v_lshlrev_b32_e32 v52, 1, v53
	s_waitcnt lgkmcnt(0)
	v_add_u32_e32 v250, 0xfffff040, v52
	v_cndmask_b32_e64 v250, v52, v250, s[40:41]
	v_cndmask_b32_e64 v248, v58, v50, s[40:41]
	v_cndmask_b32_e64 v249, v59, v51, s[40:41]
	global_store_dwordx2 v250, v[248:249], s[18:19]
	v_cndmask_b32_e64 v246, v50, v58, s[40:41]
	v_cndmask_b32_e64 v247, v51, v59, s[40:41]
	v_mul_f32_e32 v19, v19, v19
	v_fmac_f32_e32 v19, v18, v18
	v_mul_f32_e32 v18, v21, v21
	v_mul_f32_e32 v29, v29, v29
	v_fmac_f32_e32 v18, v20, v20
	v_mul_f32_e32 v27, v27, v27
	v_fmac_f32_e32 v29, v28, v28
	v_mul_f32_e32 v28, v31, v31
	v_mul_f32_e32 v31, v33, v33
	v_add_f32_e32 v18, v19, v18
	v_mul_f32_e32 v19, v23, v23
	v_mul_f32_e32 v20, v25, v25
	v_fmac_f32_e32 v31, v32, v32
	v_fmac_f32_e32 v19, v22, v22
	v_fmac_f32_e32 v20, v24, v24
	v_fmac_f32_e32 v27, v26, v26
	v_fmac_f32_e32 v28, v30, v30
	v_add_f32_e32 v19, v19, v20
	v_add_f32_e32 v20, v27, v29
	v_add_f32_e32 v21, v28, v31
	v_add_f32_e32 v18, v20, v18
	v_add_f32_e32 v19, v21, v19
	ds_bpermute_b32 v20, v190, v18
	ds_bpermute_b32 v21, v190, v19
	s_waitcnt lgkmcnt(1)
	v_add_f32_e32 v18, v18, v20
	s_waitcnt lgkmcnt(0)
	v_add_f32_e32 v21, v19, v21
	ds_bpermute_b32 v20, v191, v18
	ds_bpermute_b32 v22, v191, v21
	s_waitcnt lgkmcnt(1)
	v_add_f32_e32 v18, v18, v20
	s_waitcnt lgkmcnt(0)
	v_add_f32_e32 v20, v21, v22
	ds_bpermute_b32 v19, v204, v18
	ds_bpermute_b32 v21, v204, v20
	v_add_u32_e32 v22, 0x1040, v52
	v_cndmask_b32_e64 v22, v52, v22, s[38:39]
	global_store_dwordx2 v22, v[246:247], s[18:19]
	s_and_saveexec_b64 s[22:23], s[42:43]
	s_cbranch_execz .LBB0_1999
	s_waitcnt lgkmcnt(1)
	v_add_f32_e32 v18, v18, v19
	s_waitcnt lgkmcnt(0)
	v_add_f32_e32 v19, v20, v21
	ds_write2_b32 v194, v18, v19 offset0:96 offset1:104
; #define LAS __attribute__((address_space(3)))
; #define ERN_EOFF(q, m) (eb + (unsigned)((((q) & 1) * HALF + (m) * 16) * DM + ERN_COL((q) >> 1)))
;     __device__ __forceinline__ void operator()(const f32x4 (&acc)[2][2][4][2], const Unit& u, int wr, int wc, int fr, int fq) const {
;     ...
;         for (int g = 0; g < 8; ++g) { const int ai = g >> 2, m = g & 3;
;             if (g + 1 < 8) ERN_LOADX(g + 1);
;             float sq0 = 0.f, sq1 = 0.f; u32x2 hw[2][2];
; #pragma unroll
;             for (int bj = 0; bj < 2; ++bj) {
;                 *(LAS f32x4*)(st + wr_off) = acc[ai][bj][m][0]; *(LAS f32x4*)(st + wr_off + 64) = acc[ai][bj][m][1];
;                 const f32x4 a0 = *(const LAS f32x4*)(st + rd_off), a1 = *(const LAS f32x4*)(st + rd_off + 8 * 144);
;                 { const f32x4 xv = xb[g & 1][bj][0] + gv[bj] * a0; __builtin_nontemporal_store(xv, (f32x4*)((char*)xo + 4u * ERN_EOFF(g, bj, 0)));
;                   sq0 += (xv.x * xv.x + xv.y * xv.y) + (xv.z * xv.z + xv.w * xv.w);
;                   const f32x4 hv = xv * gsn[bj]; hw[bj][0].x = cvt_pk_bf16(hv.x, hv.y); hw[bj][0].y = cvt_pk_bf16(hv.z, hv.w); }
;                 { const f32x4 xv = xb[g & 1][bj][1] + gv[bj] * a1; __builtin_nontemporal_store(xv, (f32x4*)((char*)xo + 4u * ERN_EOFF(g, bj, 1)));
;                   sq1 += (xv.x * xv.x + xv.y * xv.y) + (xv.z * xv.z + xv.w * xv.w);
;                   const f32x4 hv = xv * gsn[bj]; hw[bj][1].x = cvt_pk_bf16(hv.x, hv.y); hw[bj][1].y = cvt_pk_bf16(hv.z, hv.w); }
;             }
;             if (!NOH && !PLAIN) {
; #pragma unroll
;                 for (int rh = 0; rh < 2; ++rh) { u32x2 rv; rv.x = __shfl_xor(hw[1][rh].x, 8); rv.y = __shfl_xor(hw[1][rh].y, 8);
;                     const unsigned e0 = ERN_EOFF(g, 0, rh);
;                     const unsigned ee = odd ? (e0 - DM + 32) : e0, eo2 = odd ? e0 : (e0 + DM + 32);
;                     *(u32x2*)((char*)ho + 2u * ee) = odd ? rv : hw[0][rh];
;                     *(u32x2*)((char*)ho + 2u * eo2) = odd ? hw[0][rh] : rv; }
;             }
;             if (!PLAIN) { sq0 += __shfl_xor(sq0, 1); sq0 += __shfl_xor(sq0, 2); sq0 += __shfl_xor(sq0, 4);
;             sq1 += __shfl_xor(sq1, 1); sq1 += __shfl_xor(sq1, 2); sq1 += __shfl_xor(sq1, 4); }
;             if (!PLAIN && pc == 0) { sst[g * 16 + rr] = sq0; sst[g * 16 + 8 + rr] = sq1; }
.LBB0_1999:
	s_or_b64 exec, exec, s[22:23]
	ds_write_b128 v200, v[14:17]
	ds_write_b128 v200, v[10:13] offset:64
	ds_read_b128 v[10:13], v201
	ds_read_b128 v[14:17], v201 offset:1152
	s_waitcnt lgkmcnt(5)
	v_lshl_add_u64 v[18:19], s[20:21], 0, v[154:155]
	v_mov_b32_e32 v71, v155
	v_lshl_add_u64 v[22:23], s[20:21], 0, v[70:71]
	s_waitcnt vmcnt(14) lgkmcnt(1)
	v_mov_b64_e32 v[46:47], v[120:121]
	v_mov_b64_e32 v[48:49], v[122:123]
	v_mov_b64_e32 v[42:43], v[124:125]
	v_mov_b64_e32 v[44:45], v[126:127]
	v_mov_b64_e32 v[38:39], v[136:137]
	v_mov_b64_e32 v[40:41], v[138:139]
	v_mov_b64_e32 v[34:35], v[140:141]
	v_mov_b64_e32 v[36:37], v[142:143]
	v_pk_fma_f32 v[12:13], v[176:177], v[12:13], v[48:49]
	v_pk_fma_f32 v[10:11], v[180:181], v[10:11], v[46:47]
	global_store_dwordx4 v[18:19], v[10:13], off nt
	v_pk_mul_f32 v[18:19], v[174:175], v[12:13]
	v_pk_mul_f32 v[20:21], v[178:179], v[10:11]
	s_waitcnt lgkmcnt(0)
	v_pk_fma_f32 v[14:15], v[180:181], v[14:15], v[42:43]
	v_cvt_pk_bf16_f32 v20, v20, v21
	v_cvt_pk_bf16_f32 v21, v18, v19
	v_pk_fma_f32 v[16:17], v[176:177], v[16:17], v[44:45]
	v_pk_mul_f32 v[18:19], v[178:179], v[14:15]
	global_store_dwordx4 v[22:23], v[14:17], off nt
	v_pk_mul_f32 v[22:23], v[174:175], v[16:17]
	v_cvt_pk_bf16_f32 v18, v18, v19
	v_mov_b32_e32 v69, v155
	v_cvt_pk_bf16_f32 v19, v22, v23
	ds_write_b128 v200, v[6:9]
	ds_write_b128 v200, v[2:5] offset:64
	ds_read_b128 v[2:5], v201
	ds_read_b128 v[6:9], v201 offset:1152
	v_lshl_add_u64 v[22:23], s[20:21], 0, v[68:69]
	v_mov_b32_e32 v67, v155
	v_lshl_add_u64 v[24:25], s[20:21], 0, v[66:67]
	s_waitcnt lgkmcnt(1)
	v_pk_fma_f32 v[4:5], v[166:167], v[4:5], v[40:41]
	v_pk_fma_f32 v[2:3], v[168:169], v[2:3], v[38:39]
	global_store_dwordx4 v[22:23], v[2:5], off nt
	v_pk_mul_f32 v[22:23], v[170:171], v[4:5]
	v_pk_mul_f32 v[26:27], v[172:173], v[2:3]
	s_waitcnt lgkmcnt(0)
	v_pk_fma_f32 v[8:9], v[166:167], v[8:9], v[36:37]
	v_cvt_pk_bf16_f32 v28, v26, v27
	v_cvt_pk_bf16_f32 v23, v22, v23
	ds_bpermute_b32 v22, v203, v28
	ds_bpermute_b32 v23, v203, v23
	v_pk_fma_f32 v[6:7], v[168:169], v[6:7], v[34:35]
	global_store_dwordx4 v[24:25], v[6:9], off nt
	v_pk_mul_f32 v[26:27], v[170:171], v[8:9]
	v_pk_mul_f32 v[24:25], v[172:173], v[6:7]
	s_nop 0
	v_cvt_pk_bf16_f32 v24, v24, v25
	v_cvt_pk_bf16_f32 v25, v26, v27
	v_add_u32_e32 v27, 0x58000, v202
	v_lshlrev_b32_e32 v26, 1, v27
	s_waitcnt lgkmcnt(0)
	v_add_u32_e32 v250, 0xfffff040, v26
	v_cndmask_b32_e64 v250, v26, v250, s[40:41]
	v_cndmask_b32_e64 v248, v20, v22, s[40:41]
	v_cndmask_b32_e64 v249, v21, v23, s[40:41]
	global_store_dwordx2 v250, v[248:249], s[18:19]
	v_cndmask_b32_e64 v246, v22, v20, s[40:41]
	v_cndmask_b32_e64 v247, v23, v21, s[40:41]
	s_waitcnt lgkmcnt(1)
	v_add_u32_e32 v22, 0x1040, v26
	v_cndmask_b32_e64 v22, v26, v22, s[38:39]
	global_store_dwordx2 v22, v[246:247], s[18:19]
	ds_bpermute_b32 v20, v203, v24
	ds_bpermute_b32 v21, v203, v25
	s_waitcnt lgkmcnt(2)
	v_add_u32_e32 v23, 0x5c000, v202
	v_lshlrev_b32_e32 v22, 1, v23
	s_waitcnt lgkmcnt(0)
	v_add_u32_e32 v250, 0xfffff040, v22
	v_cndmask_b32_e64 v250, v22, v250, s[40:41]
	v_cndmask_b32_e64 v248, v18, v20, s[40:41]
	v_cndmask_b32_e64 v249, v19, v21, s[40:41]
	global_store_dwordx2 v250, v[248:249], s[18:19]
	v_cndmask_b32_e64 v246, v20, v18, s[40:41]
	v_cndmask_b32_e64 v247, v21, v19, s[40:41]
	v_mul_f32_e32 v3, v3, v3
	v_fmac_f32_e32 v3, v2, v2
	v_mul_f32_e32 v2, v5, v5
	v_mul_f32_e32 v13, v13, v13
	v_fmac_f32_e32 v2, v4, v4
	v_mul_f32_e32 v11, v11, v11
	v_fmac_f32_e32 v13, v12, v12
	v_mul_f32_e32 v12, v15, v15
	v_mul_f32_e32 v15, v17, v17
	v_add_f32_e32 v2, v3, v2
	v_mul_f32_e32 v3, v7, v7
	v_mul_f32_e32 v4, v9, v9
	v_fmac_f32_e32 v15, v16, v16
	v_fmac_f32_e32 v3, v6, v6
	v_fmac_f32_e32 v4, v8, v8
	v_fmac_f32_e32 v11, v10, v10
	v_fmac_f32_e32 v12, v14, v14
	v_add_f32_e32 v3, v3, v4
	v_add_f32_e32 v4, v11, v13
	v_add_f32_e32 v5, v12, v15
	v_add_f32_e32 v2, v4, v2
	v_add_f32_e32 v3, v5, v3
	ds_bpermute_b32 v4, v190, v2
	ds_bpermute_b32 v5, v190, v3
	s_waitcnt lgkmcnt(1)
	v_add_f32_e32 v2, v2, v4
	s_waitcnt lgkmcnt(0)
	v_add_f32_e32 v5, v3, v5
	ds_bpermute_b32 v4, v191, v2
	ds_bpermute_b32 v6, v191, v5
	s_waitcnt lgkmcnt(1)
	v_add_f32_e32 v2, v2, v4
	s_waitcnt lgkmcnt(0)
	v_add_f32_e32 v4, v5, v6
	ds_bpermute_b32 v3, v204, v2
	ds_bpermute_b32 v5, v204, v4
	v_add_u32_e32 v6, 0x1040, v22
	v_cndmask_b32_e64 v6, v22, v6, s[38:39]
	global_store_dwordx2 v6, v[246:247], s[18:19]
	s_and_saveexec_b64 s[18:19], s[42:43]
	s_cbranch_execz .LBB0_2009
	s_waitcnt lgkmcnt(1)
	v_add_f32_e32 v2, v2, v3
	s_waitcnt lgkmcnt(0)
	v_add_f32_e32 v3, v4, v5
	ds_write2_b32 v194, v2, v3 offset0:112 offset1:120

; #define LAS __attribute__((address_space(3)))
; #define ERN_EOFF(q, m) (eb + (unsigned)((((q) & 1) * HALF + (m) * 16) * DM + ERN_COL((q) >> 1)))
;     __device__ __forceinline__ void operator()(const f32x4 (&acc)[2][2][4][2], const Unit& u, int wr, int wc, int fr, int fq) const {
;     ...
;         ERN_LOADX(0);
; #pragma unroll
;         for (int g = 0; g < 8; ++g) { const int ai = g >> 2, m = g & 3;
;             if (g + 1 < 8) ERN_LOADX(g + 1);
;             float sq0 = 0.f, sq1 = 0.f; u32x2 hw[2][2];
; #pragma unroll
;             for (int bj = 0; bj < 2; ++bj) {
;                 *(LAS f32x4*)(st + wr_off) = acc[ai][bj][m][0]; *(LAS f32x4*)(st + wr_off + 64) = acc[ai][bj][m][1];
;                 const f32x4 a0 = *(const LAS f32x4*)(st + rd_off), a1 = *(const LAS f32x4*)(st + rd_off + 8 * 144);
;                 { const f32x4 xv = xb[g & 1][bj][0] + gv[bj] * a0; __builtin_nontemporal_store(xv, (f32x4*)((char*)xo + 4u * ERN_EOFF(g, bj, 0)));
;                   sq0 += (xv.x * xv.x + xv.y * xv.y) + (xv.z * xv.z + xv.w * xv.w);
;                   const f32x4 hv = xv * gsn[bj]; hw[bj][0].x = cvt_pk_bf16(hv.x, hv.y); hw[bj][0].y = cvt_pk_bf16(hv.z, hv.w); }
;                 { const f32x4 xv = xb[g & 1][bj][1] + gv[bj] * a1; __builtin_nontemporal_store(xv, (f32x4*)((char*)xo + 4u * ERN_EOFF(g, bj, 1)));
;                   sq1 += (xv.x * xv.x + xv.y * xv.y) + (xv.z * xv.z + xv.w * xv.w);
;                   const f32x4 hv = xv * gsn[bj]; hw[bj][1].x = cvt_pk_bf16(hv.x, hv.y); hw[bj][1].y = cvt_pk_bf16(hv.z, hv.w); }
;             }
;             if (!NOH && !PLAIN) {
; #pragma unroll
;                 for (int rh = 0; rh < 2; ++rh) { u32x2 rv; rv.x = __shfl_xor(hw[1][rh].x, 8); rv.y = __shfl_xor(hw[1][rh].y, 8);
;                     const unsigned e0 = ERN_EOFF(g, 0, rh);
;                     const unsigned ee = odd ? (e0 - DM + 32) : e0, eo2 = odd ? e0 : (e0 + DM + 32);
;                     *(u32x2*)((char*)ho + 2u * ee) = odd ? rv : hw[0][rh];
;                     *(u32x2*)((char*)ho + 2u * eo2) = odd ? hw[0][rh] : rv; }
;             }
;             if (!PLAIN) { sq0 += __shfl_xor(sq0, 1); sq0 += __shfl_xor(sq0, 2); sq0 += __shfl_xor(sq0, 4);
;             sq1 += __shfl_xor(sq1, 1); sq1 += __shfl_xor(sq1, 2); sq1 += __shfl_xor(sq1, 4); }
;             if (!PLAIN && pc == 0) { sst[g * 16 + rr] = sq0; sst[g * 16 + 8 + rr] = sq1; }
.LBB0_2799:
	s_or_b64 exec, exec, s[24:25]
	v_lshl_add_u64 v[124:125], s[22:23], 0, v[162:163]
	v_add_u32_e32 v90, 0x100000, v205
	s_waitcnt lgkmcnt(1)
	v_add_u32_e32 v91, 0x110000, v205
	v_add_u32_e32 v162, 0x100080, v205
	global_load_dwordx4 v[102:105], v90, s[22:23]
	global_load_dwordx4 v[98:101], v91, s[22:23]
	v_add_u32_e32 v122, 0x110080, v205
	global_load_dwordx4 v[94:97], v162, s[22:23]
	s_waitcnt lgkmcnt(0)
	global_load_dwordx4 v[90:93], v122, s[22:23]
	v_add_u32_e32 v136, 0x120000, v205
	global_load_dwordx4 v[128:131], v136, s[22:23]
	v_add_u32_e32 v137, 0x130000, v205
	global_load_dwordx4 v[132:135], v137, s[22:23]
	v_add_u32_e32 v142, 0x120080, v205
	global_load_dwordx4 v[144:147], v142, s[22:23]
	v_add_u32_e32 v143, 0x130080, v205
	global_load_dwordx4 v[148:151], v143, s[22:23]
	ds_write_b128 v200, v[86:89]
	ds_write_b128 v200, v[82:85] offset:64
	ds_read_b128 v[82:85], v201
	ds_read_b128 v[86:89], v201 offset:1152
	v_mov_b32_e32 v139, v163
	v_mov_b32_e32 v141, v163
	s_waitcnt vmcnt(15) lgkmcnt(1)
	v_pk_fma_f32 v[84:85], v[56:57], v[84:85], v[120:121]
	v_add_u32_e32 v120, 0x18000, v202
	v_pk_fma_f32 v[82:83], v[54:55], v[82:83], v[118:119]
	v_lshlrev_b32_e32 v118, 2, v120
	s_waitcnt lgkmcnt(0)
	v_pk_fma_f32 v[86:87], v[54:55], v[86:87], v[114:115]
	global_store_dwordx4 v118, v[82:85], s[22:23] nt
	v_pk_mul_f32 v[118:119], v[180:181], v[82:83]
	v_pk_fma_f32 v[88:89], v[56:57], v[88:89], v[116:117]
	v_pk_mul_f32 v[114:115], v[180:181], v[86:87]
	v_pk_mul_f32 v[126:127], v[178:179], v[84:85]
	v_cvt_pk_bf16_f32 v118, v118, v119
	v_pk_mul_f32 v[116:117], v[178:179], v[88:89]
	v_cvt_pk_bf16_f32 v119, v126, v127
	global_store_dwordx4 v[124:125], v[86:89], off nt
	v_cvt_pk_bf16_f32 v114, v114, v115
	v_cvt_pk_bf16_f32 v115, v116, v117
	ds_write_b128 v200, v[78:81]
	ds_write_b128 v200, v[74:77] offset:64
	ds_read_b128 v[74:77], v201
	ds_read_b128 v[78:81], v201 offset:1152
	v_lshl_add_u64 v[116:117], s[22:23], 0, v[138:139]
	v_lshl_add_u64 v[124:125], s[22:23], 0, v[140:141]
	s_waitcnt lgkmcnt(1)
	v_pk_fma_f32 v[74:75], v[50:51], v[74:75], v[110:111]
	v_pk_fma_f32 v[76:77], v[52:53], v[76:77], v[112:113]
	v_pk_mul_f32 v[112:113], v[176:177], v[74:75]
	global_store_dwordx4 v[116:117], v[74:77], off nt
	v_pk_mul_f32 v[110:111], v[174:175], v[76:77]
	v_cvt_pk_bf16_f32 v112, v112, v113
	s_waitcnt vmcnt(17) lgkmcnt(0)
	v_pk_fma_f32 v[78:79], v[50:51], v[78:79], v[106:107]
	v_cvt_pk_bf16_f32 v113, v110, v111
	ds_bpermute_b32 v106, v203, v112
	ds_bpermute_b32 v107, v203, v113
	v_pk_fma_f32 v[80:81], v[52:53], v[80:81], v[108:109]
	v_pk_mul_f32 v[108:109], v[176:177], v[78:79]
	v_pk_mul_f32 v[110:111], v[174:175], v[80:81]
	global_store_dwordx4 v[124:125], v[78:81], off nt
	v_cvt_pk_bf16_f32 v108, v108, v109
	v_cvt_pk_bf16_f32 v109, v110, v111
	v_lshlrev_b32_e32 v110, 1, v120
	s_waitcnt lgkmcnt(0)
	v_add_u32_e32 v250, 0xfffff040, v110
	v_cndmask_b32_e64 v250, v110, v250, s[38:39]
	v_cndmask_b32_e64 v248, v118, v106, s[38:39]
	v_cndmask_b32_e64 v249, v119, v107, s[38:39]
	global_store_dwordx2 v250, v[248:249], s[20:21]
	v_cndmask_b32_e64 v246, v106, v118, s[38:39]
	v_cndmask_b32_e64 v247, v107, v119, s[38:39]
	s_waitcnt lgkmcnt(1)
	v_add_u32_e32 v106, 0x1040, v110
	v_cndmask_b32_e64 v106, v110, v106, s[36:37]
	global_store_dwordx2 v106, v[246:247], s[20:21]
	ds_bpermute_b32 v106, v203, v108
	s_waitcnt lgkmcnt(1)
	ds_bpermute_b32 v107, v203, v109
	v_add_u32_e32 v109, 0x1c000, v202
	v_lshlrev_b32_e32 v108, 1, v109
	s_waitcnt lgkmcnt(0)
	v_add_u32_e32 v250, 0xfffff040, v108
	v_cndmask_b32_e64 v250, v108, v250, s[38:39]
	v_cndmask_b32_e64 v248, v114, v106, s[38:39]
	v_cndmask_b32_e64 v249, v115, v107, s[38:39]
	global_store_dwordx2 v250, v[248:249], s[20:21]
	v_cndmask_b32_e64 v246, v106, v114, s[38:39]
	v_cndmask_b32_e64 v247, v107, v115, s[38:39]
	v_mul_f32_e32 v75, v75, v75
	v_fmac_f32_e32 v75, v74, v74
	v_mul_f32_e32 v74, v77, v77
	v_mul_f32_e32 v85, v85, v85
	v_fmac_f32_e32 v74, v76, v76
	v_mul_f32_e32 v83, v83, v83
	v_fmac_f32_e32 v85, v84, v84
	v_mul_f32_e32 v84, v87, v87
	v_mul_f32_e32 v87, v89, v89
	v_add_f32_e32 v74, v75, v74
	v_mul_f32_e32 v75, v79, v79
	v_mul_f32_e32 v76, v81, v81
	v_fmac_f32_e32 v87, v88, v88
	v_fmac_f32_e32 v75, v78, v78
	v_fmac_f32_e32 v76, v80, v80
	v_fmac_f32_e32 v83, v82, v82
	v_fmac_f32_e32 v84, v86, v86
	v_add_f32_e32 v75, v75, v76
	v_add_f32_e32 v76, v83, v85
	v_add_f32_e32 v77, v84, v87
	v_add_f32_e32 v74, v76, v74
	v_add_f32_e32 v75, v77, v75
	ds_bpermute_b32 v76, v190, v74
	ds_bpermute_b32 v77, v190, v75
	s_waitcnt lgkmcnt(1)
	v_add_f32_e32 v74, v74, v76
	s_waitcnt lgkmcnt(0)
	v_add_f32_e32 v77, v75, v77
	ds_bpermute_b32 v76, v191, v74
	ds_bpermute_b32 v78, v191, v77
	s_waitcnt lgkmcnt(1)
	v_add_f32_e32 v74, v74, v76
	s_waitcnt lgkmcnt(0)
	v_add_f32_e32 v76, v77, v78
	ds_bpermute_b32 v75, v204, v74
	ds_bpermute_b32 v77, v204, v76
	v_add_u32_e32 v78, 0x1040, v108
	v_cndmask_b32_e64 v78, v108, v78, s[36:37]
	global_store_dwordx2 v78, v[246:247], s[20:21]
	s_and_saveexec_b64 s[24:25], s[40:41]
	s_cbranch_execz .LBB0_2809
	s_waitcnt lgkmcnt(1)
	v_add_f32_e32 v74, v74, v75
	s_waitcnt lgkmcnt(0)
	v_add_f32_e32 v75, v76, v77
	ds_write2_b32 v194, v74, v75 offset0:48 offset1:56
; #define LAS __attribute__((address_space(3)))
; #define ERN_EOFF(q, m) (eb + (unsigned)((((q) & 1) * HALF + (m) * 16) * DM + ERN_COL((q) >> 1)))
;     __device__ __forceinline__ void operator()(const f32x4 (&acc)[2][2][4][2], const Unit& u, int wr, int wc, int fr, int fq) const {
;     ...
;         ERN_LOADX(0);
; #pragma unroll
;         for (int g = 0; g < 8; ++g) { const int ai = g >> 2, m = g & 3;
;             if (g + 1 < 8) ERN_LOADX(g + 1);
;             float sq0 = 0.f, sq1 = 0.f; u32x2 hw[2][2];
; #pragma unroll
;             for (int bj = 0; bj < 2; ++bj) {
;                 *(LAS f32x4*)(st + wr_off) = acc[ai][bj][m][0]; *(LAS f32x4*)(st + wr_off + 64) = acc[ai][bj][m][1];
;                 const f32x4 a0 = *(const LAS f32x4*)(st + rd_off), a1 = *(const LAS f32x4*)(st + rd_off + 8 * 144);
;                 { const f32x4 xv = xb[g & 1][bj][0] + gv[bj] * a0; __builtin_nontemporal_store(xv, (f32x4*)((char*)xo + 4u * ERN_EOFF(g, bj, 0)));
;                   sq0 += (xv.x * xv.x + xv.y * xv.y) + (xv.z * xv.z + xv.w * xv.w);
;                   const f32x4 hv = xv * gsn[bj]; hw[bj][0].x = cvt_pk_bf16(hv.x, hv.y); hw[bj][0].y = cvt_pk_bf16(hv.z, hv.w); }
;                 { const f32x4 xv = xb[g & 1][bj][1] + gv[bj] * a1; __builtin_nontemporal_store(xv, (f32x4*)((char*)xo + 4u * ERN_EOFF(g, bj, 1)));
;                   sq1 += (xv.x * xv.x + xv.y * xv.y) + (xv.z * xv.z + xv.w * xv.w);
;                   const f32x4 hv = xv * gsn[bj]; hw[bj][1].x = cvt_pk_bf16(hv.x, hv.y); hw[bj][1].y = cvt_pk_bf16(hv.z, hv.w); }
;             }
;             if (!NOH && !PLAIN) {
; #pragma unroll
;                 for (int rh = 0; rh < 2; ++rh) { u32x2 rv; rv.x = __shfl_xor(hw[1][rh].x, 8); rv.y = __shfl_xor(hw[1][rh].y, 8);
;                     const unsigned e0 = ERN_EOFF(g, 0, rh);
;                     const unsigned ee = odd ? (e0 - DM + 32) : e0, eo2 = odd ? e0 : (e0 + DM + 32);
;                     *(u32x2*)((char*)ho + 2u * ee) = odd ? rv : hw[0][rh];
;                     *(u32x2*)((char*)ho + 2u * eo2) = odd ? hw[0][rh] : rv; }
;             }
;             if (!PLAIN) { sq0 += __shfl_xor(sq0, 1); sq0 += __shfl_xor(sq0, 2); sq0 += __shfl_xor(sq0, 4);
;             sq1 += __shfl_xor(sq1, 1); sq1 += __shfl_xor(sq1, 2); sq1 += __shfl_xor(sq1, 4); }
;             if (!PLAIN && pc == 0) { sst[g * 16 + rr] = sq0; sst[g * 16 + 8 + rr] = sq1; }
.LBB0_2809:
	s_or_b64 exec, exec, s[24:25]
	v_lshl_add_u64 v[112:113], s[22:23], 0, v[162:163]
	v_add_u32_e32 v162, 0x120000, v205
	v_add_u32_e32 v108, 0x120080, v205
	v_add_u32_e32 v110, 0x130000, v205
	v_add_u32_e32 v106, 0x130080, v205
	s_waitcnt lgkmcnt(0)
	v_add_u32_e32 v136, 0x140000, v205
	global_load_dwordx4 v[184:187], v136, s[22:23]
	v_add_u32_e32 v137, 0x150000, v205
	global_load_dwordx4 v[208:211], v137, s[22:23]
	v_add_u32_e32 v142, 0x140080, v205
	global_load_dwordx4 v[212:215], v142, s[22:23]
	v_add_u32_e32 v143, 0x150080, v205
	global_load_dwordx4 v[216:219], v143, s[22:23]
	ds_write_b128 v200, v[70:73]
	ds_write_b128 v200, v[66:69] offset:64
	ds_read_b128 v[66:69], v201
	ds_read_b128 v[70:73], v201 offset:1152
	v_mov_b32_e32 v123, v163
	s_waitcnt vmcnt(17) lgkmcnt(1)
	v_pk_fma_f32 v[68:69], v[56:57], v[68:69], v[104:105]
	v_add_u32_e32 v104, 0x40000, v202
	v_pk_fma_f32 v[66:67], v[54:55], v[66:67], v[102:103]
	v_lshlrev_b32_e32 v102, 2, v104
	s_waitcnt vmcnt(16) lgkmcnt(0)
	v_pk_fma_f32 v[72:73], v[56:57], v[72:73], v[100:101]
	v_add_u32_e32 v100, 0x44000, v202
	global_store_dwordx4 v102, v[66:69], s[22:23] nt
	v_pk_mul_f32 v[102:103], v[180:181], v[66:67]
	v_pk_fma_f32 v[70:71], v[54:55], v[70:71], v[98:99]
	v_lshlrev_b32_e32 v98, 2, v100
	v_pk_mul_f32 v[114:115], v[178:179], v[68:69]
	v_cvt_pk_bf16_f32 v102, v102, v103
	s_nop 0
	v_cvt_pk_bf16_f32 v103, v114, v115
	global_store_dwordx4 v98, v[70:73], s[22:23] nt
	v_pk_mul_f32 v[98:99], v[180:181], v[70:71]
	v_pk_mul_f32 v[114:115], v[178:179], v[72:73]
	v_cvt_pk_bf16_f32 v98, v98, v99
	s_nop 0
	v_cvt_pk_bf16_f32 v99, v114, v115
	ds_write_b128 v200, v[62:65]
	ds_write_b128 v200, v[58:61] offset:64
	ds_read_b128 v[58:61], v201
	ds_read_b128 v[62:65], v201 offset:1152
	v_lshl_add_u64 v[114:115], s[22:23], 0, v[122:123]
	s_waitcnt vmcnt(17) lgkmcnt(1)
	v_pk_fma_f32 v[58:59], v[50:51], v[58:59], v[94:95]
	v_pk_fma_f32 v[60:61], v[52:53], v[60:61], v[96:97]
	v_pk_mul_f32 v[96:97], v[176:177], v[58:59]
	global_store_dwordx4 v[112:113], v[58:61], off nt
	v_pk_mul_f32 v[94:95], v[174:175], v[60:61]
	v_cvt_pk_bf16_f32 v96, v96, v97
	s_waitcnt vmcnt(17) lgkmcnt(0)
	v_pk_fma_f32 v[62:63], v[50:51], v[62:63], v[90:91]
	v_cvt_pk_bf16_f32 v97, v94, v95
	ds_bpermute_b32 v90, v203, v96
	ds_bpermute_b32 v91, v203, v97
	v_pk_fma_f32 v[64:65], v[52:53], v[64:65], v[92:93]
	v_pk_mul_f32 v[92:93], v[176:177], v[62:63]
	v_pk_mul_f32 v[94:95], v[174:175], v[64:65]
	global_store_dwordx4 v[114:115], v[62:65], off nt
	v_cvt_pk_bf16_f32 v92, v92, v93
	v_cvt_pk_bf16_f32 v93, v94, v95
	v_lshlrev_b32_e32 v94, 1, v104
	s_waitcnt lgkmcnt(0)
	v_add_u32_e32 v250, 0xfffff040, v94
	v_cndmask_b32_e64 v250, v94, v250, s[38:39]
	v_cndmask_b32_e64 v248, v102, v90, s[38:39]
	v_cndmask_b32_e64 v249, v103, v91, s[38:39]
	global_store_dwordx2 v250, v[248:249], s[20:21]
	v_cndmask_b32_e64 v246, v90, v102, s[38:39]
	v_cndmask_b32_e64 v247, v91, v103, s[38:39]
	s_waitcnt lgkmcnt(1)
	v_add_u32_e32 v90, 0x1040, v94
	v_cndmask_b32_e64 v90, v94, v90, s[36:37]
	global_store_dwordx2 v90, v[246:247], s[20:21]
	ds_bpermute_b32 v90, v203, v92
	s_waitcnt lgkmcnt(1)
	ds_bpermute_b32 v91, v203, v93
	v_lshlrev_b32_e32 v92, 1, v100
	s_waitcnt lgkmcnt(0)
	v_add_u32_e32 v250, 0xfffff040, v92
	v_cndmask_b32_e64 v250, v92, v250, s[38:39]
	v_cndmask_b32_e64 v248, v98, v90, s[38:39]
	v_cndmask_b32_e64 v249, v99, v91, s[38:39]
	global_store_dwordx2 v250, v[248:249], s[20:21]
	v_cndmask_b32_e64 v246, v90, v98, s[38:39]
	v_cndmask_b32_e64 v247, v91, v99, s[38:39]
	v_mul_f32_e32 v59, v59, v59
	v_fmac_f32_e32 v59, v58, v58
	v_mul_f32_e32 v58, v61, v61
	v_mul_f32_e32 v69, v69, v69
	v_fmac_f32_e32 v58, v60, v60
	v_mul_f32_e32 v67, v67, v67
	v_fmac_f32_e32 v69, v68, v68
	v_mul_f32_e32 v68, v71, v71
	v_mul_f32_e32 v71, v73, v73
	v_add_f32_e32 v58, v59, v58
	v_mul_f32_e32 v59, v63, v63
	v_mul_f32_e32 v60, v65, v65
	v_fmac_f32_e32 v71, v72, v72
	v_fmac_f32_e32 v59, v62, v62
	v_fmac_f32_e32 v60, v64, v64
	v_fmac_f32_e32 v67, v66, v66
	v_fmac_f32_e32 v68, v70, v70
	v_add_f32_e32 v59, v59, v60
	v_add_f32_e32 v60, v67, v69
	v_add_f32_e32 v61, v68, v71
	v_add_f32_e32 v58, v60, v58
	v_add_f32_e32 v59, v61, v59
	ds_bpermute_b32 v60, v190, v58
	ds_bpermute_b32 v61, v190, v59
	s_waitcnt lgkmcnt(1)
	v_add_f32_e32 v58, v58, v60
	s_waitcnt lgkmcnt(0)
	v_add_f32_e32 v61, v59, v61
	ds_bpermute_b32 v60, v191, v58
	ds_bpermute_b32 v62, v191, v61
	s_waitcnt lgkmcnt(1)
	v_add_f32_e32 v58, v58, v60
	s_waitcnt lgkmcnt(0)
	v_add_f32_e32 v60, v61, v62
	ds_bpermute_b32 v59, v204, v58
	ds_bpermute_b32 v61, v204, v60
	v_add_u32_e32 v62, 0x1040, v92
	v_cndmask_b32_e64 v62, v92, v62, s[36:37]
	global_store_dwordx2 v62, v[246:247], s[20:21]
	s_and_saveexec_b64 s[24:25], s[40:41]
	s_cbranch_execz .LBB0_2819
	s_waitcnt lgkmcnt(1)
	v_add_f32_e32 v58, v58, v59
	s_waitcnt lgkmcnt(0)
	v_add_f32_e32 v59, v60, v61
	ds_write2_b32 v194, v58, v59 offset0:64 offset1:72
; #define LAS __attribute__((address_space(3)))
; #define ERN_EOFF(q, m) (eb + (unsigned)((((q) & 1) * HALF + (m) * 16) * DM + ERN_COL((q) >> 1)))
;     __device__ __forceinline__ void operator()(const f32x4 (&acc)[2][2][4][2], const Unit& u, int wr, int wc, int fr, int fq) const {
;     ...
;         ERN_LOADX(0);
; #pragma unroll
;         for (int g = 0; g < 8; ++g) { const int ai = g >> 2, m = g & 3;
;             if (g + 1 < 8) ERN_LOADX(g + 1);
;             float sq0 = 0.f, sq1 = 0.f; u32x2 hw[2][2];
; #pragma unroll
;             for (int bj = 0; bj < 2; ++bj) {
;                 *(LAS f32x4*)(st + wr_off) = acc[ai][bj][m][0]; *(LAS f32x4*)(st + wr_off + 64) = acc[ai][bj][m][1];
;                 const f32x4 a0 = *(const LAS f32x4*)(st + rd_off), a1 = *(const LAS f32x4*)(st + rd_off + 8 * 144);
;                 { const f32x4 xv = xb[g & 1][bj][0] + gv[bj] * a0; __builtin_nontemporal_store(xv, (f32x4*)((char*)xo + 4u * ERN_EOFF(g, bj, 0)));
;                   sq0 += (xv.x * xv.x + xv.y * xv.y) + (xv.z * xv.z + xv.w * xv.w);
;                   const f32x4 hv = xv * gsn[bj]; hw[bj][0].x = cvt_pk_bf16(hv.x, hv.y); hw[bj][0].y = cvt_pk_bf16(hv.z, hv.w); }
;                 { const f32x4 xv = xb[g & 1][bj][1] + gv[bj] * a1; __builtin_nontemporal_store(xv, (f32x4*)((char*)xo + 4u * ERN_EOFF(g, bj, 1)));
;                   sq1 += (xv.x * xv.x + xv.y * xv.y) + (xv.z * xv.z + xv.w * xv.w);
;                   const f32x4 hv = xv * gsn[bj]; hw[bj][1].x = cvt_pk_bf16(hv.x, hv.y); hw[bj][1].y = cvt_pk_bf16(hv.z, hv.w); }
;             }
;             if (!NOH && !PLAIN) {
; #pragma unroll
;                 for (int rh = 0; rh < 2; ++rh) { u32x2 rv; rv.x = __shfl_xor(hw[1][rh].x, 8); rv.y = __shfl_xor(hw[1][rh].y, 8);
;                     const unsigned e0 = ERN_EOFF(g, 0, rh);
;                     const unsigned ee = odd ? (e0 - DM + 32) : e0, eo2 = odd ? e0 : (e0 + DM + 32);
;                     *(u32x2*)((char*)ho + 2u * ee) = odd ? rv : hw[0][rh];
;                     *(u32x2*)((char*)ho + 2u * eo2) = odd ? hw[0][rh] : rv; }
;             }
;             if (!PLAIN) { sq0 += __shfl_xor(sq0, 1); sq0 += __shfl_xor(sq0, 2); sq0 += __shfl_xor(sq0, 4);
;             sq1 += __shfl_xor(sq1, 1); sq1 += __shfl_xor(sq1, 2); sq1 += __shfl_xor(sq1, 4); }
;             if (!PLAIN && pc == 0) { sst[g * 16 + rr] = sq0; sst[g * 16 + 8 + rr] = sq1; }
.LBB0_2819:
	s_or_b64 exec, exec, s[24:25]
	v_lshl_add_u64 v[96:97], s[22:23], 0, v[162:163]
	v_add_u32_e32 v162, 0x140000, v205
	v_add_u32_e32 v92, 0x140080, v205
	v_add_u32_e32 v94, 0x150000, v205
	v_add_u32_e32 v90, 0x150080, v205
	s_waitcnt lgkmcnt(0)
	ds_write_b128 v200, v[46:49]
	ds_write_b128 v200, v[42:45] offset:64
	ds_read_b128 v[42:45], v201
	ds_read_b128 v[46:49], v201 offset:1152
	v_mov_b32_e32 v111, v163
	v_lshl_add_u64 v[98:99], s[22:23], 0, v[110:111]
	v_mov_b32_e32 v109, v163
	s_waitcnt vmcnt(18) lgkmcnt(1)
	v_mov_b64_e32 v[86:87], v[128:129]
	v_mov_b64_e32 v[88:89], v[130:131]
	v_mov_b64_e32 v[82:83], v[132:133]
	v_mov_b64_e32 v[84:85], v[134:135]
	v_mov_b64_e32 v[78:79], v[144:145]
	v_mov_b64_e32 v[80:81], v[146:147]
	v_mov_b64_e32 v[74:75], v[148:149]
	v_mov_b64_e32 v[76:77], v[150:151]
	v_add_u32_e32 v136, 0x160000, v205
	global_load_dwordx4 v[128:131], v136, s[22:23]
	v_add_u32_e32 v137, 0x170000, v205
	global_load_dwordx4 v[132:135], v137, s[22:23]
	v_add_u32_e32 v142, 0x160080, v205
	global_load_dwordx4 v[144:147], v142, s[22:23]
	v_add_u32_e32 v143, 0x170080, v205
	global_load_dwordx4 v[148:151], v143, s[22:23]
	v_pk_fma_f32 v[42:43], v[54:55], v[42:43], v[86:87]
	s_waitcnt lgkmcnt(0)
	v_pk_fma_f32 v[46:47], v[54:55], v[46:47], v[82:83]
	v_pk_fma_f32 v[44:45], v[56:57], v[44:45], v[88:89]
	v_pk_mul_f32 v[86:87], v[180:181], v[42:43]
	v_pk_fma_f32 v[48:49], v[56:57], v[48:49], v[84:85]
	v_pk_mul_f32 v[82:83], v[180:181], v[46:47]
	global_store_dwordx4 v[96:97], v[42:45], off nt
	v_pk_mul_f32 v[88:89], v[178:179], v[44:45]
	v_cvt_pk_bf16_f32 v86, v86, v87
	v_pk_mul_f32 v[84:85], v[178:179], v[48:49]
	v_cvt_pk_bf16_f32 v87, v88, v89
	global_store_dwordx4 v[98:99], v[46:49], off nt
	v_cvt_pk_bf16_f32 v82, v82, v83
	v_cvt_pk_bf16_f32 v83, v84, v85
	ds_write_b128 v200, v[38:41]
	ds_write_b128 v200, v[34:37] offset:64
	ds_read_b128 v[34:37], v201
	ds_read_b128 v[38:41], v201 offset:1152
	v_lshl_add_u64 v[84:85], s[22:23], 0, v[108:109]
	v_mov_b32_e32 v107, v163
	v_lshl_add_u64 v[88:89], s[22:23], 0, v[106:107]
	s_waitcnt lgkmcnt(1)
	v_pk_fma_f32 v[34:35], v[50:51], v[34:35], v[78:79]
	v_pk_fma_f32 v[36:37], v[52:53], v[36:37], v[80:81]
	v_pk_mul_f32 v[80:81], v[176:177], v[34:35]
	global_store_dwordx4 v[84:85], v[34:37], off nt
	v_pk_mul_f32 v[78:79], v[174:175], v[36:37]
	v_cvt_pk_bf16_f32 v80, v80, v81
	s_waitcnt lgkmcnt(0)
	v_pk_fma_f32 v[38:39], v[50:51], v[38:39], v[74:75]
	v_cvt_pk_bf16_f32 v81, v78, v79
	ds_bpermute_b32 v74, v203, v80
	ds_bpermute_b32 v75, v203, v81
	v_pk_fma_f32 v[40:41], v[52:53], v[40:41], v[76:77]
	v_pk_mul_f32 v[76:77], v[176:177], v[38:39]
	v_pk_mul_f32 v[78:79], v[174:175], v[40:41]
	global_store_dwordx4 v[88:89], v[38:41], off nt
	v_cvt_pk_bf16_f32 v76, v76, v77
	v_cvt_pk_bf16_f32 v77, v78, v79
	v_add_u32_e32 v79, 0x48000, v202
	v_lshlrev_b32_e32 v78, 1, v79
	s_waitcnt lgkmcnt(0)
	v_add_u32_e32 v250, 0xfffff040, v78
	v_cndmask_b32_e64 v250, v78, v250, s[38:39]
	v_cndmask_b32_e64 v248, v86, v74, s[38:39]
	v_cndmask_b32_e64 v249, v87, v75, s[38:39]
	global_store_dwordx2 v250, v[248:249], s[20:21]
	v_cndmask_b32_e64 v246, v74, v86, s[38:39]
	v_cndmask_b32_e64 v247, v75, v87, s[38:39]
	s_waitcnt lgkmcnt(1)
	v_add_u32_e32 v74, 0x1040, v78
	v_cndmask_b32_e64 v74, v78, v74, s[36:37]
	global_store_dwordx2 v74, v[246:247], s[20:21]
	ds_bpermute_b32 v74, v203, v76
	s_waitcnt lgkmcnt(1)
	ds_bpermute_b32 v75, v203, v77
	v_add_u32_e32 v77, 0x4c000, v202
	v_lshlrev_b32_e32 v76, 1, v77
	s_waitcnt lgkmcnt(0)
	v_add_u32_e32 v250, 0xfffff040, v76
	v_cndmask_b32_e64 v250, v76, v250, s[38:39]
	v_cndmask_b32_e64 v248, v82, v74, s[38:39]
	v_cndmask_b32_e64 v249, v83, v75, s[38:39]
	global_store_dwordx2 v250, v[248:249], s[20:21]
	v_cndmask_b32_e64 v246, v74, v82, s[38:39]
	v_cndmask_b32_e64 v247, v75, v83, s[38:39]
	v_mul_f32_e32 v35, v35, v35
	v_fmac_f32_e32 v35, v34, v34
	v_mul_f32_e32 v34, v37, v37
	v_mul_f32_e32 v45, v45, v45
	v_fmac_f32_e32 v34, v36, v36
	v_mul_f32_e32 v43, v43, v43
	v_fmac_f32_e32 v45, v44, v44
	v_mul_f32_e32 v44, v47, v47
	v_mul_f32_e32 v47, v49, v49
	v_add_f32_e32 v34, v35, v34
	v_mul_f32_e32 v35, v39, v39
	v_mul_f32_e32 v36, v41, v41
	v_fmac_f32_e32 v47, v48, v48
	v_fmac_f32_e32 v35, v38, v38
	v_fmac_f32_e32 v36, v40, v40
	v_fmac_f32_e32 v43, v42, v42
	v_fmac_f32_e32 v44, v46, v46
	v_add_f32_e32 v35, v35, v36
	v_add_f32_e32 v36, v43, v45
	v_add_f32_e32 v37, v44, v47
	v_add_f32_e32 v34, v36, v34
	v_add_f32_e32 v35, v37, v35
	ds_bpermute_b32 v36, v190, v34
	ds_bpermute_b32 v37, v190, v35
	s_waitcnt lgkmcnt(1)
	v_add_f32_e32 v34, v34, v36
	s_waitcnt lgkmcnt(0)
	v_add_f32_e32 v37, v35, v37
	ds_bpermute_b32 v36, v191, v34
	ds_bpermute_b32 v38, v191, v37
	s_waitcnt lgkmcnt(1)
	v_add_f32_e32 v34, v34, v36
	s_waitcnt lgkmcnt(0)
	v_add_f32_e32 v36, v37, v38
	ds_bpermute_b32 v35, v204, v34
	ds_bpermute_b32 v37, v204, v36
	v_add_u32_e32 v38, 0x1040, v76
	v_cndmask_b32_e64 v38, v76, v38, s[36:37]
	global_store_dwordx2 v38, v[246:247], s[20:21]
	s_and_saveexec_b64 s[24:25], s[40:41]
	s_cbranch_execz .LBB0_2829
	s_waitcnt lgkmcnt(1)
	v_add_f32_e32 v34, v34, v35
	s_waitcnt lgkmcnt(0)
	v_add_f32_e32 v35, v36, v37
	ds_write2_b32 v194, v34, v35 offset0:80 offset1:88
; #define LAS __attribute__((address_space(3)))
; #define ERN_EOFF(q, m) (eb + (unsigned)((((q) & 1) * HALF + (m) * 16) * DM + ERN_COL((q) >> 1)))
;     __device__ __forceinline__ void operator()(const f32x4 (&acc)[2][2][4][2], const Unit& u, int wr, int wc, int fr, int fq) const {
;     ...
;         ERN_LOADX(0);
; #pragma unroll
;         for (int g = 0; g < 8; ++g) { const int ai = g >> 2, m = g & 3;
;             if (g + 1 < 8) ERN_LOADX(g + 1);
;             float sq0 = 0.f, sq1 = 0.f; u32x2 hw[2][2];
; #pragma unroll
;             for (int bj = 0; bj < 2; ++bj) {
;                 *(LAS f32x4*)(st + wr_off) = acc[ai][bj][m][0]; *(LAS f32x4*)(st + wr_off + 64) = acc[ai][bj][m][1];
;                 const f32x4 a0 = *(const LAS f32x4*)(st + rd_off), a1 = *(const LAS f32x4*)(st + rd_off + 8 * 144);
;                 { const f32x4 xv = xb[g & 1][bj][0] + gv[bj] * a0; __builtin_nontemporal_store(xv, (f32x4*)((char*)xo + 4u * ERN_EOFF(g, bj, 0)));
;                   sq0 += (xv.x * xv.x + xv.y * xv.y) + (xv.z * xv.z + xv.w * xv.w);
;                   const f32x4 hv = xv * gsn[bj]; hw[bj][0].x = cvt_pk_bf16(hv.x, hv.y); hw[bj][0].y = cvt_pk_bf16(hv.z, hv.w); }
;                 { const f32x4 xv = xb[g & 1][bj][1] + gv[bj] * a1; __builtin_nontemporal_store(xv, (f32x4*)((char*)xo + 4u * ERN_EOFF(g, bj, 1)));
;                   sq1 += (xv.x * xv.x + xv.y * xv.y) + (xv.z * xv.z + xv.w * xv.w);
;                   const f32x4 hv = xv * gsn[bj]; hw[bj][1].x = cvt_pk_bf16(hv.x, hv.y); hw[bj][1].y = cvt_pk_bf16(hv.z, hv.w); }
;             }
;             if (!NOH && !PLAIN) {
; #pragma unroll
;                 for (int rh = 0; rh < 2; ++rh) { u32x2 rv; rv.x = __shfl_xor(hw[1][rh].x, 8); rv.y = __shfl_xor(hw[1][rh].y, 8);
;                     const unsigned e0 = ERN_EOFF(g, 0, rh);
;                     const unsigned ee = odd ? (e0 - DM + 32) : e0, eo2 = odd ? e0 : (e0 + DM + 32);
;                     *(u32x2*)((char*)ho + 2u * ee) = odd ? rv : hw[0][rh];
;                     *(u32x2*)((char*)ho + 2u * eo2) = odd ? hw[0][rh] : rv; }
;             }
;             if (!PLAIN) { sq0 += __shfl_xor(sq0, 1); sq0 += __shfl_xor(sq0, 2); sq0 += __shfl_xor(sq0, 4);
;             sq1 += __shfl_xor(sq1, 1); sq1 += __shfl_xor(sq1, 2); sq1 += __shfl_xor(sq1, 4); }
;             if (!PLAIN && pc == 0) { sst[g * 16 + rr] = sq0; sst[g * 16 + 8 + rr] = sq1; }
.LBB0_2829:
	s_or_b64 exec, exec, s[24:25]
	v_lshl_add_u64 v[80:81], s[22:23], 0, v[162:163]
	v_add_u32_e32 v162, 0x160000, v205
	v_add_u32_e32 v76, 0x160080, v205
	v_add_u32_e32 v78, 0x170000, v205
	v_add_u32_e32 v74, 0x170080, v205
	s_waitcnt lgkmcnt(0)
	ds_write_b128 v200, v[30:33]
	ds_write_b128 v200, v[26:29] offset:64
	ds_read_b128 v[26:29], v201
	ds_read_b128 v[30:33], v201 offset:1152
	v_mov_b32_e32 v95, v163
	v_lshl_add_u64 v[82:83], s[22:23], 0, v[94:95]
	v_mov_b32_e32 v93, v163
	s_waitcnt vmcnt(18) lgkmcnt(1)
	v_mov_b64_e32 v[70:71], v[184:185]
	v_mov_b64_e32 v[72:73], v[186:187]
	v_mov_b64_e32 v[66:67], v[208:209]
	v_mov_b64_e32 v[68:69], v[210:211]
	v_mov_b64_e32 v[62:63], v[212:213]
	v_mov_b64_e32 v[64:65], v[214:215]
	v_mov_b64_e32 v[58:59], v[216:217]
	v_mov_b64_e32 v[60:61], v[218:219]
	v_pk_fma_f32 v[26:27], v[54:55], v[26:27], v[70:71]
	s_waitcnt lgkmcnt(0)
	v_pk_fma_f32 v[30:31], v[54:55], v[30:31], v[66:67]
	v_pk_fma_f32 v[28:29], v[56:57], v[28:29], v[72:73]
	v_pk_mul_f32 v[70:71], v[180:181], v[26:27]
	v_pk_fma_f32 v[32:33], v[56:57], v[32:33], v[68:69]
	v_pk_mul_f32 v[66:67], v[180:181], v[30:31]
	global_store_dwordx4 v[80:81], v[26:29], off nt
	v_pk_mul_f32 v[72:73], v[178:179], v[28:29]
	v_cvt_pk_bf16_f32 v70, v70, v71
	v_pk_mul_f32 v[68:69], v[178:179], v[32:33]
	v_cvt_pk_bf16_f32 v71, v72, v73
	global_store_dwordx4 v[82:83], v[30:33], off nt
	v_cvt_pk_bf16_f32 v66, v66, v67
	v_cvt_pk_bf16_f32 v67, v68, v69
	ds_write_b128 v200, v[22:25]
	ds_write_b128 v200, v[18:21] offset:64
	ds_read_b128 v[18:21], v201
	ds_read_b128 v[22:25], v201 offset:1152
	v_lshl_add_u64 v[68:69], s[22:23], 0, v[92:93]
	v_mov_b32_e32 v91, v163
	v_lshl_add_u64 v[72:73], s[22:23], 0, v[90:91]
	s_waitcnt lgkmcnt(1)
	v_pk_fma_f32 v[18:19], v[50:51], v[18:19], v[62:63]
	v_pk_fma_f32 v[20:21], v[52:53], v[20:21], v[64:65]
	v_pk_mul_f32 v[64:65], v[176:177], v[18:19]
	global_store_dwordx4 v[68:69], v[18:21], off nt
	v_pk_mul_f32 v[62:63], v[174:175], v[20:21]
	v_cvt_pk_bf16_f32 v64, v64, v65
	s_waitcnt lgkmcnt(0)
	v_pk_fma_f32 v[22:23], v[50:51], v[22:23], v[58:59]
	v_cvt_pk_bf16_f32 v65, v62, v63
	ds_bpermute_b32 v58, v203, v64
	ds_bpermute_b32 v59, v203, v65
	v_pk_fma_f32 v[24:25], v[52:53], v[24:25], v[60:61]
	v_pk_mul_f32 v[60:61], v[176:177], v[22:23]
	v_pk_mul_f32 v[62:63], v[174:175], v[24:25]
	global_store_dwordx4 v[72:73], v[22:25], off nt
	v_cvt_pk_bf16_f32 v60, v60, v61
	v_cvt_pk_bf16_f32 v61, v62, v63
	v_add_u32_e32 v63, 0x50000, v202
	v_lshlrev_b32_e32 v62, 1, v63
	s_waitcnt lgkmcnt(0)
	v_add_u32_e32 v250, 0xfffff040, v62
	v_cndmask_b32_e64 v250, v62, v250, s[38:39]
	v_cndmask_b32_e64 v248, v70, v58, s[38:39]
	v_cndmask_b32_e64 v249, v71, v59, s[38:39]
	global_store_dwordx2 v250, v[248:249], s[20:21]
	v_cndmask_b32_e64 v246, v58, v70, s[38:39]
	v_cndmask_b32_e64 v247, v59, v71, s[38:39]
	s_waitcnt lgkmcnt(1)
	v_add_u32_e32 v58, 0x1040, v62
	v_cndmask_b32_e64 v58, v62, v58, s[36:37]
	global_store_dwordx2 v58, v[246:247], s[20:21]
	ds_bpermute_b32 v58, v203, v60
	s_waitcnt lgkmcnt(1)
	ds_bpermute_b32 v59, v203, v61
	v_add_u32_e32 v61, 0x54000, v202
	v_lshlrev_b32_e32 v60, 1, v61
	s_waitcnt lgkmcnt(0)
	v_add_u32_e32 v250, 0xfffff040, v60
	v_cndmask_b32_e64 v250, v60, v250, s[38:39]
	v_cndmask_b32_e64 v248, v66, v58, s[38:39]
	v_cndmask_b32_e64 v249, v67, v59, s[38:39]
	global_store_dwordx2 v250, v[248:249], s[20:21]
	v_cndmask_b32_e64 v246, v58, v66, s[38:39]
	v_cndmask_b32_e64 v247, v59, v67, s[38:39]
	v_mul_f32_e32 v19, v19, v19
	v_fmac_f32_e32 v19, v18, v18
	v_mul_f32_e32 v18, v21, v21
	v_mul_f32_e32 v29, v29, v29
	v_fmac_f32_e32 v18, v20, v20
	v_mul_f32_e32 v27, v27, v27
	v_fmac_f32_e32 v29, v28, v28
	v_mul_f32_e32 v28, v31, v31
	v_mul_f32_e32 v31, v33, v33
	v_add_f32_e32 v18, v19, v18
	v_mul_f32_e32 v19, v23, v23
	v_mul_f32_e32 v20, v25, v25
	v_fmac_f32_e32 v31, v32, v32
	v_fmac_f32_e32 v19, v22, v22
	v_fmac_f32_e32 v20, v24, v24
	v_fmac_f32_e32 v27, v26, v26
	v_fmac_f32_e32 v28, v30, v30
	v_add_f32_e32 v19, v19, v20
	v_add_f32_e32 v20, v27, v29
	v_add_f32_e32 v21, v28, v31
	v_add_f32_e32 v18, v20, v18
	v_add_f32_e32 v19, v21, v19
	ds_bpermute_b32 v20, v190, v18
	ds_bpermute_b32 v21, v190, v19
	s_waitcnt lgkmcnt(1)
	v_add_f32_e32 v18, v18, v20
	s_waitcnt lgkmcnt(0)
	v_add_f32_e32 v21, v19, v21
	ds_bpermute_b32 v20, v191, v18
	ds_bpermute_b32 v22, v191, v21
	s_waitcnt lgkmcnt(1)
	v_add_f32_e32 v18, v18, v20
	s_waitcnt lgkmcnt(0)
	v_add_f32_e32 v20, v21, v22
	ds_bpermute_b32 v19, v204, v18
	ds_bpermute_b32 v21, v204, v20
	v_add_u32_e32 v22, 0x1040, v60
	v_cndmask_b32_e64 v22, v60, v22, s[36:37]
	global_store_dwordx2 v22, v[246:247], s[20:21]
	s_and_saveexec_b64 s[24:25], s[40:41]
	s_cbranch_execz .LBB0_2839
	s_waitcnt lgkmcnt(1)
	v_add_f32_e32 v18, v18, v19
	s_waitcnt lgkmcnt(0)
	v_add_f32_e32 v19, v20, v21
	ds_write2_b32 v194, v18, v19 offset0:96 offset1:104
; #define LAS __attribute__((address_space(3)))
; #define ERN_EOFF(q, m) (eb + (unsigned)((((q) & 1) * HALF + (m) * 16) * DM + ERN_COL((q) >> 1)))
;     __device__ __forceinline__ void operator()(const f32x4 (&acc)[2][2][4][2], const Unit& u, int wr, int wc, int fr, int fq) const {
;     ...
;         for (int g = 0; g < 8; ++g) { const int ai = g >> 2, m = g & 3;
;             if (g + 1 < 8) ERN_LOADX(g + 1);
;             float sq0 = 0.f, sq1 = 0.f; u32x2 hw[2][2];
; #pragma unroll
;             for (int bj = 0; bj < 2; ++bj) {
;                 *(LAS f32x4*)(st + wr_off) = acc[ai][bj][m][0]; *(LAS f32x4*)(st + wr_off + 64) = acc[ai][bj][m][1];
;                 const f32x4 a0 = *(const LAS f32x4*)(st + rd_off), a1 = *(const LAS f32x4*)(st + rd_off + 8 * 144);
;                 { const f32x4 xv = xb[g & 1][bj][0] + gv[bj] * a0; __builtin_nontemporal_store(xv, (f32x4*)((char*)xo + 4u * ERN_EOFF(g, bj, 0)));
;                   sq0 += (xv.x * xv.x + xv.y * xv.y) + (xv.z * xv.z + xv.w * xv.w);
;                   const f32x4 hv = xv * gsn[bj]; hw[bj][0].x = cvt_pk_bf16(hv.x, hv.y); hw[bj][0].y = cvt_pk_bf16(hv.z, hv.w); }
;                 { const f32x4 xv = xb[g & 1][bj][1] + gv[bj] * a1; __builtin_nontemporal_store(xv, (f32x4*)((char*)xo + 4u * ERN_EOFF(g, bj, 1)));
;                   sq1 += (xv.x * xv.x + xv.y * xv.y) + (xv.z * xv.z + xv.w * xv.w);
;                   const f32x4 hv = xv * gsn[bj]; hw[bj][1].x = cvt_pk_bf16(hv.x, hv.y); hw[bj][1].y = cvt_pk_bf16(hv.z, hv.w); }
;             }
;             if (!NOH && !PLAIN) {
; #pragma unroll
;                 for (int rh = 0; rh < 2; ++rh) { u32x2 rv; rv.x = __shfl_xor(hw[1][rh].x, 8); rv.y = __shfl_xor(hw[1][rh].y, 8);
;                     const unsigned e0 = ERN_EOFF(g, 0, rh);
;                     const unsigned ee = odd ? (e0 - DM + 32) : e0, eo2 = odd ? e0 : (e0 + DM + 32);
;                     *(u32x2*)((char*)ho + 2u * ee) = odd ? rv : hw[0][rh];
;                     *(u32x2*)((char*)ho + 2u * eo2) = odd ? hw[0][rh] : rv; }
;             }
;             if (!PLAIN) { sq0 += __shfl_xor(sq0, 1); sq0 += __shfl_xor(sq0, 2); sq0 += __shfl_xor(sq0, 4);
;             sq1 += __shfl_xor(sq1, 1); sq1 += __shfl_xor(sq1, 2); sq1 += __shfl_xor(sq1, 4); }
;             if (!PLAIN && pc == 0) { sst[g * 16 + rr] = sq0; sst[g * 16 + 8 + rr] = sq1; }
.LBB0_2839:
	s_or_b64 exec, exec, s[24:25]
	ds_write_b128 v200, v[14:17]
	ds_write_b128 v200, v[10:13] offset:64
	ds_read_b128 v[10:13], v201
	ds_read_b128 v[14:17], v201 offset:1152
	s_waitcnt lgkmcnt(5)
	v_lshl_add_u64 v[18:19], s[22:23], 0, v[162:163]
	v_mov_b32_e32 v79, v163
	v_lshl_add_u64 v[22:23], s[22:23], 0, v[78:79]
	s_waitcnt vmcnt(14) lgkmcnt(1)
	v_mov_b64_e32 v[46:47], v[128:129]
	v_mov_b64_e32 v[48:49], v[130:131]
	v_mov_b64_e32 v[42:43], v[132:133]
	v_mov_b64_e32 v[44:45], v[134:135]
	v_mov_b64_e32 v[38:39], v[144:145]
	v_mov_b64_e32 v[40:41], v[146:147]
	v_mov_b64_e32 v[34:35], v[148:149]
	v_mov_b64_e32 v[36:37], v[150:151]
	v_pk_fma_f32 v[12:13], v[56:57], v[12:13], v[48:49]
	v_pk_fma_f32 v[10:11], v[54:55], v[10:11], v[46:47]
	global_store_dwordx4 v[18:19], v[10:13], off nt
	v_pk_mul_f32 v[18:19], v[178:179], v[12:13]
	v_pk_mul_f32 v[20:21], v[180:181], v[10:11]
	s_waitcnt lgkmcnt(0)
	v_pk_fma_f32 v[14:15], v[54:55], v[14:15], v[42:43]
	v_cvt_pk_bf16_f32 v20, v20, v21
	v_cvt_pk_bf16_f32 v21, v18, v19
	v_pk_fma_f32 v[16:17], v[56:57], v[16:17], v[44:45]
	v_pk_mul_f32 v[18:19], v[180:181], v[14:15]
	global_store_dwordx4 v[22:23], v[14:17], off nt
	v_pk_mul_f32 v[22:23], v[178:179], v[16:17]
	v_cvt_pk_bf16_f32 v18, v18, v19
	v_mov_b32_e32 v77, v163
	v_cvt_pk_bf16_f32 v19, v22, v23
	ds_write_b128 v200, v[6:9]
	ds_write_b128 v200, v[2:5] offset:64
	ds_read_b128 v[2:5], v201
	ds_read_b128 v[6:9], v201 offset:1152
	v_lshl_add_u64 v[22:23], s[22:23], 0, v[76:77]
	v_mov_b32_e32 v75, v163
	v_lshl_add_u64 v[24:25], s[22:23], 0, v[74:75]
	s_waitcnt lgkmcnt(1)
	v_pk_fma_f32 v[4:5], v[52:53], v[4:5], v[40:41]
	v_pk_fma_f32 v[2:3], v[50:51], v[2:3], v[38:39]
	global_store_dwordx4 v[22:23], v[2:5], off nt
	v_pk_mul_f32 v[22:23], v[174:175], v[4:5]
	v_pk_mul_f32 v[26:27], v[176:177], v[2:3]
	s_waitcnt lgkmcnt(0)
	v_pk_fma_f32 v[8:9], v[52:53], v[8:9], v[36:37]
	v_cvt_pk_bf16_f32 v28, v26, v27
	v_cvt_pk_bf16_f32 v23, v22, v23
	ds_bpermute_b32 v22, v203, v28
	ds_bpermute_b32 v23, v203, v23
	v_pk_fma_f32 v[6:7], v[50:51], v[6:7], v[34:35]
	global_store_dwordx4 v[24:25], v[6:9], off nt
	v_pk_mul_f32 v[26:27], v[174:175], v[8:9]
	v_pk_mul_f32 v[24:25], v[176:177], v[6:7]
	s_nop 0
	v_cvt_pk_bf16_f32 v24, v24, v25
	v_cvt_pk_bf16_f32 v25, v26, v27
	v_add_u32_e32 v27, 0x58000, v202
	v_lshlrev_b32_e32 v26, 1, v27
	s_waitcnt lgkmcnt(0)
	v_add_u32_e32 v250, 0xfffff040, v26
	v_cndmask_b32_e64 v250, v26, v250, s[38:39]
	v_cndmask_b32_e64 v248, v20, v22, s[38:39]
	v_cndmask_b32_e64 v249, v21, v23, s[38:39]
	global_store_dwordx2 v250, v[248:249], s[20:21]
	v_cndmask_b32_e64 v246, v22, v20, s[38:39]
	v_cndmask_b32_e64 v247, v23, v21, s[38:39]
	s_waitcnt lgkmcnt(1)
	v_add_u32_e32 v22, 0x1040, v26
	v_cndmask_b32_e64 v22, v26, v22, s[36:37]
	global_store_dwordx2 v22, v[246:247], s[20:21]
	ds_bpermute_b32 v20, v203, v24
	ds_bpermute_b32 v21, v203, v25
	s_waitcnt lgkmcnt(2)
	v_add_u32_e32 v23, 0x5c000, v202
	v_lshlrev_b32_e32 v22, 1, v23
	s_waitcnt lgkmcnt(0)
	v_add_u32_e32 v250, 0xfffff040, v22
	v_cndmask_b32_e64 v250, v22, v250, s[38:39]
	v_cndmask_b32_e64 v248, v18, v20, s[38:39]
	v_cndmask_b32_e64 v249, v19, v21, s[38:39]
	global_store_dwordx2 v250, v[248:249], s[20:21]
	v_cndmask_b32_e64 v246, v20, v18, s[38:39]
	v_cndmask_b32_e64 v247, v21, v19, s[38:39]
	v_mul_f32_e32 v3, v3, v3
	v_fmac_f32_e32 v3, v2, v2
	v_mul_f32_e32 v2, v5, v5
	v_mul_f32_e32 v13, v13, v13
	v_fmac_f32_e32 v2, v4, v4
	v_mul_f32_e32 v11, v11, v11
	v_fmac_f32_e32 v13, v12, v12
	v_mul_f32_e32 v12, v15, v15
	v_mul_f32_e32 v15, v17, v17
	v_add_f32_e32 v2, v3, v2
	v_mul_f32_e32 v3, v7, v7
	v_mul_f32_e32 v4, v9, v9
	v_fmac_f32_e32 v15, v16, v16
	v_fmac_f32_e32 v3, v6, v6
	v_fmac_f32_e32 v4, v8, v8
	v_fmac_f32_e32 v11, v10, v10
	v_fmac_f32_e32 v12, v14, v14
	v_add_f32_e32 v3, v3, v4
	v_add_f32_e32 v4, v11, v13
	v_add_f32_e32 v5, v12, v15
	v_add_f32_e32 v2, v4, v2
	v_add_f32_e32 v3, v5, v3
	ds_bpermute_b32 v4, v190, v2
	ds_bpermute_b32 v5, v190, v3
	s_waitcnt lgkmcnt(1)
	v_add_f32_e32 v2, v2, v4
	s_waitcnt lgkmcnt(0)
	v_add_f32_e32 v5, v3, v5
	ds_bpermute_b32 v4, v191, v2
	ds_bpermute_b32 v6, v191, v5
	s_waitcnt lgkmcnt(1)
	v_add_f32_e32 v2, v2, v4
	s_waitcnt lgkmcnt(0)
	v_add_f32_e32 v4, v5, v6
	ds_bpermute_b32 v3, v204, v2
	ds_bpermute_b32 v5, v204, v4
	v_add_u32_e32 v6, 0x1040, v22
	v_cndmask_b32_e64 v6, v22, v6, s[36:37]
	global_store_dwordx2 v6, v[246:247], s[20:21]
	s_and_saveexec_b64 s[20:21], s[40:41]
	s_cbranch_execz .LBB0_2849
	s_waitcnt lgkmcnt(1)
	v_add_f32_e32 v2, v2, v3
	s_waitcnt lgkmcnt(0)
	v_add_f32_e32 v3, v4, v5
	ds_write2_b32 v194, v2, v3 offset0:112 offset1:120
